# one static priority raise for waves 4-7 (s_setprio 1 at kernel start, dropped to 0 inside the attention task loop) in place of the 160 per-segment s_setprio toggles of the GEMM loops
# speedup vs baseline: 1.0008x; 1.0008x over previous
; #define LAS __attribute__((address_space(3)))
; __device__ __forceinline__ unsigned xb_add(unsigned* p, unsigned v) { return __hip_atomic_fetch_add(p, v, __ATOMIC_RELAXED, __HIP_MEMORY_SCOPE_AGENT); }
; __device__ __forceinline__ unsigned xb_xcc_id() { return (unsigned)__builtin_amdgcn_s_getreg((3 << 11) | 20) & 0xFu; }
; __device__ __forceinline__ XcdBarrier xcd_barrier_post(unsigned* bar, volatile LAS unsigned* st) {
;     XcdBarrier b; b.bar = bar; b.x = xb_xcc_id(); b.st = st;
;     if (threadIdx.x == 0) (void)xb_add(&bar[XB_XCNT(b.x)], 1u);
;     return b;
; }
; __global__ __launch_bounds__(512, 2) void mega(Args a_) {
;     extern __shared__ __attribute__((aligned(16))) unsigned char shm[];
;     LAS unsigned char* lds = (LAS unsigned char*)shm;
;     cg::grid_group grid = cg::this_grid();
;     const int ph_lo = a_.ph_lo, ph_hi = a_.ph_hi;
;     int ph = 0;
;     volatile LAS unsigned* xst = (volatile LAS unsigned*)(lds + 147712);
;     if (threadIdx.x < 4) xst[threadIdx.x] = 0u;
;     __syncthreads();
;     const XcdBarrier xb = xcd_barrier_post((unsigned*)(a_.ws + OFF_BAR), xst);
_Z4mega4Args:
	s_load_dwordx4 s[48:51], s[0:1], 0xe0
	s_load_dwordx2 s[56:57], s[0:1], 0xf0
	s_load_dword s3, s[0:1], 0xf8
	s_mov_b64 s[58:59], s[0:1]
	s_add_u32 s0, s58, 0xf0
	s_addc_u32 s1, s59, 0
	v_and_b32_e32 v216, 0x3ff, v0
	v_readfirstlane_b32 s100, v216
	s_nop 3
	s_cmpk_lt_u32 s100, 0x100
	s_cbranch_scc1 .Lprio_k
	s_setprio 1
.Lprio_k:
	s_mov_b32 s84, s2
	v_writelane_b32 v237, s0, 0
	v_cmp_gt_u32_e32 vcc, 4, v216
	s_nop 0
	v_writelane_b32 v237, s1, 1
	s_and_saveexec_b64 s[0:1], vcc
	v_lshl_add_u32 v1, v216, 2, 0
	v_add_u32_e32 v1, 0x24100, v1
	v_mov_b32_e32 v2, 0
	ds_write_b32 v1, v2
	s_or_b64 exec, exec, s[0:1]
	s_waitcnt lgkmcnt(0)
	s_barrier
	s_add_u32 s10, s48, 0x1fcf8000
	s_getreg_b32 s0, hwreg(HW_REG_XCC_ID, 0, 4)
	s_addc_u32 s11, s49, 0
	s_and_b32 s2, s0, 15
	v_cmp_eq_u32_e64 s[92:93], 0, v216
	s_and_saveexec_b64 s[0:1], s[92:93]
	s_cbranch_execz .LBB0_5
	s_mov_b64 s[4:5], exec
	v_mbcnt_lo_u32_b32 v1, s4, 0
	v_mbcnt_hi_u32_b32 v1, s5, v1
	v_cmp_eq_u32_e32 vcc, 0, v1
	s_and_b64 s[6:7], exec, vcc
	s_mov_b64 exec, s[6:7]
	s_cbranch_execz .LBB0_5
	s_lshl_b32 s6, s2, 8
	s_bcnt1_i32_b64 s4, s[4:5]
	v_mov_b32_e32 v1, s6
	v_mov_b32_e32 v2, s4
	global_atomic_add v1, v2, s[10:11] offset:1024

; #define PG8_STAGE(bufoff, gbase, voff) do { _Pragma("unroll") for (int _i = 0; _i < 2; ++_i) \
;         __builtin_amdgcn_global_load_lds((const unsigned*)((const char*)(gbase) + (voff)[_i]), (LAS unsigned*)(lds + (bufoff) + ldsw + _i * 8192), 16, 0, 0); } while (0)
; #define PG8_LDA(dst, b, h) do { _Pragma("unroll") for (int m = 0; m < 4; ++m) _Pragma("unroll") for (int k = 0; k < 2; ++k) dst[m][k] = *(const LAS bf16x8*)(lds + PG8_SA(b, h) + aoff + m * 2048 + k * 1024); } while (0)
; #define PG8_LDB(dst, b, h) do { _Pragma("unroll") for (int n = 0; n < 2; ++n) _Pragma("unroll") for (int k = 0; k < 2; ++k) dst[n][k] = *(const LAS bf16x8*)(lds + PG8_SB(b, h) + boff + n * 2048 + k * 1024); } while (0)
; #define PG8_MMA(ai, bj, At, Bt) do { __builtin_amdgcn_s_setprio(1); _Pragma("unroll") for (int m = 0; m < 4; ++m) _Pragma("unroll") for (int n = 0; n < 2; ++n) _Pragma("unroll") for (int k = 0; k < 2; ++k) \
;         acc[ai][bj][m][n] = __builtin_amdgcn_mfma_f32_16x16x32_bf16(Bt[n][k], At[m][k], acc[ai][bj][m][n], 0, 0, 0); __builtin_amdgcn_s_setprio(0); } while (0)
; #define PG8_WAIT_V(n) asm volatile("s_waitcnt vmcnt(" #n ")" ::: "memory")
; #define PG8_WAIT_L(n) asm volatile("s_waitcnt lgkmcnt(" #n ")" ::: "memory")
; #define PG8_BAR __builtin_amdgcn_s_barrier()
; #define PG8_SCHED __builtin_amdgcn_sched_barrier(0)
; template <bool HM = false, bool PERM = false, bool CP = false, class Prob, class Epi>
; __device__ __forceinline__ void gemm_phase(LAS unsigned char* lds, const Prob& S, const Epi& E) {
;     ...
;             const bool last = (t == nt - 2);
;             const char* a1 = cA + (size_t)(t + 1) * kstepA;
;             const char* a2 = last ? nA : cA + (size_t)(t + 2) * kstepA; const char* b2 = last ? nB : cB + (size_t)(t + 2) * kstepB;
;             const char* a3 = a2 + kstepA; const char* b3 = b2 + kstepB; const long h2 = last ? nhB : chB;
;     ...
;             PG8_LDB(B0, 0, 0); PG8_LDB(B1, 0, 1); PG8_SCHED; PG8_LDA(At, 0, 0); PG8_STAGE(PG8_SA(1, 1), a1 + hstepA, voffA);
;             PG8_WAIT_V(8); PG8_WAIT_L(0); PG8_BAR; if (!CP || fullu) PG8_MMA(0, 0, At, B0); PG8_MMA(0, 1, At, B1); PG8_BAR; PG8_SCHED;
;             if (!HM) PG8_LDA(At, 0, 1); PG8_STAGE(PG8_SB(0, 0), b2, voffB); PG8_STAGE(PG8_SB(0, 1), b2 + h2, voffB); PG8_STAGE(PG8_SA(0, 0), a2, voffA);
.LBB0_325:
	s_add_u32 s8, s0, 0xfffc0080
	s_addc_u32 s9, s1, -1
	s_add_i32 s76, 0, 0x10000
	s_cmp_eq_u32 s75, 12
	s_cselect_b32 s25, s70, s9
	s_cselect_b32 s24, s71, s8
	v_add_u32_e32 v0, s76, v148
	s_cselect_b32 s9, s47, s74
	s_cselect_b32 s8, s72, s73
	s_add_i32 s78, 0, 0x14000
	ds_read_b128 v[142:145], v0
	ds_read_b128 v[150:153], v0 offset:1024
	ds_read_b128 v[154:157], v0 offset:2048
	ds_read_b128 v[158:161], v0 offset:3072
	v_add_u32_e32 v0, s78, v148
	ds_read_b128 v[162:165], v0
	ds_read_b128 v[166:169], v0 offset:1024
	ds_read_b128 v[170:173], v0 offset:2048
	ds_read_b128 v[174:177], v0 offset:3072
	v_lshl_add_u64 v[210:211], s[0:1], 0, v[138:139]
	s_add_i32 m0, s19, 0xc000
	ds_read_b128 v[178:181], v149
	ds_read_b128 v[182:185], v149 offset:1024
	ds_read_b128 v[186:189], v149 offset:2048
	ds_read_b128 v[190:193], v149 offset:3072
	ds_read_b128 v[194:197], v149 offset:4096
	ds_read_b128 v[198:201], v149 offset:5120
	ds_read_b128 v[202:205], v149 offset:6144
	ds_read_b128 v[206:209], v149 offset:7168
	global_load_lds_dwordx4 v[210:211], off
	v_lshl_add_u64 v[210:211], s[0:1], 0, v[140:141]
	s_add_i32 m0, s19, 0xe000
	s_nop 0
	global_load_lds_dwordx4 v[210:211], off
	s_waitcnt vmcnt(8)
	s_waitcnt lgkmcnt(0)
	s_barrier
	s_waitcnt lgkmcnt(0)
	v_mfma_f32_16x16x32_bf16 v[126:129], v[142:145], v[178:181], v[126:129]
	v_mfma_f32_16x16x32_bf16 v[122:125], v[154:157], v[178:181], v[122:125]
	v_mfma_f32_16x16x32_bf16 v[118:121], v[142:145], v[186:189], v[118:121]
	v_mfma_f32_16x16x32_bf16 v[110:113], v[154:157], v[186:189], v[110:113]
	v_mfma_f32_16x16x32_bf16 v[102:105], v[142:145], v[194:197], v[102:105]
	v_mfma_f32_16x16x32_bf16 v[98:101], v[154:157], v[194:197], v[98:101]
	v_mfma_f32_16x16x32_bf16 v[86:89], v[142:145], v[202:205], v[86:89]
	v_mfma_f32_16x16x32_bf16 v[82:85], v[154:157], v[202:205], v[82:85]
	v_mfma_f32_16x16x32_bf16 v[126:129], v[150:153], v[182:185], v[126:129]
	v_mfma_f32_16x16x32_bf16 v[122:125], v[158:161], v[182:185], v[122:125]
	v_mfma_f32_16x16x32_bf16 v[118:121], v[150:153], v[190:193], v[118:121]
	v_mfma_f32_16x16x32_bf16 v[110:113], v[158:161], v[190:193], v[110:113]
	v_mfma_f32_16x16x32_bf16 v[102:105], v[150:153], v[198:201], v[102:105]
	v_mfma_f32_16x16x32_bf16 v[98:101], v[158:161], v[198:201], v[98:101]
	v_mfma_f32_16x16x32_bf16 v[86:89], v[150:153], v[206:209], v[86:89]
	v_mfma_f32_16x16x32_bf16 v[82:85], v[158:161], v[206:209], v[82:85]
	v_mfma_f32_16x16x32_bf16 v[114:117], v[162:165], v[178:181], v[114:117]
	v_mfma_f32_16x16x32_bf16 v[106:109], v[170:173], v[178:181], v[106:109]
	v_mfma_f32_16x16x32_bf16 v[94:97], v[162:165], v[186:189], v[94:97]
	v_mfma_f32_16x16x32_bf16 v[90:93], v[170:173], v[186:189], v[90:93]
	v_mfma_f32_16x16x32_bf16 v[78:81], v[162:165], v[194:197], v[78:81]
	v_mfma_f32_16x16x32_bf16 v[74:77], v[170:173], v[194:197], v[74:77]
	v_mfma_f32_16x16x32_bf16 v[70:73], v[162:165], v[202:205], v[70:73]
	v_mfma_f32_16x16x32_bf16 v[66:69], v[170:173], v[202:205], v[66:69]
	v_mfma_f32_16x16x32_bf16 v[114:117], v[166:169], v[182:185], v[114:117]
	v_mfma_f32_16x16x32_bf16 v[106:109], v[174:177], v[182:185], v[106:109]
	v_mfma_f32_16x16x32_bf16 v[94:97], v[166:169], v[190:193], v[94:97]
	v_mfma_f32_16x16x32_bf16 v[90:93], v[174:177], v[190:193], v[90:93]
	v_mfma_f32_16x16x32_bf16 v[78:81], v[166:169], v[198:201], v[78:81]
	v_mfma_f32_16x16x32_bf16 v[74:77], v[174:177], v[198:201], v[74:77]
	v_mfma_f32_16x16x32_bf16 v[70:73], v[166:169], v[206:209], v[70:73]
	v_mfma_f32_16x16x32_bf16 v[66:69], v[174:177], v[206:209], v[66:69]
	s_barrier
	s_add_i32 s76, s76, s18
	v_lshl_add_u64 v[210:211], s[8:9], 0, v[132:133]
	s_mov_b32 m0, s76
	ds_read_b128 v[178:181], v149 offset:16384
	ds_read_b128 v[182:185], v149 offset:17408
	ds_read_b128 v[186:189], v149 offset:18432
	ds_read_b128 v[190:193], v149 offset:19456
	ds_read_b128 v[194:197], v149 offset:20480
	ds_read_b128 v[198:201], v149 offset:21504
	ds_read_b128 v[202:205], v149 offset:22528
	ds_read_b128 v[206:209], v149 offset:23552
	global_load_lds_dwordx4 v[210:211], off
	s_add_i32 m0, s76, 0x2000
	s_add_u32 s76, s8, 0x40000
	v_lshl_add_u64 v[212:213], s[8:9], 0, v[136:137]
	s_addc_u32 s77, s9, 0
	s_add_i32 s78, s78, s18
	global_load_lds_dwordx4 v[212:213], off
	v_lshl_add_u64 v[214:215], s[76:77], 0, v[132:133]
	s_mov_b32 m0, s78
	v_lshl_add_u64 v[230:231], s[24:25], 0, v[134:135]
	global_load_lds_dwordx4 v[214:215], off
	v_lshl_add_u64 v[214:215], s[76:77], 0, v[136:137]
	s_add_i32 m0, s78, 0x2000
	s_nop 0
	global_load_lds_dwordx4 v[214:215], off
	v_lshl_add_u64 v[214:215], s[24:25], 0, v[130:131]
	s_mov_b32 m0, s19
	s_nop 0
	global_load_lds_dwordx4 v[214:215], off
	s_mov_b32 m0, s31
	s_nop 0
	global_load_lds_dwordx4 v[230:231], off
	s_waitcnt vmcnt(8)
	s_waitcnt lgkmcnt(0)
	s_barrier
; #define PG8_STAGE(bufoff, gbase, voff) do { _Pragma("unroll") for (int _i = 0; _i < 2; ++_i) \
;         __builtin_amdgcn_global_load_lds((const unsigned*)((const char*)(gbase) + (voff)[_i]), (LAS unsigned*)(lds + (bufoff) + ldsw + _i * 8192), 16, 0, 0); } while (0)
; #define PG8_LDA(dst, b, h) do { _Pragma("unroll") for (int m = 0; m < 4; ++m) _Pragma("unroll") for (int k = 0; k < 2; ++k) dst[m][k] = *(const LAS bf16x8*)(lds + PG8_SA(b, h) + aoff + m * 2048 + k * 1024); } while (0)
; #define PG8_LDB(dst, b, h) do { _Pragma("unroll") for (int n = 0; n < 2; ++n) _Pragma("unroll") for (int k = 0; k < 2; ++k) dst[n][k] = *(const LAS bf16x8*)(lds + PG8_SB(b, h) + boff + n * 2048 + k * 1024); } while (0)
; #define PG8_MMA(ai, bj, At, Bt) do { __builtin_amdgcn_s_setprio(1); _Pragma("unroll") for (int m = 0; m < 4; ++m) _Pragma("unroll") for (int n = 0; n < 2; ++n) _Pragma("unroll") for (int k = 0; k < 2; ++k) \
;         acc[ai][bj][m][n] = __builtin_amdgcn_mfma_f32_16x16x32_bf16(Bt[n][k], At[m][k], acc[ai][bj][m][n], 0, 0, 0); __builtin_amdgcn_s_setprio(0); } while (0)
; #define PG8_WAIT_V(n) asm volatile("s_waitcnt vmcnt(" #n ")" ::: "memory")
; #define PG8_WAIT_L(n) asm volatile("s_waitcnt lgkmcnt(" #n ")" ::: "memory")
; #define PG8_BAR __builtin_amdgcn_s_barrier()
; #define PG8_SCHED __builtin_amdgcn_sched_barrier(0)
; template <bool HM = false, bool PERM = false, bool CP = false, class Prob, class Epi>
; __device__ __forceinline__ void gemm_phase(LAS unsigned char* lds, const Prob& S, const Epi& E) {
;     ...
;             PG8_WAIT_V(8); PG8_WAIT_L(0); PG8_BAR; if (!HM) { if (!CP || fullu) PG8_MMA(1, 0, At, B0); PG8_MMA(1, 1, At, B1); } PG8_BAR; PG8_SCHED;
;             PG8_LDB(B0, 1, 0); PG8_LDB(B1, 1, 1); PG8_SCHED; PG8_LDA(At, 1, 0); PG8_STAGE(PG8_SA(0, 1), a2 + hstepA, voffA);
;             PG8_WAIT_V(8); PG8_WAIT_L(0); PG8_BAR; if (!CP || fullu) PG8_MMA(0, 0, At, B0); PG8_MMA(0, 1, At, B1); PG8_BAR; PG8_SCHED;
	s_waitcnt lgkmcnt(0)
	v_mfma_f32_16x16x32_bf16 v[62:65], v[142:145], v[178:181], v[62:65]
	v_mfma_f32_16x16x32_bf16 v[58:61], v[154:157], v[178:181], v[58:61]
	v_mfma_f32_16x16x32_bf16 v[54:57], v[142:145], v[186:189], v[54:57]
	v_mfma_f32_16x16x32_bf16 v[50:53], v[154:157], v[186:189], v[50:53]
	v_mfma_f32_16x16x32_bf16 v[38:41], v[142:145], v[194:197], v[38:41]
	v_mfma_f32_16x16x32_bf16 v[34:37], v[154:157], v[194:197], v[34:37]
	v_mfma_f32_16x16x32_bf16 v[22:25], v[142:145], v[202:205], v[22:25]
	v_mfma_f32_16x16x32_bf16 v[18:21], v[154:157], v[202:205], v[18:21]
	v_mfma_f32_16x16x32_bf16 v[62:65], v[150:153], v[182:185], v[62:65]
	v_mfma_f32_16x16x32_bf16 v[58:61], v[158:161], v[182:185], v[58:61]
	v_mfma_f32_16x16x32_bf16 v[54:57], v[150:153], v[190:193], v[54:57]
	v_mfma_f32_16x16x32_bf16 v[50:53], v[158:161], v[190:193], v[50:53]
	v_mfma_f32_16x16x32_bf16 v[38:41], v[150:153], v[198:201], v[38:41]
	v_mfma_f32_16x16x32_bf16 v[34:37], v[158:161], v[198:201], v[34:37]
	v_mfma_f32_16x16x32_bf16 v[22:25], v[150:153], v[206:209], v[22:25]
	v_mfma_f32_16x16x32_bf16 v[18:21], v[158:161], v[206:209], v[18:21]
	v_mfma_f32_16x16x32_bf16 v[46:49], v[162:165], v[178:181], v[46:49]
	v_mfma_f32_16x16x32_bf16 v[42:45], v[170:173], v[178:181], v[42:45]
	v_mfma_f32_16x16x32_bf16 v[30:33], v[162:165], v[186:189], v[30:33]
	v_mfma_f32_16x16x32_bf16 v[26:29], v[170:173], v[186:189], v[26:29]
	v_mfma_f32_16x16x32_bf16 v[14:17], v[162:165], v[194:197], v[14:17]
	v_mfma_f32_16x16x32_bf16 v[10:13], v[170:173], v[194:197], v[10:13]
	v_mfma_f32_16x16x32_bf16 v[6:9], v[162:165], v[202:205], v[6:9]
	v_mfma_f32_16x16x32_bf16 v[2:5], v[170:173], v[202:205], v[2:5]
	v_mfma_f32_16x16x32_bf16 v[46:49], v[166:169], v[182:185], v[46:49]
	v_mfma_f32_16x16x32_bf16 v[42:45], v[174:177], v[182:185], v[42:45]
	v_mfma_f32_16x16x32_bf16 v[30:33], v[166:169], v[190:193], v[30:33]
	v_mfma_f32_16x16x32_bf16 v[26:29], v[174:177], v[190:193], v[26:29]
	v_mfma_f32_16x16x32_bf16 v[14:17], v[166:169], v[198:201], v[14:17]
	v_mfma_f32_16x16x32_bf16 v[10:13], v[174:177], v[198:201], v[10:13]
	v_mfma_f32_16x16x32_bf16 v[6:9], v[166:169], v[206:209], v[6:9]
	v_mfma_f32_16x16x32_bf16 v[2:5], v[174:177], v[206:209], v[2:5]
	s_barrier
	s_add_i32 s76, 0, 0x18000
	v_add_u32_e32 v0, s76, v148
	s_add_i32 s77, 0, 0x1c000
	ds_read_b128 v[142:145], v0
	ds_read_b128 v[150:153], v0 offset:1024
	ds_read_b128 v[154:157], v0 offset:2048
	ds_read_b128 v[158:161], v0 offset:3072
	v_add_u32_e32 v0, s77, v148
	ds_read_b128 v[162:165], v0
	ds_read_b128 v[166:169], v0 offset:1024
	ds_read_b128 v[170:173], v0 offset:2048
	ds_read_b128 v[174:177], v0 offset:3072
	s_add_u32 s24, s24, 0x40000
	s_addc_u32 s25, s25, 0
	s_mov_b32 m0, s33
	v_lshl_add_u64 v[232:233], s[24:25], 0, v[130:131]
	ds_read_b128 v[178:181], v149 offset:32768
	ds_read_b128 v[182:185], v149 offset:33792
	ds_read_b128 v[186:189], v149 offset:34816
	ds_read_b128 v[190:193], v149 offset:35840
	ds_read_b128 v[194:197], v149 offset:36864
	ds_read_b128 v[198:201], v149 offset:37888
	ds_read_b128 v[202:205], v149 offset:38912
	ds_read_b128 v[206:209], v149 offset:39936
	global_load_lds_dwordx4 v[232:233], off
	v_lshl_add_u64 v[232:233], s[24:25], 0, v[134:135]
	s_mov_b32 m0, s34
	s_nop 0
	global_load_lds_dwordx4 v[232:233], off
	s_waitcnt vmcnt(8)
	s_waitcnt lgkmcnt(0)
	s_barrier
	s_waitcnt lgkmcnt(0)
	v_mfma_f32_16x16x32_bf16 v[126:129], v[142:145], v[178:181], v[126:129]
	v_mfma_f32_16x16x32_bf16 v[122:125], v[154:157], v[178:181], v[122:125]
	v_mfma_f32_16x16x32_bf16 v[118:121], v[142:145], v[186:189], v[118:121]
	v_mfma_f32_16x16x32_bf16 v[110:113], v[154:157], v[186:189], v[110:113]
	v_mfma_f32_16x16x32_bf16 v[102:105], v[142:145], v[194:197], v[102:105]
	v_mfma_f32_16x16x32_bf16 v[98:101], v[154:157], v[194:197], v[98:101]
	v_mfma_f32_16x16x32_bf16 v[86:89], v[142:145], v[202:205], v[86:89]
	v_mfma_f32_16x16x32_bf16 v[82:85], v[154:157], v[202:205], v[82:85]
	v_mfma_f32_16x16x32_bf16 v[126:129], v[150:153], v[182:185], v[126:129]
	v_mfma_f32_16x16x32_bf16 v[122:125], v[158:161], v[182:185], v[122:125]
	v_mfma_f32_16x16x32_bf16 v[118:121], v[150:153], v[190:193], v[118:121]
	v_mfma_f32_16x16x32_bf16 v[110:113], v[158:161], v[190:193], v[110:113]
	v_mfma_f32_16x16x32_bf16 v[102:105], v[150:153], v[198:201], v[102:105]
	v_mfma_f32_16x16x32_bf16 v[98:101], v[158:161], v[198:201], v[98:101]
	v_mfma_f32_16x16x32_bf16 v[86:89], v[150:153], v[206:209], v[86:89]
	v_mfma_f32_16x16x32_bf16 v[82:85], v[158:161], v[206:209], v[82:85]
	v_mfma_f32_16x16x32_bf16 v[114:117], v[162:165], v[178:181], v[114:117]
	v_mfma_f32_16x16x32_bf16 v[106:109], v[170:173], v[178:181], v[106:109]
	v_mfma_f32_16x16x32_bf16 v[94:97], v[162:165], v[186:189], v[94:97]
	v_mfma_f32_16x16x32_bf16 v[90:93], v[170:173], v[186:189], v[90:93]
	v_mfma_f32_16x16x32_bf16 v[78:81], v[162:165], v[194:197], v[78:81]
	v_mfma_f32_16x16x32_bf16 v[74:77], v[170:173], v[194:197], v[74:77]
	v_mfma_f32_16x16x32_bf16 v[70:73], v[162:165], v[202:205], v[70:73]
	v_mfma_f32_16x16x32_bf16 v[66:69], v[170:173], v[202:205], v[66:69]
	v_mfma_f32_16x16x32_bf16 v[114:117], v[166:169], v[182:185], v[114:117]
	v_mfma_f32_16x16x32_bf16 v[106:109], v[174:177], v[182:185], v[106:109]
	v_mfma_f32_16x16x32_bf16 v[94:97], v[166:169], v[190:193], v[94:97]
	v_mfma_f32_16x16x32_bf16 v[90:93], v[174:177], v[190:193], v[90:93]
	v_mfma_f32_16x16x32_bf16 v[78:81], v[166:169], v[198:201], v[78:81]
	v_mfma_f32_16x16x32_bf16 v[74:77], v[174:177], v[198:201], v[74:77]
	v_mfma_f32_16x16x32_bf16 v[70:73], v[166:169], v[206:209], v[70:73]
	v_mfma_f32_16x16x32_bf16 v[66:69], v[174:177], v[206:209], v[66:69]
	s_barrier
; #define PG8_STAGE(bufoff, gbase, voff) do { _Pragma("unroll") for (int _i = 0; _i < 2; ++_i) \
;         __builtin_amdgcn_global_load_lds((const unsigned*)((const char*)(gbase) + (voff)[_i]), (LAS unsigned*)(lds + (bufoff) + ldsw + _i * 8192), 16, 0, 0); } while (0)
; #define PG8_LDA(dst, b, h) do { _Pragma("unroll") for (int m = 0; m < 4; ++m) _Pragma("unroll") for (int k = 0; k < 2; ++k) dst[m][k] = *(const LAS bf16x8*)(lds + PG8_SA(b, h) + aoff + m * 2048 + k * 1024); } while (0)
; #define PG8_MMA(ai, bj, At, Bt) do { __builtin_amdgcn_s_setprio(1); _Pragma("unroll") for (int m = 0; m < 4; ++m) _Pragma("unroll") for (int n = 0; n < 2; ++n) _Pragma("unroll") for (int k = 0; k < 2; ++k) \
;         acc[ai][bj][m][n] = __builtin_amdgcn_mfma_f32_16x16x32_bf16(Bt[n][k], At[m][k], acc[ai][bj][m][n], 0, 0, 0); __builtin_amdgcn_s_setprio(0); } while (0)
; #define PG8_WAIT_V(n) asm volatile("s_waitcnt vmcnt(" #n ")" ::: "memory")
; #define PG8_WAIT_L(n) asm volatile("s_waitcnt lgkmcnt(" #n ")" ::: "memory")
; #define PG8_BAR __builtin_amdgcn_s_barrier()
; #define PG8_SCHED __builtin_amdgcn_sched_barrier(0)
; template <bool HM = false, bool PERM = false, bool CP = false, class Prob, class Epi>
; __device__ __forceinline__ void gemm_phase(LAS unsigned char* lds, const Prob& S, const Epi& E) {
;     ...
;         for (int t = 0; t < nt; t += 2) {
;     ...
;             if (!HM) PG8_LDA(At, 1, 1); PG8_STAGE(PG8_SB(1, 0), b3, voffB); PG8_STAGE(PG8_SB(1, 1), b3 + h2, voffB); PG8_STAGE(PG8_SA(1, 0), a3, voffA);
;             PG8_WAIT_V(8); PG8_WAIT_L(0); PG8_BAR; if (!HM) { if (!CP || fullu) PG8_MMA(1, 0, At, B0); PG8_MMA(1, 1, At, B1); } PG8_BAR; PG8_SCHED;
	s_add_i32 s24, s76, s18
	v_lshl_add_u64 v[210:211], v[210:211], 0, s[20:21]
	s_mov_b32 m0, s24
	ds_read_b128 v[178:181], v149 offset:49152
	ds_read_b128 v[182:185], v149 offset:50176
	ds_read_b128 v[186:189], v149 offset:51200
	ds_read_b128 v[190:193], v149 offset:52224
	ds_read_b128 v[194:197], v149 offset:53248
	ds_read_b128 v[198:201], v149 offset:54272
	ds_read_b128 v[202:205], v149 offset:55296
	ds_read_b128 v[206:209], v149 offset:56320
	global_load_lds_dwordx4 v[210:211], off
	s_add_i32 m0, s24, 0x2000
	s_add_u32 s8, s8, 0x40080
	v_lshl_add_u64 v[210:211], v[212:213], 0, s[20:21]
	s_addc_u32 s9, s9, 0
	s_add_i32 s24, s77, s18
	global_load_lds_dwordx4 v[210:211], off
	v_lshl_add_u64 v[210:211], s[8:9], 0, v[132:133]
	s_mov_b32 m0, s24
	s_nop 0
	global_load_lds_dwordx4 v[210:211], off
	v_lshl_add_u64 v[210:211], s[8:9], 0, v[136:137]
	s_add_i32 m0, s24, 0x2000
	s_nop 0
	global_load_lds_dwordx4 v[210:211], off
	v_lshl_add_u64 v[210:211], v[214:215], 0, s[20:21]
	s_mov_b32 m0, s61
	s_nop 0
	global_load_lds_dwordx4 v[210:211], off
	v_lshl_add_u64 v[210:211], v[230:231], 0, s[20:21]
	s_mov_b32 m0, s62
	s_nop 0
	global_load_lds_dwordx4 v[210:211], off
	s_waitcnt vmcnt(8)
	s_waitcnt lgkmcnt(0)
	s_barrier
	s_waitcnt lgkmcnt(0)
	v_mfma_f32_16x16x32_bf16 v[62:65], v[142:145], v[178:181], v[62:65]
	v_mfma_f32_16x16x32_bf16 v[58:61], v[154:157], v[178:181], v[58:61]
	v_mfma_f32_16x16x32_bf16 v[54:57], v[142:145], v[186:189], v[54:57]
	v_mfma_f32_16x16x32_bf16 v[50:53], v[154:157], v[186:189], v[50:53]
	v_mfma_f32_16x16x32_bf16 v[38:41], v[142:145], v[194:197], v[38:41]
	v_mfma_f32_16x16x32_bf16 v[34:37], v[154:157], v[194:197], v[34:37]
	v_mfma_f32_16x16x32_bf16 v[22:25], v[142:145], v[202:205], v[22:25]
	v_mfma_f32_16x16x32_bf16 v[18:21], v[154:157], v[202:205], v[18:21]
	v_mfma_f32_16x16x32_bf16 v[62:65], v[150:153], v[182:185], v[62:65]
	v_mfma_f32_16x16x32_bf16 v[58:61], v[158:161], v[182:185], v[58:61]
	v_mfma_f32_16x16x32_bf16 v[54:57], v[150:153], v[190:193], v[54:57]
	v_mfma_f32_16x16x32_bf16 v[50:53], v[158:161], v[190:193], v[50:53]
	v_mfma_f32_16x16x32_bf16 v[38:41], v[150:153], v[198:201], v[38:41]
	v_mfma_f32_16x16x32_bf16 v[34:37], v[158:161], v[198:201], v[34:37]
	v_mfma_f32_16x16x32_bf16 v[22:25], v[150:153], v[206:209], v[22:25]
	v_mfma_f32_16x16x32_bf16 v[18:21], v[158:161], v[206:209], v[18:21]
	v_mfma_f32_16x16x32_bf16 v[46:49], v[162:165], v[178:181], v[46:49]
	v_mfma_f32_16x16x32_bf16 v[42:45], v[170:173], v[178:181], v[42:45]
	v_mfma_f32_16x16x32_bf16 v[30:33], v[162:165], v[186:189], v[30:33]
	v_mfma_f32_16x16x32_bf16 v[26:29], v[170:173], v[186:189], v[26:29]
	v_mfma_f32_16x16x32_bf16 v[14:17], v[162:165], v[194:197], v[14:17]
	v_mfma_f32_16x16x32_bf16 v[10:13], v[170:173], v[194:197], v[10:13]
	v_mfma_f32_16x16x32_bf16 v[6:9], v[162:165], v[202:205], v[6:9]
	v_mfma_f32_16x16x32_bf16 v[2:5], v[170:173], v[202:205], v[2:5]
	v_mfma_f32_16x16x32_bf16 v[46:49], v[166:169], v[182:185], v[46:49]
	v_mfma_f32_16x16x32_bf16 v[42:45], v[174:177], v[182:185], v[42:45]
	v_mfma_f32_16x16x32_bf16 v[30:33], v[166:169], v[190:193], v[30:33]
	v_mfma_f32_16x16x32_bf16 v[26:29], v[174:177], v[190:193], v[26:29]
	v_mfma_f32_16x16x32_bf16 v[14:17], v[166:169], v[198:201], v[14:17]
	v_mfma_f32_16x16x32_bf16 v[10:13], v[174:177], v[198:201], v[10:13]
	v_mfma_f32_16x16x32_bf16 v[6:9], v[166:169], v[206:209], v[6:9]
	v_mfma_f32_16x16x32_bf16 v[2:5], v[174:177], v[206:209], v[2:5]
	s_barrier
	s_add_i32 s75, s75, 2
	s_add_u32 s0, s0, 0x100
	s_addc_u32 s1, s1, 0
	s_add_u32 s73, s73, 0x100
	s_addc_u32 s74, s74, 0
	s_cmp_gt_u32 s75, 13
	s_cbranch_scc0 .LBB0_325
	s_and_b64 vcc, exec, s[42:43]
	s_cbranch_vccz .LBB0_328
	s_barrier

; #define PG8_STAGE(bufoff, gbase, voff) do { _Pragma("unroll") for (int _i = 0; _i < 2; ++_i) \
;         __builtin_amdgcn_global_load_lds((const unsigned*)((const char*)(gbase) + (voff)[_i]), (LAS unsigned*)(lds + (bufoff) + ldsw + _i * 8192), 16, 0, 0); } while (0)
; #define PG8_LDA(dst, b, h) do { _Pragma("unroll") for (int m = 0; m < 4; ++m) _Pragma("unroll") for (int k = 0; k < 2; ++k) dst[m][k] = *(const LAS bf16x8*)(lds + PG8_SA(b, h) + aoff + m * 2048 + k * 1024); } while (0)
; #define PG8_LDB(dst, b, h) do { _Pragma("unroll") for (int n = 0; n < 2; ++n) _Pragma("unroll") for (int k = 0; k < 2; ++k) dst[n][k] = *(const LAS bf16x8*)(lds + PG8_SB(b, h) + boff + n * 2048 + k * 1024); } while (0)
; #define PG8_MMA(ai, bj, At, Bt) do { __builtin_amdgcn_s_setprio(1); _Pragma("unroll") for (int m = 0; m < 4; ++m) _Pragma("unroll") for (int n = 0; n < 2; ++n) _Pragma("unroll") for (int k = 0; k < 2; ++k) \
;         acc[ai][bj][m][n] = __builtin_amdgcn_mfma_f32_16x16x32_bf16(Bt[n][k], At[m][k], acc[ai][bj][m][n], 0, 0, 0); __builtin_amdgcn_s_setprio(0); } while (0)
; #define PG8_WAIT_V(n) asm volatile("s_waitcnt vmcnt(" #n ")" ::: "memory")
; #define PG8_WAIT_L(n) asm volatile("s_waitcnt lgkmcnt(" #n ")" ::: "memory")
; #define PG8_BAR __builtin_amdgcn_s_barrier()
; #define PG8_SCHED __builtin_amdgcn_sched_barrier(0)
; template <bool HM = false, bool PERM = false, bool CP = false, class Prob, class Epi>
; __device__ __forceinline__ void gemm_phase(LAS unsigned char* lds, const Prob& S, const Epi& E) {
;     ...
;             const bool last = (t == nt - 2);
;             const char* a1 = cA + (size_t)(t + 1) * kstepA;
;             const char* a2 = last ? nA : cA + (size_t)(t + 2) * kstepA; const char* b2 = last ? nB : cB + (size_t)(t + 2) * kstepB;
;             const char* a3 = a2 + kstepA; const char* b3 = b2 + kstepB; const long h2 = last ? nhB : chB;
;     ...
;             PG8_LDB(B0, 0, 0); PG8_LDB(B1, 0, 1); PG8_SCHED; PG8_LDA(At, 0, 0); PG8_STAGE(PG8_SA(1, 1), a1 + hstepA, voffA);
;             PG8_WAIT_V(8); PG8_WAIT_L(0); PG8_BAR; if (!CP || fullu) PG8_MMA(0, 0, At, B0); PG8_MMA(0, 1, At, B1); PG8_BAR; PG8_SCHED;
;             if (!HM) PG8_LDA(At, 0, 1); PG8_STAGE(PG8_SB(0, 0), b2, voffB); PG8_STAGE(PG8_SB(0, 1), b2 + h2, voffB); PG8_STAGE(PG8_SA(0, 0), a2, voffA);
.LBB0_452:
	s_add_u32 s24, s0, 0x100
	s_addc_u32 s25, s1, 0
	s_cmp_eq_u32 s64, 4
	s_cselect_b32 s49, s45, s25
	s_cselect_b32 s48, s44, s24
	s_cselect_b32 s35, s47, s43
	s_cselect_b32 s34, s46, s39
	s_add_i32 s65, 0, 0x10000
	s_add_i32 s66, 0, 0x14000
	v_add_u32_e32 v156, s65, v146
	v_add_u32_e32 v172, s66, v146
	ds_read_b128 v[140:143], v156
	ds_read_b128 v[148:151], v156 offset:1024
	ds_read_b128 v[152:155], v156 offset:2048
	ds_read_b128 v[156:159], v156 offset:3072
	ds_read_b128 v[160:163], v172
	ds_read_b128 v[164:167], v172 offset:1024
	ds_read_b128 v[168:171], v172 offset:2048
	ds_read_b128 v[172:175], v172 offset:3072
	v_lshl_add_u64 v[208:209], s[0:1], 0, v[136:137]
	s_add_i32 m0, s17, 0xc000
	ds_read_b128 v[176:179], v147
	ds_read_b128 v[180:183], v147 offset:1024
	ds_read_b128 v[184:187], v147 offset:2048
	ds_read_b128 v[188:191], v147 offset:3072
	ds_read_b128 v[192:195], v147 offset:4096
	ds_read_b128 v[196:199], v147 offset:5120
	ds_read_b128 v[200:203], v147 offset:6144
	ds_read_b128 v[204:207], v147 offset:7168
	global_load_lds_dwordx4 v[208:209], off
	v_lshl_add_u64 v[208:209], s[0:1], 0, v[138:139]
	s_add_i32 m0, s17, 0xe000
	s_nop 0
	global_load_lds_dwordx4 v[208:209], off
	s_waitcnt vmcnt(8)
	s_waitcnt lgkmcnt(0)
	s_barrier
	s_waitcnt lgkmcnt(0)
	v_mfma_f32_16x16x32_bf16 v[126:129], v[140:143], v[176:179], v[126:129]
	v_mfma_f32_16x16x32_bf16 v[122:125], v[152:155], v[176:179], v[122:125]
	v_mfma_f32_16x16x32_bf16 v[118:121], v[140:143], v[184:187], v[118:121]
	v_mfma_f32_16x16x32_bf16 v[110:113], v[152:155], v[184:187], v[110:113]
	v_mfma_f32_16x16x32_bf16 v[102:105], v[140:143], v[192:195], v[102:105]
	v_mfma_f32_16x16x32_bf16 v[94:97], v[152:155], v[192:195], v[94:97]
	v_mfma_f32_16x16x32_bf16 v[86:89], v[140:143], v[200:203], v[86:89]
	v_mfma_f32_16x16x32_bf16 v[78:81], v[152:155], v[200:203], v[78:81]
	v_mfma_f32_16x16x32_bf16 v[126:129], v[148:151], v[180:183], v[126:129]
	v_mfma_f32_16x16x32_bf16 v[122:125], v[156:159], v[180:183], v[122:125]
	v_mfma_f32_16x16x32_bf16 v[118:121], v[148:151], v[188:191], v[118:121]
	v_mfma_f32_16x16x32_bf16 v[110:113], v[156:159], v[188:191], v[110:113]
	v_mfma_f32_16x16x32_bf16 v[102:105], v[148:151], v[196:199], v[102:105]
	v_mfma_f32_16x16x32_bf16 v[94:97], v[156:159], v[196:199], v[94:97]
	v_mfma_f32_16x16x32_bf16 v[86:89], v[148:151], v[204:207], v[86:89]
	v_mfma_f32_16x16x32_bf16 v[78:81], v[156:159], v[204:207], v[78:81]
	v_mfma_f32_16x16x32_bf16 v[114:117], v[160:163], v[176:179], v[114:117]
	v_mfma_f32_16x16x32_bf16 v[106:109], v[168:171], v[176:179], v[106:109]
	v_mfma_f32_16x16x32_bf16 v[98:101], v[160:163], v[184:187], v[98:101]
	v_mfma_f32_16x16x32_bf16 v[90:93], v[168:171], v[184:187], v[90:93]
	v_mfma_f32_16x16x32_bf16 v[82:85], v[160:163], v[192:195], v[82:85]
	v_mfma_f32_16x16x32_bf16 v[74:77], v[168:171], v[192:195], v[74:77]
	v_mfma_f32_16x16x32_bf16 v[70:73], v[160:163], v[200:203], v[70:73]
	v_mfma_f32_16x16x32_bf16 v[66:69], v[168:171], v[200:203], v[66:69]
	v_mfma_f32_16x16x32_bf16 v[114:117], v[164:167], v[180:183], v[114:117]
	v_mfma_f32_16x16x32_bf16 v[106:109], v[172:175], v[180:183], v[106:109]
	v_mfma_f32_16x16x32_bf16 v[98:101], v[164:167], v[188:191], v[98:101]
	v_mfma_f32_16x16x32_bf16 v[90:93], v[172:175], v[188:191], v[90:93]
	v_mfma_f32_16x16x32_bf16 v[82:85], v[164:167], v[196:199], v[82:85]
	v_mfma_f32_16x16x32_bf16 v[74:77], v[172:175], v[196:199], v[74:77]
	v_mfma_f32_16x16x32_bf16 v[70:73], v[164:167], v[204:207], v[70:73]
	v_mfma_f32_16x16x32_bf16 v[66:69], v[172:175], v[204:207], v[66:69]
	s_barrier
	s_add_i32 s0, s65, s52
	v_lshl_add_u64 v[208:209], s[34:35], 0, v[0:1]
	s_mov_b32 m0, s0
	ds_read_b128 v[176:179], v147 offset:16384
	ds_read_b128 v[180:183], v147 offset:17408
	ds_read_b128 v[184:187], v147 offset:18432
	ds_read_b128 v[188:191], v147 offset:19456
	ds_read_b128 v[192:195], v147 offset:20480
	ds_read_b128 v[196:199], v147 offset:21504
	ds_read_b128 v[200:203], v147 offset:22528
	ds_read_b128 v[204:207], v147 offset:23552
	global_load_lds_dwordx4 v[208:209], off
	s_add_i32 m0, s0, 0x2000
	s_add_u32 s0, s34, 0x20000
	v_lshl_add_u64 v[210:211], s[34:35], 0, v[134:135]
	s_addc_u32 s1, s35, 0
	s_add_i32 s65, s66, s52
	global_load_lds_dwordx4 v[210:211], off
	v_lshl_add_u64 v[212:213], s[0:1], 0, v[0:1]
	s_mov_b32 m0, s65
	v_lshl_add_u64 v[214:215], s[48:49], 0, v[132:133]
	global_load_lds_dwordx4 v[212:213], off
	v_lshl_add_u64 v[212:213], s[0:1], 0, v[134:135]
	s_add_i32 m0, s65, 0x2000
	s_nop 0
	global_load_lds_dwordx4 v[212:213], off
	v_lshl_add_u64 v[212:213], s[48:49], 0, v[130:131]
	s_mov_b32 m0, s17
	s_nop 0
	global_load_lds_dwordx4 v[212:213], off
	s_mov_b32 m0, s53
	s_nop 0
	global_load_lds_dwordx4 v[214:215], off
	s_waitcnt vmcnt(8)
	s_waitcnt lgkmcnt(0)
	s_barrier
; #define PG8_STAGE(bufoff, gbase, voff) do { _Pragma("unroll") for (int _i = 0; _i < 2; ++_i) \
;         __builtin_amdgcn_global_load_lds((const unsigned*)((const char*)(gbase) + (voff)[_i]), (LAS unsigned*)(lds + (bufoff) + ldsw + _i * 8192), 16, 0, 0); } while (0)
; #define PG8_LDA(dst, b, h) do { _Pragma("unroll") for (int m = 0; m < 4; ++m) _Pragma("unroll") for (int k = 0; k < 2; ++k) dst[m][k] = *(const LAS bf16x8*)(lds + PG8_SA(b, h) + aoff + m * 2048 + k * 1024); } while (0)
; #define PG8_LDB(dst, b, h) do { _Pragma("unroll") for (int n = 0; n < 2; ++n) _Pragma("unroll") for (int k = 0; k < 2; ++k) dst[n][k] = *(const LAS bf16x8*)(lds + PG8_SB(b, h) + boff + n * 2048 + k * 1024); } while (0)
; #define PG8_MMA(ai, bj, At, Bt) do { __builtin_amdgcn_s_setprio(1); _Pragma("unroll") for (int m = 0; m < 4; ++m) _Pragma("unroll") for (int n = 0; n < 2; ++n) _Pragma("unroll") for (int k = 0; k < 2; ++k) \
;         acc[ai][bj][m][n] = __builtin_amdgcn_mfma_f32_16x16x32_bf16(Bt[n][k], At[m][k], acc[ai][bj][m][n], 0, 0, 0); __builtin_amdgcn_s_setprio(0); } while (0)
; #define PG8_WAIT_V(n) asm volatile("s_waitcnt vmcnt(" #n ")" ::: "memory")
; #define PG8_WAIT_L(n) asm volatile("s_waitcnt lgkmcnt(" #n ")" ::: "memory")
; #define PG8_BAR __builtin_amdgcn_s_barrier()
; #define PG8_SCHED __builtin_amdgcn_sched_barrier(0)
; template <bool HM = false, bool PERM = false, bool CP = false, class Prob, class Epi>
; __device__ __forceinline__ void gemm_phase(LAS unsigned char* lds, const Prob& S, const Epi& E) {
;     ...
;             PG8_WAIT_V(8); PG8_WAIT_L(0); PG8_BAR; if (!HM) { if (!CP || fullu) PG8_MMA(1, 0, At, B0); PG8_MMA(1, 1, At, B1); } PG8_BAR; PG8_SCHED;
;             PG8_LDB(B0, 1, 0); PG8_LDB(B1, 1, 1); PG8_SCHED; PG8_LDA(At, 1, 0); PG8_STAGE(PG8_SA(0, 1), a2 + hstepA, voffA);
;             PG8_WAIT_V(8); PG8_WAIT_L(0); PG8_BAR; if (!CP || fullu) PG8_MMA(0, 0, At, B0); PG8_MMA(0, 1, At, B1); PG8_BAR; PG8_SCHED;
	s_waitcnt lgkmcnt(0)
	v_mfma_f32_16x16x32_bf16 v[62:65], v[140:143], v[176:179], v[62:65]
	v_mfma_f32_16x16x32_bf16 v[58:61], v[152:155], v[176:179], v[58:61]
	v_mfma_f32_16x16x32_bf16 v[54:57], v[140:143], v[184:187], v[54:57]
	v_mfma_f32_16x16x32_bf16 v[46:49], v[152:155], v[184:187], v[46:49]
	v_mfma_f32_16x16x32_bf16 v[38:41], v[140:143], v[192:195], v[38:41]
	v_mfma_f32_16x16x32_bf16 v[30:33], v[152:155], v[192:195], v[30:33]
	v_mfma_f32_16x16x32_bf16 v[22:25], v[140:143], v[200:203], v[22:25]
	v_mfma_f32_16x16x32_bf16 v[14:17], v[152:155], v[200:203], v[14:17]
	v_mfma_f32_16x16x32_bf16 v[62:65], v[148:151], v[180:183], v[62:65]
	v_mfma_f32_16x16x32_bf16 v[58:61], v[156:159], v[180:183], v[58:61]
	v_mfma_f32_16x16x32_bf16 v[54:57], v[148:151], v[188:191], v[54:57]
	v_mfma_f32_16x16x32_bf16 v[46:49], v[156:159], v[188:191], v[46:49]
	v_mfma_f32_16x16x32_bf16 v[38:41], v[148:151], v[196:199], v[38:41]
	v_mfma_f32_16x16x32_bf16 v[30:33], v[156:159], v[196:199], v[30:33]
	v_mfma_f32_16x16x32_bf16 v[22:25], v[148:151], v[204:207], v[22:25]
	v_mfma_f32_16x16x32_bf16 v[14:17], v[156:159], v[204:207], v[14:17]
	v_mfma_f32_16x16x32_bf16 v[50:53], v[160:163], v[176:179], v[50:53]
	v_mfma_f32_16x16x32_bf16 v[42:45], v[168:171], v[176:179], v[42:45]
	v_mfma_f32_16x16x32_bf16 v[34:37], v[160:163], v[184:187], v[34:37]
	v_mfma_f32_16x16x32_bf16 v[26:29], v[168:171], v[184:187], v[26:29]
	v_mfma_f32_16x16x32_bf16 v[18:21], v[160:163], v[192:195], v[18:21]
	v_mfma_f32_16x16x32_bf16 v[10:13], v[168:171], v[192:195], v[10:13]
	v_mfma_f32_16x16x32_bf16 v[6:9], v[160:163], v[200:203], v[6:9]
	v_mfma_f32_16x16x32_bf16 v[2:5], v[168:171], v[200:203], v[2:5]
	v_mfma_f32_16x16x32_bf16 v[50:53], v[164:167], v[180:183], v[50:53]
	v_mfma_f32_16x16x32_bf16 v[42:45], v[172:175], v[180:183], v[42:45]
	v_mfma_f32_16x16x32_bf16 v[34:37], v[164:167], v[188:191], v[34:37]
	v_mfma_f32_16x16x32_bf16 v[26:29], v[172:175], v[188:191], v[26:29]
	v_mfma_f32_16x16x32_bf16 v[18:21], v[164:167], v[196:199], v[18:21]
	v_mfma_f32_16x16x32_bf16 v[10:13], v[172:175], v[196:199], v[10:13]
	v_mfma_f32_16x16x32_bf16 v[6:9], v[164:167], v[204:207], v[6:9]
	v_mfma_f32_16x16x32_bf16 v[2:5], v[172:175], v[204:207], v[2:5]
	s_barrier
	s_add_i32 s65, 0, 0x18000
	s_add_i32 s66, 0, 0x1c000
	v_add_u32_e32 v156, s65, v146
	v_add_u32_e32 v172, s66, v146
	ds_read_b128 v[140:143], v156
	ds_read_b128 v[148:151], v156 offset:1024
	ds_read_b128 v[152:155], v156 offset:2048
	ds_read_b128 v[156:159], v156 offset:3072
	ds_read_b128 v[160:163], v172
	ds_read_b128 v[164:167], v172 offset:1024
	ds_read_b128 v[168:171], v172 offset:2048
	ds_read_b128 v[172:175], v172 offset:3072
	s_add_u32 s0, s48, 0x30000
	s_addc_u32 s1, s49, 0
	s_mov_b32 m0, s54
	v_lshl_add_u64 v[230:231], s[0:1], 0, v[130:131]
	ds_read_b128 v[176:179], v147 offset:32768
	ds_read_b128 v[180:183], v147 offset:33792
	ds_read_b128 v[184:187], v147 offset:34816
	ds_read_b128 v[188:191], v147 offset:35840
	ds_read_b128 v[192:195], v147 offset:36864
	ds_read_b128 v[196:199], v147 offset:37888
	ds_read_b128 v[200:203], v147 offset:38912
	ds_read_b128 v[204:207], v147 offset:39936
	global_load_lds_dwordx4 v[230:231], off
	v_lshl_add_u64 v[230:231], s[0:1], 0, v[132:133]
	s_mov_b32 m0, s55
	s_nop 0
	global_load_lds_dwordx4 v[230:231], off
	s_waitcnt vmcnt(8)
	s_waitcnt lgkmcnt(0)
	s_barrier
	s_waitcnt lgkmcnt(0)
	v_mfma_f32_16x16x32_bf16 v[126:129], v[140:143], v[176:179], v[126:129]
	v_mfma_f32_16x16x32_bf16 v[122:125], v[152:155], v[176:179], v[122:125]
	v_mfma_f32_16x16x32_bf16 v[118:121], v[140:143], v[184:187], v[118:121]
	v_mfma_f32_16x16x32_bf16 v[110:113], v[152:155], v[184:187], v[110:113]
	v_mfma_f32_16x16x32_bf16 v[102:105], v[140:143], v[192:195], v[102:105]
	v_mfma_f32_16x16x32_bf16 v[94:97], v[152:155], v[192:195], v[94:97]
	v_mfma_f32_16x16x32_bf16 v[86:89], v[140:143], v[200:203], v[86:89]
	v_mfma_f32_16x16x32_bf16 v[78:81], v[152:155], v[200:203], v[78:81]
	v_mfma_f32_16x16x32_bf16 v[126:129], v[148:151], v[180:183], v[126:129]
	v_mfma_f32_16x16x32_bf16 v[122:125], v[156:159], v[180:183], v[122:125]
	v_mfma_f32_16x16x32_bf16 v[118:121], v[148:151], v[188:191], v[118:121]
	v_mfma_f32_16x16x32_bf16 v[110:113], v[156:159], v[188:191], v[110:113]
	v_mfma_f32_16x16x32_bf16 v[102:105], v[148:151], v[196:199], v[102:105]
	v_mfma_f32_16x16x32_bf16 v[94:97], v[156:159], v[196:199], v[94:97]
	v_mfma_f32_16x16x32_bf16 v[86:89], v[148:151], v[204:207], v[86:89]
	v_mfma_f32_16x16x32_bf16 v[78:81], v[156:159], v[204:207], v[78:81]
	v_mfma_f32_16x16x32_bf16 v[114:117], v[160:163], v[176:179], v[114:117]
	v_mfma_f32_16x16x32_bf16 v[106:109], v[168:171], v[176:179], v[106:109]
	v_mfma_f32_16x16x32_bf16 v[98:101], v[160:163], v[184:187], v[98:101]
	v_mfma_f32_16x16x32_bf16 v[90:93], v[168:171], v[184:187], v[90:93]
	v_mfma_f32_16x16x32_bf16 v[82:85], v[160:163], v[192:195], v[82:85]
	v_mfma_f32_16x16x32_bf16 v[74:77], v[168:171], v[192:195], v[74:77]
	v_mfma_f32_16x16x32_bf16 v[70:73], v[160:163], v[200:203], v[70:73]
	v_mfma_f32_16x16x32_bf16 v[66:69], v[168:171], v[200:203], v[66:69]
	v_mfma_f32_16x16x32_bf16 v[114:117], v[164:167], v[180:183], v[114:117]
	v_mfma_f32_16x16x32_bf16 v[106:109], v[172:175], v[180:183], v[106:109]
	v_mfma_f32_16x16x32_bf16 v[98:101], v[164:167], v[188:191], v[98:101]
	v_mfma_f32_16x16x32_bf16 v[90:93], v[172:175], v[188:191], v[90:93]
	v_mfma_f32_16x16x32_bf16 v[82:85], v[164:167], v[196:199], v[82:85]
	v_mfma_f32_16x16x32_bf16 v[74:77], v[172:175], v[196:199], v[74:77]
	v_mfma_f32_16x16x32_bf16 v[70:73], v[164:167], v[204:207], v[70:73]
	v_mfma_f32_16x16x32_bf16 v[66:69], v[172:175], v[204:207], v[66:69]
	s_barrier
; #define PG8_STAGE(bufoff, gbase, voff) do { _Pragma("unroll") for (int _i = 0; _i < 2; ++_i) \
;         __builtin_amdgcn_global_load_lds((const unsigned*)((const char*)(gbase) + (voff)[_i]), (LAS unsigned*)(lds + (bufoff) + ldsw + _i * 8192), 16, 0, 0); } while (0)
; #define PG8_LDA(dst, b, h) do { _Pragma("unroll") for (int m = 0; m < 4; ++m) _Pragma("unroll") for (int k = 0; k < 2; ++k) dst[m][k] = *(const LAS bf16x8*)(lds + PG8_SA(b, h) + aoff + m * 2048 + k * 1024); } while (0)
; #define PG8_MMA(ai, bj, At, Bt) do { __builtin_amdgcn_s_setprio(1); _Pragma("unroll") for (int m = 0; m < 4; ++m) _Pragma("unroll") for (int n = 0; n < 2; ++n) _Pragma("unroll") for (int k = 0; k < 2; ++k) \
;         acc[ai][bj][m][n] = __builtin_amdgcn_mfma_f32_16x16x32_bf16(Bt[n][k], At[m][k], acc[ai][bj][m][n], 0, 0, 0); __builtin_amdgcn_s_setprio(0); } while (0)
; #define PG8_WAIT_V(n) asm volatile("s_waitcnt vmcnt(" #n ")" ::: "memory")
; #define PG8_WAIT_L(n) asm volatile("s_waitcnt lgkmcnt(" #n ")" ::: "memory")
; #define PG8_BAR __builtin_amdgcn_s_barrier()
; #define PG8_SCHED __builtin_amdgcn_sched_barrier(0)
; template <bool HM = false, bool PERM = false, bool CP = false, class Prob, class Epi>
; __device__ __forceinline__ void gemm_phase(LAS unsigned char* lds, const Prob& S, const Epi& E) {
;     ...
;         for (int t = 0; t < nt; t += 2) {
;     ...
;             if (!HM) PG8_LDA(At, 1, 1); PG8_STAGE(PG8_SB(1, 0), b3, voffB); PG8_STAGE(PG8_SB(1, 1), b3 + h2, voffB); PG8_STAGE(PG8_SA(1, 0), a3, voffA);
;             PG8_WAIT_V(8); PG8_WAIT_L(0); PG8_BAR; if (!HM) { if (!CP || fullu) PG8_MMA(1, 0, At, B0); PG8_MMA(1, 1, At, B1); } PG8_BAR; PG8_SCHED;
	s_add_i32 s0, s65, s52
	v_lshl_add_u64 v[208:209], v[208:209], 0, s[20:21]
	s_mov_b32 m0, s0
	ds_read_b128 v[176:179], v147 offset:49152
	ds_read_b128 v[180:183], v147 offset:50176
	ds_read_b128 v[184:187], v147 offset:51200
	ds_read_b128 v[188:191], v147 offset:52224
	ds_read_b128 v[192:195], v147 offset:53248
	ds_read_b128 v[196:199], v147 offset:54272
	ds_read_b128 v[200:203], v147 offset:55296
	ds_read_b128 v[204:207], v147 offset:56320
	global_load_lds_dwordx4 v[208:209], off
	s_add_i32 m0, s0, 0x2000
	s_add_u32 s0, s34, 0x20080
	v_lshl_add_u64 v[208:209], v[210:211], 0, s[20:21]
	s_addc_u32 s1, s35, 0
	s_add_i32 s34, s66, s52
	global_load_lds_dwordx4 v[208:209], off
	v_lshl_add_u64 v[208:209], s[0:1], 0, v[0:1]
	s_mov_b32 m0, s34
	s_nop 0
	global_load_lds_dwordx4 v[208:209], off
	v_lshl_add_u64 v[208:209], s[0:1], 0, v[134:135]
	s_add_i32 m0, s34, 0x2000
	s_nop 0
	global_load_lds_dwordx4 v[208:209], off
	v_lshl_add_u64 v[208:209], v[212:213], 0, s[20:21]
	s_mov_b32 m0, s60
	s_nop 0
	global_load_lds_dwordx4 v[208:209], off
	v_lshl_add_u64 v[208:209], v[214:215], 0, s[20:21]
	s_mov_b32 m0, s61
	s_nop 0
	global_load_lds_dwordx4 v[208:209], off
	s_waitcnt vmcnt(8)
	s_waitcnt lgkmcnt(0)
	s_barrier
	s_waitcnt lgkmcnt(0)
	v_mfma_f32_16x16x32_bf16 v[62:65], v[140:143], v[176:179], v[62:65]
	v_mfma_f32_16x16x32_bf16 v[58:61], v[152:155], v[176:179], v[58:61]
	v_mfma_f32_16x16x32_bf16 v[54:57], v[140:143], v[184:187], v[54:57]
	v_mfma_f32_16x16x32_bf16 v[46:49], v[152:155], v[184:187], v[46:49]
	v_mfma_f32_16x16x32_bf16 v[38:41], v[140:143], v[192:195], v[38:41]
	v_mfma_f32_16x16x32_bf16 v[30:33], v[152:155], v[192:195], v[30:33]
	v_mfma_f32_16x16x32_bf16 v[22:25], v[140:143], v[200:203], v[22:25]
	v_mfma_f32_16x16x32_bf16 v[14:17], v[152:155], v[200:203], v[14:17]
	v_mfma_f32_16x16x32_bf16 v[62:65], v[148:151], v[180:183], v[62:65]
	v_mfma_f32_16x16x32_bf16 v[58:61], v[156:159], v[180:183], v[58:61]
	v_mfma_f32_16x16x32_bf16 v[54:57], v[148:151], v[188:191], v[54:57]
	v_mfma_f32_16x16x32_bf16 v[46:49], v[156:159], v[188:191], v[46:49]
	v_mfma_f32_16x16x32_bf16 v[38:41], v[148:151], v[196:199], v[38:41]
	v_mfma_f32_16x16x32_bf16 v[30:33], v[156:159], v[196:199], v[30:33]
	v_mfma_f32_16x16x32_bf16 v[22:25], v[148:151], v[204:207], v[22:25]
	v_mfma_f32_16x16x32_bf16 v[14:17], v[156:159], v[204:207], v[14:17]
	v_mfma_f32_16x16x32_bf16 v[50:53], v[160:163], v[176:179], v[50:53]
	v_mfma_f32_16x16x32_bf16 v[42:45], v[168:171], v[176:179], v[42:45]
	v_mfma_f32_16x16x32_bf16 v[34:37], v[160:163], v[184:187], v[34:37]
	v_mfma_f32_16x16x32_bf16 v[26:29], v[168:171], v[184:187], v[26:29]
	v_mfma_f32_16x16x32_bf16 v[18:21], v[160:163], v[192:195], v[18:21]
	v_mfma_f32_16x16x32_bf16 v[10:13], v[168:171], v[192:195], v[10:13]
	v_mfma_f32_16x16x32_bf16 v[6:9], v[160:163], v[200:203], v[6:9]
	v_mfma_f32_16x16x32_bf16 v[2:5], v[168:171], v[200:203], v[2:5]
	v_mfma_f32_16x16x32_bf16 v[50:53], v[164:167], v[180:183], v[50:53]
	v_mfma_f32_16x16x32_bf16 v[42:45], v[172:175], v[180:183], v[42:45]
	v_mfma_f32_16x16x32_bf16 v[34:37], v[164:167], v[188:191], v[34:37]
	v_mfma_f32_16x16x32_bf16 v[26:29], v[172:175], v[188:191], v[26:29]
	v_mfma_f32_16x16x32_bf16 v[18:21], v[164:167], v[196:199], v[18:21]
	v_mfma_f32_16x16x32_bf16 v[10:13], v[172:175], v[196:199], v[10:13]
	v_mfma_f32_16x16x32_bf16 v[6:9], v[164:167], v[204:207], v[6:9]
	v_mfma_f32_16x16x32_bf16 v[2:5], v[172:175], v[204:207], v[2:5]
	s_barrier
	s_add_i32 s64, s64, 2
	s_add_u32 s39, s39, 0x100
	s_addc_u32 s43, s43, 0
	s_cmp_gt_u32 s64, 5
	s_mov_b64 s[0:1], s[24:25]
	s_cbranch_scc0 .LBB0_452
	s_and_b64 vcc, exec, s[36:37]
	s_cbranch_vccz .LBB0_455
	s_barrier

; __device__ __forceinline__ void attn_all(KArgs& a, LAS unsigned char* lds, int l) {
;     const int tid = tid_(), lane = tid & 63, wave = __builtin_amdgcn_readfirstlane(tid >> 6), q32 = lane & 31, g = lane >> 5;
;     LAS float* rpb_s = (LAS float*)(lds + 1024);
;     for (int i = tid; i < 3720; i += 512) rpb_s[i] = a.na_rpb[l * 3720 + i] * 1.44269504f;
;     LAS unsigned char* wbuf = lds + 16384 + wave * 16384;
;     __syncthreads();
;     const bf16_t* PA = (const bf16_t*)(a.ws + OFF_R1); const bf16_t* VT = (const bf16_t*)(a.ws + OFF_VT); const bf16_t* KH = (const bf16_t*)(a.ws + OFF_KH); bf16_t* OA = (bf16_t*)(a.ws + OFF_R2 + 2 * SZ_ACT);
;     const int nb = nblk_(), bid = nb - 1 - bid_(), ntb = 1024 + (l < DEPTH - 1 ? 64 : 0);
;     const bool xl = (nb & 7) == 0;
;     const int gw = xl ? (bid >> 3) * 8 + wave : bid * 8 + wave, ngw = xl ? nb : nb * 8, tend = xl ? ntb : 8 * ntb;
;     for (int ti = gw; ti < tend; ti += ngw) {
;         const int b = xl ? (bid & 7) : ti / ntb, task = xl ? ti : ti - b * ntb;
;         int h, qtok, n_local = 0, krow_lo = 0, tc0 = 0, qrow_g = 0, qcol = 0, r0q = 0;
;         float cadd[16];
; #pragma unroll
;         for (int j = 0; j < 16; ++j) cadd[j] = 0.f;
;         if (task < 1024) {
;             h = task & 7; const int cb = (task >> 3) & 3, rp = task >> 5;
;             const int rr0 = 2 * rp; qrow_g = rr0 + (q32 >> 4); qcol = cb * 16 + (q32 & 15);
;             qtok = b * TPB + CTXL + qrow_g * 64 + qcol;
;             r0q = min(max(qrow_g - 4, 0), 56); const int csq = min(max(qcol - 8, 0), 48);
;             tc0 = min(max(cb * 16 - 8, 0), 32);
;             krow_lo = min(max(rr0 - 4, 0), 56); n_local = min(max(rr0 - 3, 0), 56) + 8 - krow_lo;
; #pragma unroll
;             for (int j = 0; j < 16; ++j) { const int ko = 8 * (j >> 2) + 4 * g + (j & 3); cadd[j] = (unsigned)(tc0 + ko - csq) < 16u ? 0.f : -1e30f; }
;         } else { const int j = task - 1024; h = j & 7; qtok = b * TPB + (j >> 3) * 32 + q32; }
;         const bf16_t* KHb = KH + (size_t)(b * 8 + h) * TPB * 64; const bf16_t* VTb = VT + (size_t)(b * 8 + h) * 544 * 512;
;         bf16x8 qf[4];
;         { const bf16_t* qp = PA + (size_t)qtok * PALD + 1536 + h * 64 + g * 8;
; #pragma unroll
;           for (int ks = 0; ks < 4; ++ks) qf[ks] = *(const bf16x8*)(qp + ks * 16); }
;         f32x16 O0, O1;
; #pragma unroll
.LBB0_490:
	s_or_b64 exec, exec, s[0:1]
	s_waitcnt lgkmcnt(0)
	v_readlane_b32 s4, v237, 2
	v_readlane_b32 s5, v237, 3
	s_waitcnt vmcnt(0)
	s_barrier
	s_setprio 0
	s_load_dwordx2 s[0:1], s[4:5], 0xf0
	s_waitcnt lgkmcnt(0)
	s_mov_b32 s1, s84
	s_not_b32 s1, s1
	s_ashr_i32 s8, s6, 6
	s_add_i32 s3, s0, s1
	s_cmp_lt_i32 s2, 3
	s_cselect_b32 s2, s95, 0x400
	s_and_b32 s9, s0, 7
	s_cmp_lg_u32 s9, 0
	s_cselect_b64 s[4:5], -1, 0
	s_and_b32 s22, s3, -8
	s_lshl_b32 s3, s3, 3
	s_lshl_b32 s23, s2, 3
	s_cmp_eq_u32 s9, 0
	s_cselect_b64 s[16:17], -1, 0
	s_and_b64 s[18:19], s[16:17], exec
	s_cselect_b32 s9, s22, s3
	s_cselect_b32 s3, s2, s23
	s_add_i32 s18, s9, s8
	s_cmp_ge_i32 s18, s3
	s_cbranch_scc1 .LBB0_524
	s_lshl_b32 s8, s8, 14
	s_add_i32 s19, s8, 0
	s_add_u32 s24, s14, 0x174f8000
	v_and_b32_e32 v5, 31, v2
	v_bfe_u32 v6, v2, 5, 1
	v_and_b32_e32 v7, 7, v2
	v_bfe_u32 v8, v2, 3, 2
	s_addc_u32 s25, s15, 0
	v_lshlrev_b32_e32 v152, 10, v8
	v_bfe_u32 v8, v5, 3, 1
	v_lshlrev_b32_e32 v153, 7, v7
	v_bitop3_b32 v7, v6, v2, 7 bitop3:0x78
	s_add_u32 s31, s14, 0x152f8000
	v_xor_b32_e32 v7, v7, v8
	s_addc_u32 s33, s15, 0
	s_lshl_b32 s22, s0, 3
	v_lshlrev_b32_e32 v154, 4, v7
	v_or_b32_e32 v7, 2, v6
	s_and_b64 s[8:9], s[16:17], exec
	v_bitop3_b32 v7, v2, v7, 7 bitop3:0x6c
	s_cselect_b32 s34, s0, s22
	v_xor_b32_e32 v7, v7, v8
	s_bfe_u32 s36, s6, 0x30006
	s_bfe_u32 s100, s18, 0x30003
	s_and_b32 s101, s34, 63
	s_cselect_b32 s100, s36, s100
	s_cmp_lg_u64 s[16:17], 0
	s_cselect_b32 s36, s100, s36
	s_and_b32 s35, s1, 7
	v_lshlrev_b32_e32 v150, 2, v6
	v_lshlrev_b32_e32 v0, 3, v6
	v_bfe_u32 v151, v2, 3, 3
	v_lshlrev_b32_e32 v155, 4, v7
	v_or_b32_e32 v7, 4, v6
	v_or_b32_e32 v6, 6, v6
	s_lshl_b32 s6, s36, 6
	s_lshl_b32 s0, s36, 7
	v_and_b32_e32 v3, 63, v2
	v_bfe_u32 v148, v2, 4, 1
	v_and_b32_e32 v149, 15, v2
	v_bitop3_b32 v4, v151, v2, 7 bitop3:0x78
	v_bitop3_b32 v7, v2, v7, 7 bitop3:0x6c
	v_bitop3_b32 v2, v2, v6, 7 bitop3:0x6c
	s_add_u32 s0, s14, s0
	v_xor_b32_e32 v2, v2, v8
	s_addc_u32 s1, s15, 0
	v_lshlrev_b32_e32 v102, 4, v3
	v_lshlrev_b32_e32 v157, 4, v2
	v_cmp_gt_u32_e64 s[40:41], 32, v3
	v_lshl_add_u64 v[2:3], s[0:1], 0, v[0:1]
	s_mov_b64 s[0:1], 0x1daf8000
	v_lshl_add_u64 v[104:105], v[2:3], 0, s[0:1]
	v_cvt_f32_u32_e32 v2, s2
	s_sub_i32 s0, 0, s2
	v_lshlrev_b32_e32 v100, 3, v4
	s_mul_i32 s8, s36, 0x744
	v_rcp_iflag_f32_e32 v2, v2
	v_xor_b32_e32 v4, 8, v100
	v_xor_b32_e32 v7, v7, v8
	s_add_i32 s38, s8, 0
	v_mul_f32_e32 v2, 0x4f7ffffe, v2
	v_cvt_u32_f32_e32 v2, v2
	v_or_b32_e32 v101, 0xfffff000, v5
	v_mov_b32_e32 v103, v1
	v_lshlrev_b32_e32 v156, 4, v7
	v_readfirstlane_b32 s1, v2
	s_mul_i32 s0, s0, s1
	s_mul_hi_u32 s0, s1, s0
	v_lshlrev_b32_e32 v158, 4, v5
	s_add_i32 s37, s1, s0
	s_addk_i32 s38, 0x43c
	s_lshl_b32 s6, s6, 1
	v_lshlrev_b32_e32 v106, 1, v0
	v_lshlrev_b32_e32 v108, 1, v4
	s_add_i32 s39, s19, 0x4400
	s_add_i32 s42, s19, 0x4800
	s_add_i32 s43, s19, 0x4c00
	s_add_i32 s44, s19, 0x5000
	s_add_i32 s45, s19, 0x5400
	s_add_i32 s46, s19, 0x5800
	s_add_i32 s47, s19, 0x5c00
	s_add_i32 s48, s19, 0x6400
	s_add_i32 s49, s19, 0x6800
	s_add_i32 s52, s19, 0x6c00
	s_add_i32 s53, s19, 0x7000
	s_add_i32 s54, s19, 0x7400
	s_add_i32 s55, s19, 0x7800
	s_add_i32 s56, s19, 0x7c00
	s_branch .LBB0_493

; __device__ __forceinline__ void attn_all(KArgs& a, LAS unsigned char* lds, int l) {
;     ...
;     for (int ti = gw; ti < tend; ti += ngw) {
;     ...
;     __syncthreads();
.LBB0_524:
	v_readfirstlane_b32 s100, v216
	s_nop 3
	s_cmpk_lt_u32 s100, 0x100
	s_cbranch_scc1 .Lprio_c
	s_setprio 1

; #define PG8_STAGE(bufoff, gbase, voff) do { _Pragma("unroll") for (int _i = 0; _i < 2; ++_i) \
;         __builtin_amdgcn_global_load_lds((const unsigned*)((const char*)(gbase) + (voff)[_i]), (LAS unsigned*)(lds + (bufoff) + ldsw + _i * 8192), 16, 0, 0); } while (0)
; #define PG8_LDA(dst, b, h) do { _Pragma("unroll") for (int m = 0; m < 4; ++m) _Pragma("unroll") for (int k = 0; k < 2; ++k) dst[m][k] = *(const LAS bf16x8*)(lds + PG8_SA(b, h) + aoff + m * 2048 + k * 1024); } while (0)
; #define PG8_LDB(dst, b, h) do { _Pragma("unroll") for (int n = 0; n < 2; ++n) _Pragma("unroll") for (int k = 0; k < 2; ++k) dst[n][k] = *(const LAS bf16x8*)(lds + PG8_SB(b, h) + boff + n * 2048 + k * 1024); } while (0)
; #define PG8_MMA(ai, bj, At, Bt) do { __builtin_amdgcn_s_setprio(1); _Pragma("unroll") for (int m = 0; m < 4; ++m) _Pragma("unroll") for (int n = 0; n < 2; ++n) _Pragma("unroll") for (int k = 0; k < 2; ++k) \
;         acc[ai][bj][m][n] = __builtin_amdgcn_mfma_f32_16x16x32_bf16(Bt[n][k], At[m][k], acc[ai][bj][m][n], 0, 0, 0); __builtin_amdgcn_s_setprio(0); } while (0)
; #define PG8_WAIT_V(n) asm volatile("s_waitcnt vmcnt(" #n ")" ::: "memory")
; #define PG8_WAIT_L(n) asm volatile("s_waitcnt lgkmcnt(" #n ")" ::: "memory")
; #define PG8_BAR __builtin_amdgcn_s_barrier()
; #define PG8_SCHED __builtin_amdgcn_sched_barrier(0)
; template <bool HM = false, bool PERM = false, bool CP = false, class Prob, class Epi>
; __device__ __forceinline__ void gemm_phase(LAS unsigned char* lds, const Prob& S, const Epi& E) {
;     ...
;             const bool last = (t == nt - 2);
;             const char* a1 = cA + (size_t)(t + 1) * kstepA;
;             const char* a2 = last ? nA : cA + (size_t)(t + 2) * kstepA; const char* b2 = last ? nB : cB + (size_t)(t + 2) * kstepB;
;             const char* a3 = a2 + kstepA; const char* b3 = b2 + kstepB; const long h2 = last ? nhB : chB;
;     ...
;             PG8_LDB(B0, 0, 0); PG8_LDB(B1, 0, 1); PG8_SCHED; PG8_LDA(At, 0, 0); PG8_STAGE(PG8_SA(1, 1), a1 + hstepA, voffA);
;             PG8_WAIT_V(8); PG8_WAIT_L(0); PG8_BAR; if (!CP || fullu) PG8_MMA(0, 0, At, B0); PG8_MMA(0, 1, At, B1); PG8_BAR; PG8_SCHED;
;             if (!HM) PG8_LDA(At, 0, 1); PG8_STAGE(PG8_SB(0, 0), b2, voffB); PG8_STAGE(PG8_SB(0, 1), b2 + h2, voffB); PG8_STAGE(PG8_SA(0, 0), a2, voffA);
.LBB0_696:
	s_add_u32 s4, s0, 0x100
	s_addc_u32 s5, s1, 0
	s_cmp_eq_u32 s31, 8
	s_cselect_b32 s17, s55, s5
	s_cselect_b32 s16, s54, s4
	s_cselect_b32 s9, s67, s19
	s_cselect_b32 s8, s66, s18
	s_add_i32 s33, 0, 0x10000
	v_add_u32_e32 v0, s33, v144
	s_add_i32 s56, 0, 0x14000
	ds_read_b128 v[146:149], v0
	ds_read_b128 v[150:153], v0 offset:1024
	ds_read_b128 v[154:157], v0 offset:2048
	ds_read_b128 v[158:161], v0 offset:3072
	v_add_u32_e32 v0, s56, v144
	ds_read_b128 v[162:165], v0
	ds_read_b128 v[166:169], v0 offset:1024
	ds_read_b128 v[170:173], v0 offset:2048
	ds_read_b128 v[174:177], v0 offset:3072
	v_lshl_add_u64 v[210:211], s[0:1], 0, v[138:139]
	s_add_i32 m0, s36, 0xc000
	ds_read_b128 v[178:181], v145
	ds_read_b128 v[182:185], v145 offset:1024
	ds_read_b128 v[186:189], v145 offset:2048
	ds_read_b128 v[190:193], v145 offset:3072
	ds_read_b128 v[194:197], v145 offset:4096
	ds_read_b128 v[198:201], v145 offset:5120
	ds_read_b128 v[202:205], v145 offset:6144
	ds_read_b128 v[206:209], v145 offset:7168
	global_load_lds_dwordx4 v[210:211], off
	v_lshl_add_u64 v[210:211], s[0:1], 0, v[140:141]
	s_add_i32 m0, s36, 0xe000
	s_nop 0
	global_load_lds_dwordx4 v[210:211], off
	s_waitcnt vmcnt(8)
	s_waitcnt lgkmcnt(0)
	s_barrier
	s_waitcnt lgkmcnt(0)
	v_mfma_f32_16x16x32_bf16 v[126:129], v[146:149], v[178:181], v[126:129]
	v_mfma_f32_16x16x32_bf16 v[122:125], v[154:157], v[178:181], v[122:125]
	v_mfma_f32_16x16x32_bf16 v[110:113], v[146:149], v[186:189], v[110:113]
	v_mfma_f32_16x16x32_bf16 v[106:109], v[154:157], v[186:189], v[106:109]
	v_mfma_f32_16x16x32_bf16 v[94:97], v[146:149], v[194:197], v[94:97]
	v_mfma_f32_16x16x32_bf16 v[90:93], v[154:157], v[194:197], v[90:93]
	v_mfma_f32_16x16x32_bf16 v[78:81], v[146:149], v[202:205], v[78:81]
	v_mfma_f32_16x16x32_bf16 v[74:77], v[154:157], v[202:205], v[74:77]
	v_mfma_f32_16x16x32_bf16 v[126:129], v[150:153], v[182:185], v[126:129]
	v_mfma_f32_16x16x32_bf16 v[122:125], v[158:161], v[182:185], v[122:125]
	v_mfma_f32_16x16x32_bf16 v[110:113], v[150:153], v[190:193], v[110:113]
	v_mfma_f32_16x16x32_bf16 v[106:109], v[158:161], v[190:193], v[106:109]
	v_mfma_f32_16x16x32_bf16 v[94:97], v[150:153], v[198:201], v[94:97]
	v_mfma_f32_16x16x32_bf16 v[90:93], v[158:161], v[198:201], v[90:93]
	v_mfma_f32_16x16x32_bf16 v[78:81], v[150:153], v[206:209], v[78:81]
	v_mfma_f32_16x16x32_bf16 v[74:77], v[158:161], v[206:209], v[74:77]
	v_mfma_f32_16x16x32_bf16 v[118:121], v[162:165], v[178:181], v[118:121]
	v_mfma_f32_16x16x32_bf16 v[114:117], v[170:173], v[178:181], v[114:117]
	v_mfma_f32_16x16x32_bf16 v[102:105], v[162:165], v[186:189], v[102:105]
	v_mfma_f32_16x16x32_bf16 v[98:101], v[170:173], v[186:189], v[98:101]
	v_mfma_f32_16x16x32_bf16 v[86:89], v[162:165], v[194:197], v[86:89]
	v_mfma_f32_16x16x32_bf16 v[82:85], v[170:173], v[194:197], v[82:85]
	v_mfma_f32_16x16x32_bf16 v[70:73], v[162:165], v[202:205], v[70:73]
	v_mfma_f32_16x16x32_bf16 v[66:69], v[170:173], v[202:205], v[66:69]
	v_mfma_f32_16x16x32_bf16 v[118:121], v[166:169], v[182:185], v[118:121]
	v_mfma_f32_16x16x32_bf16 v[114:117], v[174:177], v[182:185], v[114:117]
	v_mfma_f32_16x16x32_bf16 v[102:105], v[166:169], v[190:193], v[102:105]
	v_mfma_f32_16x16x32_bf16 v[98:101], v[174:177], v[190:193], v[98:101]
	v_mfma_f32_16x16x32_bf16 v[86:89], v[166:169], v[198:201], v[86:89]
	v_mfma_f32_16x16x32_bf16 v[82:85], v[174:177], v[198:201], v[82:85]
	v_mfma_f32_16x16x32_bf16 v[70:73], v[166:169], v[206:209], v[70:73]
	v_mfma_f32_16x16x32_bf16 v[66:69], v[174:177], v[206:209], v[66:69]
	s_barrier
	s_add_i32 s0, s33, s35
	v_lshl_add_u64 v[210:211], s[8:9], 0, v[132:133]
	s_mov_b32 m0, s0
	ds_read_b128 v[178:181], v145 offset:16384
	ds_read_b128 v[182:185], v145 offset:17408
	ds_read_b128 v[186:189], v145 offset:18432
	ds_read_b128 v[190:193], v145 offset:19456
	ds_read_b128 v[194:197], v145 offset:20480
	ds_read_b128 v[198:201], v145 offset:21504
	ds_read_b128 v[202:205], v145 offset:22528
	ds_read_b128 v[206:209], v145 offset:23552
	global_load_lds_dwordx4 v[210:211], off
	s_add_i32 m0, s0, 0x2000
	s_add_u32 s0, s8, 0x30000
	v_lshl_add_u64 v[212:213], s[8:9], 0, v[136:137]
	s_addc_u32 s1, s9, 0
	s_add_i32 s33, s56, s35
	global_load_lds_dwordx4 v[212:213], off
	v_lshl_add_u64 v[214:215], s[0:1], 0, v[132:133]
	s_mov_b32 m0, s33
	v_lshl_add_u64 v[230:231], s[16:17], 0, v[134:135]
	global_load_lds_dwordx4 v[214:215], off
	v_lshl_add_u64 v[214:215], s[0:1], 0, v[136:137]
	s_add_i32 m0, s33, 0x2000
	s_nop 0
	global_load_lds_dwordx4 v[214:215], off
	v_lshl_add_u64 v[214:215], s[16:17], 0, v[130:131]
	s_mov_b32 m0, s36
	s_nop 0
	global_load_lds_dwordx4 v[214:215], off
	s_mov_b32 m0, s37
	s_nop 0
	global_load_lds_dwordx4 v[230:231], off
	s_waitcnt vmcnt(8)
	s_waitcnt lgkmcnt(0)
	s_barrier
; #define PG8_STAGE(bufoff, gbase, voff) do { _Pragma("unroll") for (int _i = 0; _i < 2; ++_i) \
;         __builtin_amdgcn_global_load_lds((const unsigned*)((const char*)(gbase) + (voff)[_i]), (LAS unsigned*)(lds + (bufoff) + ldsw + _i * 8192), 16, 0, 0); } while (0)
; #define PG8_LDA(dst, b, h) do { _Pragma("unroll") for (int m = 0; m < 4; ++m) _Pragma("unroll") for (int k = 0; k < 2; ++k) dst[m][k] = *(const LAS bf16x8*)(lds + PG8_SA(b, h) + aoff + m * 2048 + k * 1024); } while (0)
; #define PG8_LDB(dst, b, h) do { _Pragma("unroll") for (int n = 0; n < 2; ++n) _Pragma("unroll") for (int k = 0; k < 2; ++k) dst[n][k] = *(const LAS bf16x8*)(lds + PG8_SB(b, h) + boff + n * 2048 + k * 1024); } while (0)
; #define PG8_MMA(ai, bj, At, Bt) do { __builtin_amdgcn_s_setprio(1); _Pragma("unroll") for (int m = 0; m < 4; ++m) _Pragma("unroll") for (int n = 0; n < 2; ++n) _Pragma("unroll") for (int k = 0; k < 2; ++k) \
;         acc[ai][bj][m][n] = __builtin_amdgcn_mfma_f32_16x16x32_bf16(Bt[n][k], At[m][k], acc[ai][bj][m][n], 0, 0, 0); __builtin_amdgcn_s_setprio(0); } while (0)
; #define PG8_WAIT_V(n) asm volatile("s_waitcnt vmcnt(" #n ")" ::: "memory")
; #define PG8_WAIT_L(n) asm volatile("s_waitcnt lgkmcnt(" #n ")" ::: "memory")
; #define PG8_BAR __builtin_amdgcn_s_barrier()
; #define PG8_SCHED __builtin_amdgcn_sched_barrier(0)
; template <bool HM = false, bool PERM = false, bool CP = false, class Prob, class Epi>
; __device__ __forceinline__ void gemm_phase(LAS unsigned char* lds, const Prob& S, const Epi& E) {
;     ...
;             PG8_WAIT_V(8); PG8_WAIT_L(0); PG8_BAR; if (!HM) { if (!CP || fullu) PG8_MMA(1, 0, At, B0); PG8_MMA(1, 1, At, B1); } PG8_BAR; PG8_SCHED;
;             PG8_LDB(B0, 1, 0); PG8_LDB(B1, 1, 1); PG8_SCHED; PG8_LDA(At, 1, 0); PG8_STAGE(PG8_SA(0, 1), a2 + hstepA, voffA);
;             PG8_WAIT_V(8); PG8_WAIT_L(0); PG8_BAR; if (!CP || fullu) PG8_MMA(0, 0, At, B0); PG8_MMA(0, 1, At, B1); PG8_BAR; PG8_SCHED;
	s_waitcnt lgkmcnt(0)
	v_mfma_f32_16x16x32_bf16 v[62:65], v[146:149], v[178:181], v[62:65]
	v_mfma_f32_16x16x32_bf16 v[58:61], v[154:157], v[178:181], v[58:61]
	v_mfma_f32_16x16x32_bf16 v[46:49], v[146:149], v[186:189], v[46:49]
	v_mfma_f32_16x16x32_bf16 v[42:45], v[154:157], v[186:189], v[42:45]
	v_mfma_f32_16x16x32_bf16 v[30:33], v[146:149], v[194:197], v[30:33]
	v_mfma_f32_16x16x32_bf16 v[26:29], v[154:157], v[194:197], v[26:29]
	v_mfma_f32_16x16x32_bf16 v[14:17], v[146:149], v[202:205], v[14:17]
	v_mfma_f32_16x16x32_bf16 v[10:13], v[154:157], v[202:205], v[10:13]
	v_mfma_f32_16x16x32_bf16 v[62:65], v[150:153], v[182:185], v[62:65]
	v_mfma_f32_16x16x32_bf16 v[58:61], v[158:161], v[182:185], v[58:61]
	v_mfma_f32_16x16x32_bf16 v[46:49], v[150:153], v[190:193], v[46:49]
	v_mfma_f32_16x16x32_bf16 v[42:45], v[158:161], v[190:193], v[42:45]
	v_mfma_f32_16x16x32_bf16 v[30:33], v[150:153], v[198:201], v[30:33]
	v_mfma_f32_16x16x32_bf16 v[26:29], v[158:161], v[198:201], v[26:29]
	v_mfma_f32_16x16x32_bf16 v[14:17], v[150:153], v[206:209], v[14:17]
	v_mfma_f32_16x16x32_bf16 v[10:13], v[158:161], v[206:209], v[10:13]
	v_mfma_f32_16x16x32_bf16 v[54:57], v[162:165], v[178:181], v[54:57]
	v_mfma_f32_16x16x32_bf16 v[50:53], v[170:173], v[178:181], v[50:53]
	v_mfma_f32_16x16x32_bf16 v[38:41], v[162:165], v[186:189], v[38:41]
	v_mfma_f32_16x16x32_bf16 v[34:37], v[170:173], v[186:189], v[34:37]
	v_mfma_f32_16x16x32_bf16 v[22:25], v[162:165], v[194:197], v[22:25]
	v_mfma_f32_16x16x32_bf16 v[18:21], v[170:173], v[194:197], v[18:21]
	v_mfma_f32_16x16x32_bf16 v[6:9], v[162:165], v[202:205], v[6:9]
	v_mfma_f32_16x16x32_bf16 v[2:5], v[170:173], v[202:205], v[2:5]
	v_mfma_f32_16x16x32_bf16 v[54:57], v[166:169], v[182:185], v[54:57]
	v_mfma_f32_16x16x32_bf16 v[50:53], v[174:177], v[182:185], v[50:53]
	v_mfma_f32_16x16x32_bf16 v[38:41], v[166:169], v[190:193], v[38:41]
	v_mfma_f32_16x16x32_bf16 v[34:37], v[174:177], v[190:193], v[34:37]
	v_mfma_f32_16x16x32_bf16 v[22:25], v[166:169], v[198:201], v[22:25]
	v_mfma_f32_16x16x32_bf16 v[18:21], v[174:177], v[198:201], v[18:21]
	v_mfma_f32_16x16x32_bf16 v[6:9], v[166:169], v[206:209], v[6:9]
	v_mfma_f32_16x16x32_bf16 v[2:5], v[174:177], v[206:209], v[2:5]
	s_barrier
	s_add_i32 s33, 0, 0x18000
	v_add_u32_e32 v0, s33, v144
	s_add_i32 s56, 0, 0x1c000
	ds_read_b128 v[146:149], v0
	ds_read_b128 v[150:153], v0 offset:1024
	ds_read_b128 v[154:157], v0 offset:2048
	ds_read_b128 v[158:161], v0 offset:3072
	v_add_u32_e32 v0, s56, v144
	ds_read_b128 v[162:165], v0
	ds_read_b128 v[166:169], v0 offset:1024
	ds_read_b128 v[170:173], v0 offset:2048
	ds_read_b128 v[174:177], v0 offset:3072
	s_add_u32 s0, s16, 0x30000
	s_addc_u32 s1, s17, 0
	s_mov_b32 m0, s38
	v_lshl_add_u64 v[232:233], s[0:1], 0, v[130:131]
	ds_read_b128 v[178:181], v145 offset:32768
	ds_read_b128 v[182:185], v145 offset:33792
	ds_read_b128 v[186:189], v145 offset:34816
	ds_read_b128 v[190:193], v145 offset:35840
	ds_read_b128 v[194:197], v145 offset:36864
	ds_read_b128 v[198:201], v145 offset:37888
	ds_read_b128 v[202:205], v145 offset:38912
	ds_read_b128 v[206:209], v145 offset:39936
	global_load_lds_dwordx4 v[232:233], off
	v_lshl_add_u64 v[232:233], s[0:1], 0, v[134:135]
	s_mov_b32 m0, s39
	s_nop 0
	global_load_lds_dwordx4 v[232:233], off
	s_waitcnt vmcnt(8)
	s_waitcnt lgkmcnt(0)
	s_barrier
	s_waitcnt lgkmcnt(0)
	v_mfma_f32_16x16x32_bf16 v[126:129], v[146:149], v[178:181], v[126:129]
	v_mfma_f32_16x16x32_bf16 v[122:125], v[154:157], v[178:181], v[122:125]
	v_mfma_f32_16x16x32_bf16 v[110:113], v[146:149], v[186:189], v[110:113]
	v_mfma_f32_16x16x32_bf16 v[106:109], v[154:157], v[186:189], v[106:109]
	v_mfma_f32_16x16x32_bf16 v[94:97], v[146:149], v[194:197], v[94:97]
	v_mfma_f32_16x16x32_bf16 v[90:93], v[154:157], v[194:197], v[90:93]
	v_mfma_f32_16x16x32_bf16 v[78:81], v[146:149], v[202:205], v[78:81]
	v_mfma_f32_16x16x32_bf16 v[74:77], v[154:157], v[202:205], v[74:77]
	v_mfma_f32_16x16x32_bf16 v[126:129], v[150:153], v[182:185], v[126:129]
	v_mfma_f32_16x16x32_bf16 v[122:125], v[158:161], v[182:185], v[122:125]
	v_mfma_f32_16x16x32_bf16 v[110:113], v[150:153], v[190:193], v[110:113]
	v_mfma_f32_16x16x32_bf16 v[106:109], v[158:161], v[190:193], v[106:109]
	v_mfma_f32_16x16x32_bf16 v[94:97], v[150:153], v[198:201], v[94:97]
	v_mfma_f32_16x16x32_bf16 v[90:93], v[158:161], v[198:201], v[90:93]
	v_mfma_f32_16x16x32_bf16 v[78:81], v[150:153], v[206:209], v[78:81]
	v_mfma_f32_16x16x32_bf16 v[74:77], v[158:161], v[206:209], v[74:77]
	v_mfma_f32_16x16x32_bf16 v[118:121], v[162:165], v[178:181], v[118:121]
	v_mfma_f32_16x16x32_bf16 v[114:117], v[170:173], v[178:181], v[114:117]
	v_mfma_f32_16x16x32_bf16 v[102:105], v[162:165], v[186:189], v[102:105]
	v_mfma_f32_16x16x32_bf16 v[98:101], v[170:173], v[186:189], v[98:101]
	v_mfma_f32_16x16x32_bf16 v[86:89], v[162:165], v[194:197], v[86:89]
	v_mfma_f32_16x16x32_bf16 v[82:85], v[170:173], v[194:197], v[82:85]
	v_mfma_f32_16x16x32_bf16 v[70:73], v[162:165], v[202:205], v[70:73]
	v_mfma_f32_16x16x32_bf16 v[66:69], v[170:173], v[202:205], v[66:69]
	v_mfma_f32_16x16x32_bf16 v[118:121], v[166:169], v[182:185], v[118:121]
	v_mfma_f32_16x16x32_bf16 v[114:117], v[174:177], v[182:185], v[114:117]
	v_mfma_f32_16x16x32_bf16 v[102:105], v[166:169], v[190:193], v[102:105]
	v_mfma_f32_16x16x32_bf16 v[98:101], v[174:177], v[190:193], v[98:101]
	v_mfma_f32_16x16x32_bf16 v[86:89], v[166:169], v[198:201], v[86:89]
	v_mfma_f32_16x16x32_bf16 v[82:85], v[174:177], v[198:201], v[82:85]
	v_mfma_f32_16x16x32_bf16 v[70:73], v[166:169], v[206:209], v[70:73]
	v_mfma_f32_16x16x32_bf16 v[66:69], v[174:177], v[206:209], v[66:69]
	s_barrier
; #define PG8_STAGE(bufoff, gbase, voff) do { _Pragma("unroll") for (int _i = 0; _i < 2; ++_i) \
;         __builtin_amdgcn_global_load_lds((const unsigned*)((const char*)(gbase) + (voff)[_i]), (LAS unsigned*)(lds + (bufoff) + ldsw + _i * 8192), 16, 0, 0); } while (0)
; #define PG8_LDA(dst, b, h) do { _Pragma("unroll") for (int m = 0; m < 4; ++m) _Pragma("unroll") for (int k = 0; k < 2; ++k) dst[m][k] = *(const LAS bf16x8*)(lds + PG8_SA(b, h) + aoff + m * 2048 + k * 1024); } while (0)
; #define PG8_MMA(ai, bj, At, Bt) do { __builtin_amdgcn_s_setprio(1); _Pragma("unroll") for (int m = 0; m < 4; ++m) _Pragma("unroll") for (int n = 0; n < 2; ++n) _Pragma("unroll") for (int k = 0; k < 2; ++k) \
;         acc[ai][bj][m][n] = __builtin_amdgcn_mfma_f32_16x16x32_bf16(Bt[n][k], At[m][k], acc[ai][bj][m][n], 0, 0, 0); __builtin_amdgcn_s_setprio(0); } while (0)
; #define PG8_WAIT_V(n) asm volatile("s_waitcnt vmcnt(" #n ")" ::: "memory")
; #define PG8_WAIT_L(n) asm volatile("s_waitcnt lgkmcnt(" #n ")" ::: "memory")
; #define PG8_BAR __builtin_amdgcn_s_barrier()
; #define PG8_SCHED __builtin_amdgcn_sched_barrier(0)
; template <bool HM = false, bool PERM = false, bool CP = false, class Prob, class Epi>
; __device__ __forceinline__ void gemm_phase(LAS unsigned char* lds, const Prob& S, const Epi& E) {
;     ...
;         for (int t = 0; t < nt; t += 2) {
;     ...
;             if (!HM) PG8_LDA(At, 1, 1); PG8_STAGE(PG8_SB(1, 0), b3, voffB); PG8_STAGE(PG8_SB(1, 1), b3 + h2, voffB); PG8_STAGE(PG8_SA(1, 0), a3, voffA);
;             PG8_WAIT_V(8); PG8_WAIT_L(0); PG8_BAR; if (!HM) { if (!CP || fullu) PG8_MMA(1, 0, At, B0); PG8_MMA(1, 1, At, B1); } PG8_BAR; PG8_SCHED;
	s_add_i32 s0, s33, s35
	v_lshl_add_u64 v[210:211], v[210:211], 0, s[20:21]
	s_mov_b32 m0, s0
	ds_read_b128 v[178:181], v145 offset:49152
	ds_read_b128 v[182:185], v145 offset:50176
	ds_read_b128 v[186:189], v145 offset:51200
	ds_read_b128 v[190:193], v145 offset:52224
	ds_read_b128 v[194:197], v145 offset:53248
	ds_read_b128 v[198:201], v145 offset:54272
	ds_read_b128 v[202:205], v145 offset:55296
	ds_read_b128 v[206:209], v145 offset:56320
	global_load_lds_dwordx4 v[210:211], off
	s_add_i32 m0, s0, 0x2000
	s_add_u32 s0, s8, 0x30080
	v_lshl_add_u64 v[210:211], v[212:213], 0, s[20:21]
	s_addc_u32 s1, s9, 0
	s_add_i32 s8, s56, s35
	global_load_lds_dwordx4 v[210:211], off
	v_lshl_add_u64 v[210:211], s[0:1], 0, v[132:133]
	s_mov_b32 m0, s8
	s_nop 0
	global_load_lds_dwordx4 v[210:211], off
	v_lshl_add_u64 v[210:211], s[0:1], 0, v[136:137]
	s_add_i32 m0, s8, 0x2000
	s_nop 0
	global_load_lds_dwordx4 v[210:211], off
	v_lshl_add_u64 v[210:211], v[214:215], 0, s[20:21]
	s_mov_b32 m0, s58
	s_nop 0
	global_load_lds_dwordx4 v[210:211], off
	v_lshl_add_u64 v[210:211], v[230:231], 0, s[20:21]
	s_mov_b32 m0, s59
	s_nop 0
	global_load_lds_dwordx4 v[210:211], off
	s_waitcnt vmcnt(8)
	s_waitcnt lgkmcnt(0)
	s_barrier
	s_waitcnt lgkmcnt(0)
	v_mfma_f32_16x16x32_bf16 v[62:65], v[146:149], v[178:181], v[62:65]
	v_mfma_f32_16x16x32_bf16 v[58:61], v[154:157], v[178:181], v[58:61]
	v_mfma_f32_16x16x32_bf16 v[46:49], v[146:149], v[186:189], v[46:49]
	v_mfma_f32_16x16x32_bf16 v[42:45], v[154:157], v[186:189], v[42:45]
	v_mfma_f32_16x16x32_bf16 v[30:33], v[146:149], v[194:197], v[30:33]
	v_mfma_f32_16x16x32_bf16 v[26:29], v[154:157], v[194:197], v[26:29]
	v_mfma_f32_16x16x32_bf16 v[14:17], v[146:149], v[202:205], v[14:17]
	v_mfma_f32_16x16x32_bf16 v[10:13], v[154:157], v[202:205], v[10:13]
	v_mfma_f32_16x16x32_bf16 v[62:65], v[150:153], v[182:185], v[62:65]
	v_mfma_f32_16x16x32_bf16 v[58:61], v[158:161], v[182:185], v[58:61]
	v_mfma_f32_16x16x32_bf16 v[46:49], v[150:153], v[190:193], v[46:49]
	v_mfma_f32_16x16x32_bf16 v[42:45], v[158:161], v[190:193], v[42:45]
	v_mfma_f32_16x16x32_bf16 v[30:33], v[150:153], v[198:201], v[30:33]
	v_mfma_f32_16x16x32_bf16 v[26:29], v[158:161], v[198:201], v[26:29]
	v_mfma_f32_16x16x32_bf16 v[14:17], v[150:153], v[206:209], v[14:17]
	v_mfma_f32_16x16x32_bf16 v[10:13], v[158:161], v[206:209], v[10:13]
	v_mfma_f32_16x16x32_bf16 v[54:57], v[162:165], v[178:181], v[54:57]
	v_mfma_f32_16x16x32_bf16 v[50:53], v[170:173], v[178:181], v[50:53]
	v_mfma_f32_16x16x32_bf16 v[38:41], v[162:165], v[186:189], v[38:41]
	v_mfma_f32_16x16x32_bf16 v[34:37], v[170:173], v[186:189], v[34:37]
	v_mfma_f32_16x16x32_bf16 v[22:25], v[162:165], v[194:197], v[22:25]
	v_mfma_f32_16x16x32_bf16 v[18:21], v[170:173], v[194:197], v[18:21]
	v_mfma_f32_16x16x32_bf16 v[6:9], v[162:165], v[202:205], v[6:9]
	v_mfma_f32_16x16x32_bf16 v[2:5], v[170:173], v[202:205], v[2:5]
	v_mfma_f32_16x16x32_bf16 v[54:57], v[166:169], v[182:185], v[54:57]
	v_mfma_f32_16x16x32_bf16 v[50:53], v[174:177], v[182:185], v[50:53]
	v_mfma_f32_16x16x32_bf16 v[38:41], v[166:169], v[190:193], v[38:41]
	v_mfma_f32_16x16x32_bf16 v[34:37], v[174:177], v[190:193], v[34:37]
	v_mfma_f32_16x16x32_bf16 v[22:25], v[166:169], v[198:201], v[22:25]
	v_mfma_f32_16x16x32_bf16 v[18:21], v[174:177], v[198:201], v[18:21]
	v_mfma_f32_16x16x32_bf16 v[6:9], v[166:169], v[206:209], v[6:9]
	v_mfma_f32_16x16x32_bf16 v[2:5], v[174:177], v[206:209], v[2:5]
	s_barrier
	s_add_i32 s31, s31, 2
	s_add_u32 s18, s18, 0x100
	s_addc_u32 s19, s19, 0
	s_cmp_gt_u32 s31, 9
	s_mov_b64 s[0:1], s[4:5]
	s_cbranch_scc0 .LBB0_696
	s_and_b64 vcc, exec, s[52:53]
	s_cbranch_vccz .LBB0_699
	s_barrier

; #define PG8_STAGE(bufoff, gbase, voff) do { _Pragma("unroll") for (int _i = 0; _i < 2; ++_i) \
;         __builtin_amdgcn_global_load_lds((const unsigned*)((const char*)(gbase) + (voff)[_i]), (LAS unsigned*)(lds + (bufoff) + ldsw + _i * 8192), 16, 0, 0); } while (0)
; #define PG8_LDA(dst, b, h) do { _Pragma("unroll") for (int m = 0; m < 4; ++m) _Pragma("unroll") for (int k = 0; k < 2; ++k) dst[m][k] = *(const LAS bf16x8*)(lds + PG8_SA(b, h) + aoff + m * 2048 + k * 1024); } while (0)
; #define PG8_LDB(dst, b, h) do { _Pragma("unroll") for (int n = 0; n < 2; ++n) _Pragma("unroll") for (int k = 0; k < 2; ++k) dst[n][k] = *(const LAS bf16x8*)(lds + PG8_SB(b, h) + boff + n * 2048 + k * 1024); } while (0)
; #define PG8_MMA(ai, bj, At, Bt) do { __builtin_amdgcn_s_setprio(1); _Pragma("unroll") for (int m = 0; m < 4; ++m) _Pragma("unroll") for (int n = 0; n < 2; ++n) _Pragma("unroll") for (int k = 0; k < 2; ++k) \
;         acc[ai][bj][m][n] = __builtin_amdgcn_mfma_f32_16x16x32_bf16(Bt[n][k], At[m][k], acc[ai][bj][m][n], 0, 0, 0); __builtin_amdgcn_s_setprio(0); } while (0)
; #define PG8_WAIT_V(n) asm volatile("s_waitcnt vmcnt(" #n ")" ::: "memory")
; #define PG8_WAIT_L(n) asm volatile("s_waitcnt lgkmcnt(" #n ")" ::: "memory")
; #define PG8_BAR __builtin_amdgcn_s_barrier()
; #define PG8_SCHED __builtin_amdgcn_sched_barrier(0)
; template <bool HM = false, bool PERM = false, bool CP = false, class Prob, class Epi>
; __device__ __forceinline__ void gemm_phase(LAS unsigned char* lds, const Prob& S, const Epi& E) {
;     ...
;             const bool last = (t == nt - 2);
;             const char* a1 = cA + (size_t)(t + 1) * kstepA;
;             const char* a2 = last ? nA : cA + (size_t)(t + 2) * kstepA; const char* b2 = last ? nB : cB + (size_t)(t + 2) * kstepB;
;             const char* a3 = a2 + kstepA; const char* b3 = b2 + kstepB; const long h2 = last ? nhB : chB;
;     ...
;             PG8_LDB(B0, 0, 0); PG8_LDB(B1, 0, 1); PG8_SCHED; PG8_LDA(At, 0, 0); PG8_STAGE(PG8_SA(1, 1), a1 + hstepA, voffA);
;             PG8_WAIT_V(8); PG8_WAIT_L(0); PG8_BAR; if (!CP || fullu) PG8_MMA(0, 0, At, B0); PG8_MMA(0, 1, At, B1); PG8_BAR; PG8_SCHED;
;             if (!HM) PG8_LDA(At, 0, 1); PG8_STAGE(PG8_SB(0, 0), b2, voffB); PG8_STAGE(PG8_SB(0, 1), b2 + h2, voffB); PG8_STAGE(PG8_SA(0, 0), a2, voffA);
.LBB0_728:
	s_add_u32 s24, s0, 0xfffc0080
	s_addc_u32 s25, s1, -1
	s_cmp_eq_u32 s66, 12
	s_cselect_b32 s35, s41, s25
	s_cselect_b32 s34, s62, s24
	s_cselect_b32 s25, s39, s65
	s_cselect_b32 s24, s63, s64
	s_add_i32 s67, 0, 0x10000
	s_add_i32 s70, 0, 0x14000
	v_add_u32_e32 v156, s67, v142
	v_add_u32_e32 v172, s70, v142
	ds_read_b128 v[144:147], v156
	ds_read_b128 v[148:151], v156 offset:1024
	ds_read_b128 v[152:155], v156 offset:2048
	ds_read_b128 v[156:159], v156 offset:3072
	ds_read_b128 v[160:163], v172
	ds_read_b128 v[164:167], v172 offset:1024
	ds_read_b128 v[168:171], v172 offset:2048
	ds_read_b128 v[172:175], v172 offset:3072
	v_lshl_add_u64 v[208:209], s[0:1], 0, v[136:137]
	s_add_i32 m0, s53, 0xc000
	ds_read_b128 v[176:179], v143
	ds_read_b128 v[180:183], v143 offset:1024
	ds_read_b128 v[184:187], v143 offset:2048
	ds_read_b128 v[188:191], v143 offset:3072
	ds_read_b128 v[192:195], v143 offset:4096
	ds_read_b128 v[196:199], v143 offset:5120
	ds_read_b128 v[200:203], v143 offset:6144
	ds_read_b128 v[204:207], v143 offset:7168
	global_load_lds_dwordx4 v[208:209], off
	v_lshl_add_u64 v[208:209], s[0:1], 0, v[138:139]
	s_add_i32 m0, s53, 0xe000
	s_nop 0
	global_load_lds_dwordx4 v[208:209], off
	s_waitcnt vmcnt(8)
	s_waitcnt lgkmcnt(0)
	s_barrier
	s_waitcnt lgkmcnt(0)
	v_mfma_f32_16x16x32_bf16 v[126:129], v[144:147], v[176:179], v[126:129]
	v_mfma_f32_16x16x32_bf16 v[122:125], v[152:155], v[176:179], v[122:125]
	v_mfma_f32_16x16x32_bf16 v[110:113], v[144:147], v[184:187], v[110:113]
	v_mfma_f32_16x16x32_bf16 v[106:109], v[152:155], v[184:187], v[106:109]
	v_mfma_f32_16x16x32_bf16 v[94:97], v[144:147], v[192:195], v[94:97]
	v_mfma_f32_16x16x32_bf16 v[90:93], v[152:155], v[192:195], v[90:93]
	v_mfma_f32_16x16x32_bf16 v[78:81], v[144:147], v[200:203], v[78:81]
	v_mfma_f32_16x16x32_bf16 v[74:77], v[152:155], v[200:203], v[74:77]
	v_mfma_f32_16x16x32_bf16 v[126:129], v[148:151], v[180:183], v[126:129]
	v_mfma_f32_16x16x32_bf16 v[122:125], v[156:159], v[180:183], v[122:125]
	v_mfma_f32_16x16x32_bf16 v[110:113], v[148:151], v[188:191], v[110:113]
	v_mfma_f32_16x16x32_bf16 v[106:109], v[156:159], v[188:191], v[106:109]
	v_mfma_f32_16x16x32_bf16 v[94:97], v[148:151], v[196:199], v[94:97]
	v_mfma_f32_16x16x32_bf16 v[90:93], v[156:159], v[196:199], v[90:93]
	v_mfma_f32_16x16x32_bf16 v[78:81], v[148:151], v[204:207], v[78:81]
	v_mfma_f32_16x16x32_bf16 v[74:77], v[156:159], v[204:207], v[74:77]
	v_mfma_f32_16x16x32_bf16 v[118:121], v[160:163], v[176:179], v[118:121]
	v_mfma_f32_16x16x32_bf16 v[114:117], v[168:171], v[176:179], v[114:117]
	v_mfma_f32_16x16x32_bf16 v[102:105], v[160:163], v[184:187], v[102:105]
	v_mfma_f32_16x16x32_bf16 v[98:101], v[168:171], v[184:187], v[98:101]
	v_mfma_f32_16x16x32_bf16 v[86:89], v[160:163], v[192:195], v[86:89]
	v_mfma_f32_16x16x32_bf16 v[82:85], v[168:171], v[192:195], v[82:85]
	v_mfma_f32_16x16x32_bf16 v[70:73], v[160:163], v[200:203], v[70:73]
	v_mfma_f32_16x16x32_bf16 v[66:69], v[168:171], v[200:203], v[66:69]
	v_mfma_f32_16x16x32_bf16 v[118:121], v[164:167], v[180:183], v[118:121]
	v_mfma_f32_16x16x32_bf16 v[114:117], v[172:175], v[180:183], v[114:117]
	v_mfma_f32_16x16x32_bf16 v[102:105], v[164:167], v[188:191], v[102:105]
	v_mfma_f32_16x16x32_bf16 v[98:101], v[172:175], v[188:191], v[98:101]
	v_mfma_f32_16x16x32_bf16 v[86:89], v[164:167], v[196:199], v[86:89]
	v_mfma_f32_16x16x32_bf16 v[82:85], v[172:175], v[196:199], v[82:85]
	v_mfma_f32_16x16x32_bf16 v[70:73], v[164:167], v[204:207], v[70:73]
	v_mfma_f32_16x16x32_bf16 v[66:69], v[172:175], v[204:207], v[66:69]
	s_barrier
	s_add_i32 s67, s67, s48
	v_lshl_add_u64 v[208:209], s[24:25], 0, v[0:1]
	s_mov_b32 m0, s67
	ds_read_b128 v[176:179], v143 offset:16384
	ds_read_b128 v[180:183], v143 offset:17408
	ds_read_b128 v[184:187], v143 offset:18432
	ds_read_b128 v[188:191], v143 offset:19456
	ds_read_b128 v[192:195], v143 offset:20480
	ds_read_b128 v[196:199], v143 offset:21504
	ds_read_b128 v[200:203], v143 offset:22528
	ds_read_b128 v[204:207], v143 offset:23552
	global_load_lds_dwordx4 v[208:209], off
	s_add_i32 m0, s67, 0x2000
	s_add_u32 s68, s24, 0x40000
	v_lshl_add_u64 v[210:211], s[24:25], 0, v[130:131]
	s_addc_u32 s69, s25, 0
	s_add_i32 s67, s70, s48
	global_load_lds_dwordx4 v[210:211], off
	v_lshl_add_u64 v[212:213], s[68:69], 0, v[0:1]
	s_mov_b32 m0, s67
	v_lshl_add_u64 v[214:215], s[34:35], 0, v[132:133]
	global_load_lds_dwordx4 v[212:213], off
	v_lshl_add_u64 v[212:213], s[68:69], 0, v[130:131]
	s_add_i32 m0, s67, 0x2000
	s_nop 0
	global_load_lds_dwordx4 v[212:213], off
	v_lshl_add_u64 v[212:213], s[34:35], 0, v[134:135]
	s_mov_b32 m0, s53
	s_nop 0
	global_load_lds_dwordx4 v[212:213], off
	s_mov_b32 m0, s9
	s_nop 0
	global_load_lds_dwordx4 v[214:215], off
	s_waitcnt vmcnt(8)
	s_waitcnt lgkmcnt(0)
	s_barrier
; #define PG8_STAGE(bufoff, gbase, voff) do { _Pragma("unroll") for (int _i = 0; _i < 2; ++_i) \
;         __builtin_amdgcn_global_load_lds((const unsigned*)((const char*)(gbase) + (voff)[_i]), (LAS unsigned*)(lds + (bufoff) + ldsw + _i * 8192), 16, 0, 0); } while (0)
; #define PG8_LDA(dst, b, h) do { _Pragma("unroll") for (int m = 0; m < 4; ++m) _Pragma("unroll") for (int k = 0; k < 2; ++k) dst[m][k] = *(const LAS bf16x8*)(lds + PG8_SA(b, h) + aoff + m * 2048 + k * 1024); } while (0)
; #define PG8_LDB(dst, b, h) do { _Pragma("unroll") for (int n = 0; n < 2; ++n) _Pragma("unroll") for (int k = 0; k < 2; ++k) dst[n][k] = *(const LAS bf16x8*)(lds + PG8_SB(b, h) + boff + n * 2048 + k * 1024); } while (0)
; #define PG8_MMA(ai, bj, At, Bt) do { __builtin_amdgcn_s_setprio(1); _Pragma("unroll") for (int m = 0; m < 4; ++m) _Pragma("unroll") for (int n = 0; n < 2; ++n) _Pragma("unroll") for (int k = 0; k < 2; ++k) \
;         acc[ai][bj][m][n] = __builtin_amdgcn_mfma_f32_16x16x32_bf16(Bt[n][k], At[m][k], acc[ai][bj][m][n], 0, 0, 0); __builtin_amdgcn_s_setprio(0); } while (0)
; #define PG8_WAIT_V(n) asm volatile("s_waitcnt vmcnt(" #n ")" ::: "memory")
; #define PG8_WAIT_L(n) asm volatile("s_waitcnt lgkmcnt(" #n ")" ::: "memory")
; #define PG8_BAR __builtin_amdgcn_s_barrier()
; #define PG8_SCHED __builtin_amdgcn_sched_barrier(0)
; template <bool HM = false, bool PERM = false, bool CP = false, class Prob, class Epi>
; __device__ __forceinline__ void gemm_phase(LAS unsigned char* lds, const Prob& S, const Epi& E) {
;     ...
;             PG8_WAIT_V(8); PG8_WAIT_L(0); PG8_BAR; if (!HM) { if (!CP || fullu) PG8_MMA(1, 0, At, B0); PG8_MMA(1, 1, At, B1); } PG8_BAR; PG8_SCHED;
;             PG8_LDB(B0, 1, 0); PG8_LDB(B1, 1, 1); PG8_SCHED; PG8_LDA(At, 1, 0); PG8_STAGE(PG8_SA(0, 1), a2 + hstepA, voffA);
;             PG8_WAIT_V(8); PG8_WAIT_L(0); PG8_BAR; if (!CP || fullu) PG8_MMA(0, 0, At, B0); PG8_MMA(0, 1, At, B1); PG8_BAR; PG8_SCHED;
	s_waitcnt lgkmcnt(0)
	v_mfma_f32_16x16x32_bf16 v[62:65], v[144:147], v[176:179], v[62:65]
	v_mfma_f32_16x16x32_bf16 v[58:61], v[152:155], v[176:179], v[58:61]
	v_mfma_f32_16x16x32_bf16 v[46:49], v[144:147], v[184:187], v[46:49]
	v_mfma_f32_16x16x32_bf16 v[42:45], v[152:155], v[184:187], v[42:45]
	v_mfma_f32_16x16x32_bf16 v[30:33], v[144:147], v[192:195], v[30:33]
	v_mfma_f32_16x16x32_bf16 v[26:29], v[152:155], v[192:195], v[26:29]
	v_mfma_f32_16x16x32_bf16 v[14:17], v[144:147], v[200:203], v[14:17]
	v_mfma_f32_16x16x32_bf16 v[10:13], v[152:155], v[200:203], v[10:13]
	v_mfma_f32_16x16x32_bf16 v[62:65], v[148:151], v[180:183], v[62:65]
	v_mfma_f32_16x16x32_bf16 v[58:61], v[156:159], v[180:183], v[58:61]
	v_mfma_f32_16x16x32_bf16 v[46:49], v[148:151], v[188:191], v[46:49]
	v_mfma_f32_16x16x32_bf16 v[42:45], v[156:159], v[188:191], v[42:45]
	v_mfma_f32_16x16x32_bf16 v[30:33], v[148:151], v[196:199], v[30:33]
	v_mfma_f32_16x16x32_bf16 v[26:29], v[156:159], v[196:199], v[26:29]
	v_mfma_f32_16x16x32_bf16 v[14:17], v[148:151], v[204:207], v[14:17]
	v_mfma_f32_16x16x32_bf16 v[10:13], v[156:159], v[204:207], v[10:13]
	v_mfma_f32_16x16x32_bf16 v[54:57], v[160:163], v[176:179], v[54:57]
	v_mfma_f32_16x16x32_bf16 v[50:53], v[168:171], v[176:179], v[50:53]
	v_mfma_f32_16x16x32_bf16 v[38:41], v[160:163], v[184:187], v[38:41]
	v_mfma_f32_16x16x32_bf16 v[34:37], v[168:171], v[184:187], v[34:37]
	v_mfma_f32_16x16x32_bf16 v[22:25], v[160:163], v[192:195], v[22:25]
	v_mfma_f32_16x16x32_bf16 v[18:21], v[168:171], v[192:195], v[18:21]
	v_mfma_f32_16x16x32_bf16 v[6:9], v[160:163], v[200:203], v[6:9]
	v_mfma_f32_16x16x32_bf16 v[2:5], v[168:171], v[200:203], v[2:5]
	v_mfma_f32_16x16x32_bf16 v[54:57], v[164:167], v[180:183], v[54:57]
	v_mfma_f32_16x16x32_bf16 v[50:53], v[172:175], v[180:183], v[50:53]
	v_mfma_f32_16x16x32_bf16 v[38:41], v[164:167], v[188:191], v[38:41]
	v_mfma_f32_16x16x32_bf16 v[34:37], v[172:175], v[188:191], v[34:37]
	v_mfma_f32_16x16x32_bf16 v[22:25], v[164:167], v[196:199], v[22:25]
	v_mfma_f32_16x16x32_bf16 v[18:21], v[172:175], v[196:199], v[18:21]
	v_mfma_f32_16x16x32_bf16 v[6:9], v[164:167], v[204:207], v[6:9]
	v_mfma_f32_16x16x32_bf16 v[2:5], v[172:175], v[204:207], v[2:5]
	s_barrier
	s_add_i32 s67, 0, 0x18000
	s_add_i32 s68, 0, 0x1c000
	v_add_u32_e32 v156, s67, v142
	v_add_u32_e32 v172, s68, v142
	ds_read_b128 v[144:147], v156
	ds_read_b128 v[148:151], v156 offset:1024
	ds_read_b128 v[152:155], v156 offset:2048
	ds_read_b128 v[156:159], v156 offset:3072
	ds_read_b128 v[160:163], v172
	ds_read_b128 v[164:167], v172 offset:1024
	ds_read_b128 v[168:171], v172 offset:2048
	ds_read_b128 v[172:175], v172 offset:3072
	s_add_u32 s34, s34, 0x40000
	s_addc_u32 s35, s35, 0
	s_mov_b32 m0, s54
	v_lshl_add_u64 v[230:231], s[34:35], 0, v[134:135]
	ds_read_b128 v[176:179], v143 offset:32768
	ds_read_b128 v[180:183], v143 offset:33792
	ds_read_b128 v[184:187], v143 offset:34816
	ds_read_b128 v[188:191], v143 offset:35840
	ds_read_b128 v[192:195], v143 offset:36864
	ds_read_b128 v[196:199], v143 offset:37888
	ds_read_b128 v[200:203], v143 offset:38912
	ds_read_b128 v[204:207], v143 offset:39936
	global_load_lds_dwordx4 v[230:231], off
	v_lshl_add_u64 v[230:231], s[34:35], 0, v[132:133]
	s_mov_b32 m0, s55
	s_nop 0
	global_load_lds_dwordx4 v[230:231], off
	s_waitcnt vmcnt(8)
	s_waitcnt lgkmcnt(0)
	s_barrier
	s_waitcnt lgkmcnt(0)
	v_mfma_f32_16x16x32_bf16 v[126:129], v[144:147], v[176:179], v[126:129]
	v_mfma_f32_16x16x32_bf16 v[122:125], v[152:155], v[176:179], v[122:125]
	v_mfma_f32_16x16x32_bf16 v[110:113], v[144:147], v[184:187], v[110:113]
	v_mfma_f32_16x16x32_bf16 v[106:109], v[152:155], v[184:187], v[106:109]
	v_mfma_f32_16x16x32_bf16 v[94:97], v[144:147], v[192:195], v[94:97]
	v_mfma_f32_16x16x32_bf16 v[90:93], v[152:155], v[192:195], v[90:93]
	v_mfma_f32_16x16x32_bf16 v[78:81], v[144:147], v[200:203], v[78:81]
	v_mfma_f32_16x16x32_bf16 v[74:77], v[152:155], v[200:203], v[74:77]
	v_mfma_f32_16x16x32_bf16 v[126:129], v[148:151], v[180:183], v[126:129]
	v_mfma_f32_16x16x32_bf16 v[122:125], v[156:159], v[180:183], v[122:125]
	v_mfma_f32_16x16x32_bf16 v[110:113], v[148:151], v[188:191], v[110:113]
	v_mfma_f32_16x16x32_bf16 v[106:109], v[156:159], v[188:191], v[106:109]
	v_mfma_f32_16x16x32_bf16 v[94:97], v[148:151], v[196:199], v[94:97]
	v_mfma_f32_16x16x32_bf16 v[90:93], v[156:159], v[196:199], v[90:93]
	v_mfma_f32_16x16x32_bf16 v[78:81], v[148:151], v[204:207], v[78:81]
	v_mfma_f32_16x16x32_bf16 v[74:77], v[156:159], v[204:207], v[74:77]
	v_mfma_f32_16x16x32_bf16 v[118:121], v[160:163], v[176:179], v[118:121]
	v_mfma_f32_16x16x32_bf16 v[114:117], v[168:171], v[176:179], v[114:117]
	v_mfma_f32_16x16x32_bf16 v[102:105], v[160:163], v[184:187], v[102:105]
	v_mfma_f32_16x16x32_bf16 v[98:101], v[168:171], v[184:187], v[98:101]
	v_mfma_f32_16x16x32_bf16 v[86:89], v[160:163], v[192:195], v[86:89]
	v_mfma_f32_16x16x32_bf16 v[82:85], v[168:171], v[192:195], v[82:85]
	v_mfma_f32_16x16x32_bf16 v[70:73], v[160:163], v[200:203], v[70:73]
	v_mfma_f32_16x16x32_bf16 v[66:69], v[168:171], v[200:203], v[66:69]
	v_mfma_f32_16x16x32_bf16 v[118:121], v[164:167], v[180:183], v[118:121]
	v_mfma_f32_16x16x32_bf16 v[114:117], v[172:175], v[180:183], v[114:117]
	v_mfma_f32_16x16x32_bf16 v[102:105], v[164:167], v[188:191], v[102:105]
	v_mfma_f32_16x16x32_bf16 v[98:101], v[172:175], v[188:191], v[98:101]
	v_mfma_f32_16x16x32_bf16 v[86:89], v[164:167], v[196:199], v[86:89]
	v_mfma_f32_16x16x32_bf16 v[82:85], v[172:175], v[196:199], v[82:85]
	v_mfma_f32_16x16x32_bf16 v[70:73], v[164:167], v[204:207], v[70:73]
	v_mfma_f32_16x16x32_bf16 v[66:69], v[172:175], v[204:207], v[66:69]
	s_barrier
; #define PG8_STAGE(bufoff, gbase, voff) do { _Pragma("unroll") for (int _i = 0; _i < 2; ++_i) \
;         __builtin_amdgcn_global_load_lds((const unsigned*)((const char*)(gbase) + (voff)[_i]), (LAS unsigned*)(lds + (bufoff) + ldsw + _i * 8192), 16, 0, 0); } while (0)
; #define PG8_LDA(dst, b, h) do { _Pragma("unroll") for (int m = 0; m < 4; ++m) _Pragma("unroll") for (int k = 0; k < 2; ++k) dst[m][k] = *(const LAS bf16x8*)(lds + PG8_SA(b, h) + aoff + m * 2048 + k * 1024); } while (0)
; #define PG8_MMA(ai, bj, At, Bt) do { __builtin_amdgcn_s_setprio(1); _Pragma("unroll") for (int m = 0; m < 4; ++m) _Pragma("unroll") for (int n = 0; n < 2; ++n) _Pragma("unroll") for (int k = 0; k < 2; ++k) \
;         acc[ai][bj][m][n] = __builtin_amdgcn_mfma_f32_16x16x32_bf16(Bt[n][k], At[m][k], acc[ai][bj][m][n], 0, 0, 0); __builtin_amdgcn_s_setprio(0); } while (0)
; #define PG8_WAIT_V(n) asm volatile("s_waitcnt vmcnt(" #n ")" ::: "memory")
; #define PG8_WAIT_L(n) asm volatile("s_waitcnt lgkmcnt(" #n ")" ::: "memory")
; #define PG8_BAR __builtin_amdgcn_s_barrier()
; #define PG8_SCHED __builtin_amdgcn_sched_barrier(0)
; template <bool HM = false, bool PERM = false, bool CP = false, class Prob, class Epi>
; __device__ __forceinline__ void gemm_phase(LAS unsigned char* lds, const Prob& S, const Epi& E) {
;     ...
;         for (int t = 0; t < nt; t += 2) {
;     ...
;             if (!HM) PG8_LDA(At, 1, 1); PG8_STAGE(PG8_SB(1, 0), b3, voffB); PG8_STAGE(PG8_SB(1, 1), b3 + h2, voffB); PG8_STAGE(PG8_SA(1, 0), a3, voffA);
;             PG8_WAIT_V(8); PG8_WAIT_L(0); PG8_BAR; if (!HM) { if (!CP || fullu) PG8_MMA(1, 0, At, B0); PG8_MMA(1, 1, At, B1); } PG8_BAR; PG8_SCHED;
	s_add_i32 s34, s67, s48
	v_lshl_add_u64 v[208:209], v[208:209], 0, s[20:21]
	s_mov_b32 m0, s34
	ds_read_b128 v[176:179], v143 offset:49152
	ds_read_b128 v[180:183], v143 offset:50176
	ds_read_b128 v[184:187], v143 offset:51200
	ds_read_b128 v[188:191], v143 offset:52224
	ds_read_b128 v[192:195], v143 offset:53248
	ds_read_b128 v[196:199], v143 offset:54272
	ds_read_b128 v[200:203], v143 offset:55296
	ds_read_b128 v[204:207], v143 offset:56320
	global_load_lds_dwordx4 v[208:209], off
	s_add_i32 m0, s34, 0x2000
	s_add_u32 s24, s24, 0x40080
	v_lshl_add_u64 v[208:209], v[210:211], 0, s[20:21]
	s_addc_u32 s25, s25, 0
	s_add_i32 s34, s68, s48
	global_load_lds_dwordx4 v[208:209], off
	v_lshl_add_u64 v[208:209], s[24:25], 0, v[0:1]
	s_mov_b32 m0, s34
	s_nop 0
	global_load_lds_dwordx4 v[208:209], off
	v_lshl_add_u64 v[208:209], s[24:25], 0, v[130:131]
	s_add_i32 m0, s34, 0x2000
	s_nop 0
	global_load_lds_dwordx4 v[208:209], off
	v_lshl_add_u64 v[208:209], v[212:213], 0, s[20:21]
	s_mov_b32 m0, s58
	s_nop 0
	global_load_lds_dwordx4 v[208:209], off
	v_lshl_add_u64 v[208:209], v[214:215], 0, s[20:21]
	s_mov_b32 m0, s59
	s_nop 0
	global_load_lds_dwordx4 v[208:209], off
	s_waitcnt vmcnt(8)
	s_waitcnt lgkmcnt(0)
	s_barrier
	s_waitcnt lgkmcnt(0)
	v_mfma_f32_16x16x32_bf16 v[62:65], v[144:147], v[176:179], v[62:65]
	v_mfma_f32_16x16x32_bf16 v[58:61], v[152:155], v[176:179], v[58:61]
	v_mfma_f32_16x16x32_bf16 v[46:49], v[144:147], v[184:187], v[46:49]
	v_mfma_f32_16x16x32_bf16 v[42:45], v[152:155], v[184:187], v[42:45]
	v_mfma_f32_16x16x32_bf16 v[30:33], v[144:147], v[192:195], v[30:33]
	v_mfma_f32_16x16x32_bf16 v[26:29], v[152:155], v[192:195], v[26:29]
	v_mfma_f32_16x16x32_bf16 v[14:17], v[144:147], v[200:203], v[14:17]
	v_mfma_f32_16x16x32_bf16 v[10:13], v[152:155], v[200:203], v[10:13]
	v_mfma_f32_16x16x32_bf16 v[62:65], v[148:151], v[180:183], v[62:65]
	v_mfma_f32_16x16x32_bf16 v[58:61], v[156:159], v[180:183], v[58:61]
	v_mfma_f32_16x16x32_bf16 v[46:49], v[148:151], v[188:191], v[46:49]
	v_mfma_f32_16x16x32_bf16 v[42:45], v[156:159], v[188:191], v[42:45]
	v_mfma_f32_16x16x32_bf16 v[30:33], v[148:151], v[196:199], v[30:33]
	v_mfma_f32_16x16x32_bf16 v[26:29], v[156:159], v[196:199], v[26:29]
	v_mfma_f32_16x16x32_bf16 v[14:17], v[148:151], v[204:207], v[14:17]
	v_mfma_f32_16x16x32_bf16 v[10:13], v[156:159], v[204:207], v[10:13]
	v_mfma_f32_16x16x32_bf16 v[54:57], v[160:163], v[176:179], v[54:57]
	v_mfma_f32_16x16x32_bf16 v[50:53], v[168:171], v[176:179], v[50:53]
	v_mfma_f32_16x16x32_bf16 v[38:41], v[160:163], v[184:187], v[38:41]
	v_mfma_f32_16x16x32_bf16 v[34:37], v[168:171], v[184:187], v[34:37]
	v_mfma_f32_16x16x32_bf16 v[22:25], v[160:163], v[192:195], v[22:25]
	v_mfma_f32_16x16x32_bf16 v[18:21], v[168:171], v[192:195], v[18:21]
	v_mfma_f32_16x16x32_bf16 v[6:9], v[160:163], v[200:203], v[6:9]
	v_mfma_f32_16x16x32_bf16 v[2:5], v[168:171], v[200:203], v[2:5]
	v_mfma_f32_16x16x32_bf16 v[54:57], v[164:167], v[180:183], v[54:57]
	v_mfma_f32_16x16x32_bf16 v[50:53], v[172:175], v[180:183], v[50:53]
	v_mfma_f32_16x16x32_bf16 v[38:41], v[164:167], v[188:191], v[38:41]
	v_mfma_f32_16x16x32_bf16 v[34:37], v[172:175], v[188:191], v[34:37]
	v_mfma_f32_16x16x32_bf16 v[22:25], v[164:167], v[196:199], v[22:25]
	v_mfma_f32_16x16x32_bf16 v[18:21], v[172:175], v[196:199], v[18:21]
	v_mfma_f32_16x16x32_bf16 v[6:9], v[164:167], v[204:207], v[6:9]
	v_mfma_f32_16x16x32_bf16 v[2:5], v[172:175], v[204:207], v[2:5]
	s_barrier
	s_add_i32 s66, s66, 2
	s_add_u32 s0, s0, 0x100
	s_addc_u32 s1, s1, 0
	s_add_u32 s64, s64, 0x100
	s_addc_u32 s65, s65, 0
	s_cmp_gt_u32 s66, 13
	s_cbranch_scc0 .LBB0_728
	s_and_b64 vcc, exec, s[22:23]
	s_cbranch_vccz .LBB0_731
	s_barrier

; #define PG8_MMA(ai, bj, At, Bt) do { __builtin_amdgcn_s_setprio(1); _Pragma("unroll") for (int m = 0; m < 4; ++m) _Pragma("unroll") for (int n = 0; n < 2; ++n) _Pragma("unroll") for (int k = 0; k < 2; ++k) \
;         acc[ai][bj][m][n] = __builtin_amdgcn_mfma_f32_16x16x32_bf16(Bt[n][k], At[m][k], acc[ai][bj][m][n], 0, 0, 0); __builtin_amdgcn_s_setprio(0); } while (0)
; #define PG8_WAIT_V(n) asm volatile("s_waitcnt vmcnt(" #n ")" ::: "memory")
; #define PG8_WAIT_L(n) asm volatile("s_waitcnt lgkmcnt(" #n ")" ::: "memory")
; #define PG8_BAR __builtin_amdgcn_s_barrier()
; #define PG8_SCHED __builtin_amdgcn_sched_barrier(0)
; template <bool HM = false, bool PERM = false, bool CP = false, class Prob, class Epi>
; __device__ __forceinline__ void gemm_phase(LAS unsigned char* lds, const Prob& S, const Epi& E) {
;     ...
;         for (int t = 0; t < nt; t += 2) {
;     ...
;             PG8_WAIT_V(8); PG8_WAIT_L(0); PG8_BAR; if (!HM) { if (!CP || fullu) PG8_MMA(1, 0, At, B0); PG8_MMA(1, 1, At, B1); } PG8_BAR; PG8_SCHED;
.LBB0_825:
	s_waitcnt lgkmcnt(0)
	v_mfma_f32_16x16x32_bf16 v[86:89], v[130:133], v[186:189], v[86:89]
	v_mfma_f32_16x16x32_bf16 v[82:85], v[138:141], v[186:189], v[82:85]
	v_mfma_f32_16x16x32_bf16 v[70:73], v[130:133], v[178:181], v[70:73]
	v_mfma_f32_16x16x32_bf16 v[66:69], v[138:141], v[178:181], v[66:69]
	v_mfma_f32_16x16x32_bf16 v[54:57], v[130:133], v[170:173], v[54:57]
	v_mfma_f32_16x16x32_bf16 v[50:53], v[138:141], v[170:173], v[50:53]
	v_mfma_f32_16x16x32_bf16 v[38:41], v[130:133], v[162:165], v[38:41]
	v_mfma_f32_16x16x32_bf16 v[26:29], v[138:141], v[162:165], v[26:29]
	v_mfma_f32_16x16x32_bf16 v[86:89], v[134:137], v[190:193], v[86:89]
	v_mfma_f32_16x16x32_bf16 v[82:85], v[142:145], v[190:193], v[82:85]
	v_mfma_f32_16x16x32_bf16 v[70:73], v[134:137], v[182:185], v[70:73]
	v_mfma_f32_16x16x32_bf16 v[66:69], v[142:145], v[182:185], v[66:69]
	v_mfma_f32_16x16x32_bf16 v[54:57], v[134:137], v[174:177], v[54:57]
	v_mfma_f32_16x16x32_bf16 v[50:53], v[142:145], v[174:177], v[50:53]
	v_mfma_f32_16x16x32_bf16 v[38:41], v[134:137], v[166:169], v[38:41]
	v_mfma_f32_16x16x32_bf16 v[26:29], v[142:145], v[166:169], v[26:29]
	s_barrier
	s_add_i32 s9, s9, 2
	s_add_u32 s34, s34, 0x100
	s_addc_u32 s35, s35, 0
	s_add_u32 s5, s5, 0x100
	s_addc_u32 s6, s6, 0
	s_cmp_gt_u32 s9, 5
	s_cbranch_scc1 .LBB0_842

; #define PG8_STAGE(bufoff, gbase, voff) do { _Pragma("unroll") for (int _i = 0; _i < 2; ++_i) \
;         __builtin_amdgcn_global_load_lds((const unsigned*)((const char*)(gbase) + (voff)[_i]), (LAS unsigned*)(lds + (bufoff) + ldsw + _i * 8192), 16, 0, 0); } while (0)
; #define PG8_LDA(dst, b, h) do { _Pragma("unroll") for (int m = 0; m < 4; ++m) _Pragma("unroll") for (int k = 0; k < 2; ++k) dst[m][k] = *(const LAS bf16x8*)(lds + PG8_SA(b, h) + aoff + m * 2048 + k * 1024); } while (0)
; #define PG8_LDB(dst, b, h) do { _Pragma("unroll") for (int n = 0; n < 2; ++n) _Pragma("unroll") for (int k = 0; k < 2; ++k) dst[n][k] = *(const LAS bf16x8*)(lds + PG8_SB(b, h) + boff + n * 2048 + k * 1024); } while (0)
; #define PG8_MMA(ai, bj, At, Bt) do { __builtin_amdgcn_s_setprio(1); _Pragma("unroll") for (int m = 0; m < 4; ++m) _Pragma("unroll") for (int n = 0; n < 2; ++n) _Pragma("unroll") for (int k = 0; k < 2; ++k) \
;         acc[ai][bj][m][n] = __builtin_amdgcn_mfma_f32_16x16x32_bf16(Bt[n][k], At[m][k], acc[ai][bj][m][n], 0, 0, 0); __builtin_amdgcn_s_setprio(0); } while (0)
; #define PG8_WAIT_V(n) asm volatile("s_waitcnt vmcnt(" #n ")" ::: "memory")
; #define PG8_WAIT_L(n) asm volatile("s_waitcnt lgkmcnt(" #n ")" ::: "memory")
; #define PG8_BAR __builtin_amdgcn_s_barrier()
; #define PG8_SCHED __builtin_amdgcn_sched_barrier(0)
; template <bool HM = false, bool PERM = false, bool CP = false, class Prob, class Epi>
; __device__ __forceinline__ void gemm_phase(LAS unsigned char* lds, const Prob& S, const Epi& E) {
;     ...
;             const bool last = (t == nt - 2);
;             const char* a1 = cA + (size_t)(t + 1) * kstepA;
;             const char* a2 = last ? nA : cA + (size_t)(t + 2) * kstepA; const char* b2 = last ? nB : cB + (size_t)(t + 2) * kstepB;
;             const char* a3 = a2 + kstepA; const char* b3 = b2 + kstepB; const long h2 = last ? nhB : chB;
;     ...
;             PG8_LDB(B0, 0, 0); PG8_LDB(B1, 0, 1); PG8_SCHED; PG8_LDA(At, 0, 0); PG8_STAGE(PG8_SA(1, 1), a1 + hstepA, voffA);
;             PG8_WAIT_V(8); PG8_WAIT_L(0); PG8_BAR; if (!CP || fullu) PG8_MMA(0, 0, At, B0); PG8_MMA(0, 1, At, B1); PG8_BAR; PG8_SCHED;
;             if (!HM) PG8_LDA(At, 0, 1); PG8_STAGE(PG8_SB(0, 0), b2, voffB); PG8_STAGE(PG8_SB(0, 1), b2 + h2, voffB); PG8_STAGE(PG8_SA(0, 0), a2, voffA);
.LBB0_828:
	s_andn2_b64 vcc, exec, s[68:69]
	s_cbranch_vccnz .LBB0_830
	s_waitcnt lgkmcnt(0)
	v_mfma_f32_16x16x32_bf16 v[94:97], v[146:149], v[186:189], v[94:97]
	v_mfma_f32_16x16x32_bf16 v[90:93], v[154:157], v[186:189], v[90:93]
	v_mfma_f32_16x16x32_bf16 v[78:81], v[146:149], v[178:181], v[78:81]
	v_mfma_f32_16x16x32_bf16 v[74:77], v[154:157], v[178:181], v[74:77]
	v_mfma_f32_16x16x32_bf16 v[62:65], v[146:149], v[170:173], v[62:65]
	v_mfma_f32_16x16x32_bf16 v[58:61], v[154:157], v[170:173], v[58:61]
	v_mfma_f32_16x16x32_bf16 v[46:49], v[146:149], v[162:165], v[46:49]
	v_mfma_f32_16x16x32_bf16 v[42:45], v[154:157], v[162:165], v[42:45]
	v_mfma_f32_16x16x32_bf16 v[94:97], v[150:153], v[190:193], v[94:97]
	v_mfma_f32_16x16x32_bf16 v[90:93], v[158:161], v[190:193], v[90:93]
	v_mfma_f32_16x16x32_bf16 v[78:81], v[150:153], v[182:185], v[78:81]
	v_mfma_f32_16x16x32_bf16 v[74:77], v[158:161], v[182:185], v[74:77]
	v_mfma_f32_16x16x32_bf16 v[62:65], v[150:153], v[174:177], v[62:65]
	v_mfma_f32_16x16x32_bf16 v[58:61], v[158:161], v[174:177], v[58:61]
	v_mfma_f32_16x16x32_bf16 v[46:49], v[150:153], v[166:169], v[46:49]
	v_mfma_f32_16x16x32_bf16 v[42:45], v[158:161], v[166:169], v[42:45]
.LBB0_830:
	s_add_u32 s49, s34, 0xfffe0080
	s_addc_u32 vcc_lo, s35, -1
	s_cmp_eq_u32 s9, 4
	s_cselect_b64 s[70:71], -1, 0
	s_and_b64 s[68:69], s[70:71], exec
	s_cselect_b32 s69, s63, vcc_lo
	s_cselect_b32 s68, s62, s49
	s_cselect_b32 vcc_hi, s17, s6
	s_cselect_b32 vcc_lo, s16, s5
	s_and_b64 s[70:71], s[0:1], s[70:71]
	s_and_b64 s[70:71], s[70:71], exec
	s_cselect_b32 s70, s60, s36
	s_cselect_b32 s49, s61, s37
	s_waitcnt lgkmcnt(0)
	v_mfma_f32_16x16x32_bf16 v[126:129], v[130:133], v[186:189], v[126:129]
	v_mfma_f32_16x16x32_bf16 v[122:125], v[138:141], v[186:189], v[122:125]
	v_mfma_f32_16x16x32_bf16 v[118:121], v[130:133], v[178:181], v[118:121]
	v_mfma_f32_16x16x32_bf16 v[114:117], v[138:141], v[178:181], v[114:117]
	v_mfma_f32_16x16x32_bf16 v[110:113], v[130:133], v[170:173], v[110:113]
	v_mfma_f32_16x16x32_bf16 v[106:109], v[138:141], v[170:173], v[106:109]
	v_mfma_f32_16x16x32_bf16 v[102:105], v[130:133], v[162:165], v[102:105]
	v_mfma_f32_16x16x32_bf16 v[98:101], v[138:141], v[162:165], v[98:101]
	v_mfma_f32_16x16x32_bf16 v[126:129], v[134:137], v[190:193], v[126:129]
	v_mfma_f32_16x16x32_bf16 v[122:125], v[142:145], v[190:193], v[122:125]
	v_mfma_f32_16x16x32_bf16 v[118:121], v[134:137], v[182:185], v[118:121]
	v_mfma_f32_16x16x32_bf16 v[114:117], v[142:145], v[182:185], v[114:117]
	v_mfma_f32_16x16x32_bf16 v[110:113], v[134:137], v[174:177], v[110:113]
	v_mfma_f32_16x16x32_bf16 v[106:109], v[142:145], v[174:177], v[106:109]
	v_mfma_f32_16x16x32_bf16 v[102:105], v[134:137], v[166:169], v[102:105]
	v_mfma_f32_16x16x32_bf16 v[98:101], v[142:145], v[166:169], v[98:101]
	s_barrier
	s_mov_b32 m0, s77
	v_lshl_add_u64 v[204:205], vcc, 0, v[0:1]
	s_add_u32 s70, vcc_lo, s70
	ds_read_b128 v[186:189], v232 offset:16384
	ds_read_b128 v[190:193], v232 offset:17408
	ds_read_b128 v[178:181], v232 offset:18432
	ds_read_b128 v[182:185], v232 offset:19456
	ds_read_b128 v[170:173], v232 offset:20480
	ds_read_b128 v[174:177], v232 offset:21504
	ds_read_b128 v[162:165], v232 offset:22528
	ds_read_b128 v[166:169], v232 offset:23552
	global_load_lds_dwordx4 v[204:205], off
	v_lshl_add_u64 v[206:207], vcc, 0, v[198:199]
	s_mov_b32 m0, s78
	s_addc_u32 s71, vcc_hi, s49
	global_load_lds_dwordx4 v[206:207], off
	v_lshl_add_u64 v[208:209], s[70:71], 0, v[0:1]
	s_mov_b32 m0, s79
	v_lshl_add_u64 v[210:211], s[70:71], 0, v[198:199]
	global_load_lds_dwordx4 v[208:209], off
	s_mov_b32 m0, s80
	v_lshl_add_u64 v[212:213], s[68:69], 0, v[194:195]
	global_load_lds_dwordx4 v[210:211], off
	s_mov_b32 m0, s76
	v_lshl_add_u64 v[214:215], s[68:69], 0, v[196:197]
	global_load_lds_dwordx4 v[212:213], off
	s_mov_b32 m0, s81
	s_and_b64 vcc, exec, s[42:43]
	global_load_lds_dwordx4 v[214:215], off
	s_waitcnt vmcnt(8)
	s_waitcnt lgkmcnt(0)
	s_mov_b64 s[70:71], -1
	s_barrier
	s_cbranch_vccnz .LBB0_832
	s_mov_b64 s[70:71], 0
; #define PG8_STAGE(bufoff, gbase, voff) do { _Pragma("unroll") for (int _i = 0; _i < 2; ++_i) \
;         __builtin_amdgcn_global_load_lds((const unsigned*)((const char*)(gbase) + (voff)[_i]), (LAS unsigned*)(lds + (bufoff) + ldsw + _i * 8192), 16, 0, 0); } while (0)
; #define PG8_LDA(dst, b, h) do { _Pragma("unroll") for (int m = 0; m < 4; ++m) _Pragma("unroll") for (int k = 0; k < 2; ++k) dst[m][k] = *(const LAS bf16x8*)(lds + PG8_SA(b, h) + aoff + m * 2048 + k * 1024); } while (0)
; #define PG8_LDB(dst, b, h) do { _Pragma("unroll") for (int n = 0; n < 2; ++n) _Pragma("unroll") for (int k = 0; k < 2; ++k) dst[n][k] = *(const LAS bf16x8*)(lds + PG8_SB(b, h) + boff + n * 2048 + k * 1024); } while (0)
; #define PG8_MMA(ai, bj, At, Bt) do { __builtin_amdgcn_s_setprio(1); _Pragma("unroll") for (int m = 0; m < 4; ++m) _Pragma("unroll") for (int n = 0; n < 2; ++n) _Pragma("unroll") for (int k = 0; k < 2; ++k) \
;         acc[ai][bj][m][n] = __builtin_amdgcn_mfma_f32_16x16x32_bf16(Bt[n][k], At[m][k], acc[ai][bj][m][n], 0, 0, 0); __builtin_amdgcn_s_setprio(0); } while (0)
; #define PG8_WAIT_V(n) asm volatile("s_waitcnt vmcnt(" #n ")" ::: "memory")
; #define PG8_WAIT_L(n) asm volatile("s_waitcnt lgkmcnt(" #n ")" ::: "memory")
; #define PG8_BAR __builtin_amdgcn_s_barrier()
; #define PG8_SCHED __builtin_amdgcn_sched_barrier(0)
; template <bool HM = false, bool PERM = false, bool CP = false, class Prob, class Epi>
; __device__ __forceinline__ void gemm_phase(LAS unsigned char* lds, const Prob& S, const Epi& E) {
;     ...
;             PG8_WAIT_V(8); PG8_WAIT_L(0); PG8_BAR; if (!HM) { if (!CP || fullu) PG8_MMA(1, 0, At, B0); PG8_MMA(1, 1, At, B1); } PG8_BAR; PG8_SCHED;
;             PG8_LDB(B0, 1, 0); PG8_LDB(B1, 1, 1); PG8_SCHED; PG8_LDA(At, 1, 0); PG8_STAGE(PG8_SA(0, 1), a2 + hstepA, voffA);
.LBB0_832:
	s_andn2_b64 vcc, exec, s[70:71]
	s_cbranch_vccnz .LBB0_834
	s_waitcnt lgkmcnt(0)
	v_mfma_f32_16x16x32_bf16 v[34:37], v[146:149], v[186:189], v[34:37]
	v_mfma_f32_16x16x32_bf16 v[30:33], v[154:157], v[186:189], v[30:33]
	v_mfma_f32_16x16x32_bf16 v[22:25], v[146:149], v[178:181], v[22:25]
	v_mfma_f32_16x16x32_bf16 v[18:21], v[154:157], v[178:181], v[18:21]
	v_mfma_f32_16x16x32_bf16 v[14:17], v[146:149], v[170:173], v[14:17]
	v_mfma_f32_16x16x32_bf16 v[10:13], v[154:157], v[170:173], v[10:13]
	v_mfma_f32_16x16x32_bf16 v[6:9], v[146:149], v[162:165], v[6:9]
	v_mfma_f32_16x16x32_bf16 v[2:5], v[154:157], v[162:165], v[2:5]
	v_mfma_f32_16x16x32_bf16 v[34:37], v[150:153], v[190:193], v[34:37]
	v_mfma_f32_16x16x32_bf16 v[30:33], v[158:161], v[190:193], v[30:33]
	v_mfma_f32_16x16x32_bf16 v[22:25], v[150:153], v[182:185], v[22:25]
	v_mfma_f32_16x16x32_bf16 v[18:21], v[158:161], v[182:185], v[18:21]
	v_mfma_f32_16x16x32_bf16 v[14:17], v[150:153], v[174:177], v[14:17]
	v_mfma_f32_16x16x32_bf16 v[10:13], v[158:161], v[174:177], v[10:13]
	v_mfma_f32_16x16x32_bf16 v[6:9], v[150:153], v[166:169], v[6:9]
	v_mfma_f32_16x16x32_bf16 v[2:5], v[158:161], v[166:169], v[2:5]
.LBB0_834:
	s_waitcnt lgkmcnt(0)
	v_mfma_f32_16x16x32_bf16 v[86:89], v[130:133], v[186:189], v[86:89]
	v_mfma_f32_16x16x32_bf16 v[82:85], v[138:141], v[186:189], v[82:85]
	v_mfma_f32_16x16x32_bf16 v[70:73], v[130:133], v[178:181], v[70:73]
	v_mfma_f32_16x16x32_bf16 v[66:69], v[138:141], v[178:181], v[66:69]
	v_mfma_f32_16x16x32_bf16 v[54:57], v[130:133], v[170:173], v[54:57]
	v_mfma_f32_16x16x32_bf16 v[50:53], v[138:141], v[170:173], v[50:53]
	v_mfma_f32_16x16x32_bf16 v[38:41], v[130:133], v[162:165], v[38:41]
	v_mfma_f32_16x16x32_bf16 v[26:29], v[138:141], v[162:165], v[26:29]
	v_mfma_f32_16x16x32_bf16 v[86:89], v[134:137], v[190:193], v[86:89]
	v_mfma_f32_16x16x32_bf16 v[82:85], v[142:145], v[190:193], v[82:85]
	v_mfma_f32_16x16x32_bf16 v[70:73], v[134:137], v[182:185], v[70:73]
	v_mfma_f32_16x16x32_bf16 v[66:69], v[142:145], v[182:185], v[66:69]
	v_mfma_f32_16x16x32_bf16 v[54:57], v[134:137], v[174:177], v[54:57]
	v_mfma_f32_16x16x32_bf16 v[50:53], v[142:145], v[174:177], v[50:53]
	v_mfma_f32_16x16x32_bf16 v[38:41], v[134:137], v[166:169], v[38:41]
	v_mfma_f32_16x16x32_bf16 v[26:29], v[142:145], v[166:169], v[26:29]
	s_barrier
	v_add_u32_e32 v130, 0x18000, v231
	v_add_u32_e32 v142, 0x1c000, v231
	ds_read_b128 v[146:149], v130
	ds_read_b128 v[150:153], v130 offset:1024
	ds_read_b128 v[154:157], v130 offset:2048
	ds_read_b128 v[158:161], v130 offset:3072
	ds_read_b128 v[130:133], v142
	ds_read_b128 v[134:137], v142 offset:1024
	ds_read_b128 v[138:141], v142 offset:2048
	ds_read_b128 v[142:145], v142 offset:3072
	s_add_u32 s68, s68, 0x20000
	s_addc_u32 s69, s69, 0
	s_mov_b32 m0, s82
	v_lshl_add_u64 v[234:235], s[68:69], 0, v[194:195]
	ds_read_b128 v[186:189], v232 offset:32768
	ds_read_b128 v[190:193], v232 offset:33792
	ds_read_b128 v[178:181], v232 offset:34816
	ds_read_b128 v[182:185], v232 offset:35840
	ds_read_b128 v[170:173], v232 offset:36864
	ds_read_b128 v[174:177], v232 offset:37888
	ds_read_b128 v[162:165], v232 offset:38912
	ds_read_b128 v[166:169], v232 offset:39936
	global_load_lds_dwordx4 v[234:235], off
	v_lshl_add_u64 v[234:235], s[68:69], 0, v[196:197]
	s_mov_b32 m0, s83
	s_and_b64 vcc, exec, s[42:43]
	global_load_lds_dwordx4 v[234:235], off
	s_waitcnt vmcnt(8)
	s_waitcnt lgkmcnt(0)
	s_mov_b64 s[68:69], -1
	s_barrier
	s_cbranch_vccnz .LBB0_836
	s_mov_b64 s[68:69], 0

; #define PG8_STAGE(bufoff, gbase, voff) do { _Pragma("unroll") for (int _i = 0; _i < 2; ++_i) \
;         __builtin_amdgcn_global_load_lds((const unsigned*)((const char*)(gbase) + (voff)[_i]), (LAS unsigned*)(lds + (bufoff) + ldsw + _i * 8192), 16, 0, 0); } while (0)
; #define PG8_LDA(dst, b, h) do { _Pragma("unroll") for (int m = 0; m < 4; ++m) _Pragma("unroll") for (int k = 0; k < 2; ++k) dst[m][k] = *(const LAS bf16x8*)(lds + PG8_SA(b, h) + aoff + m * 2048 + k * 1024); } while (0)
; #define PG8_MMA(ai, bj, At, Bt) do { __builtin_amdgcn_s_setprio(1); _Pragma("unroll") for (int m = 0; m < 4; ++m) _Pragma("unroll") for (int n = 0; n < 2; ++n) _Pragma("unroll") for (int k = 0; k < 2; ++k) \
;         acc[ai][bj][m][n] = __builtin_amdgcn_mfma_f32_16x16x32_bf16(Bt[n][k], At[m][k], acc[ai][bj][m][n], 0, 0, 0); __builtin_amdgcn_s_setprio(0); } while (0)
; #define PG8_WAIT_V(n) asm volatile("s_waitcnt vmcnt(" #n ")" ::: "memory")
; #define PG8_WAIT_L(n) asm volatile("s_waitcnt lgkmcnt(" #n ")" ::: "memory")
; #define PG8_BAR __builtin_amdgcn_s_barrier()
; #define PG8_SCHED __builtin_amdgcn_sched_barrier(0)
; template <bool HM = false, bool PERM = false, bool CP = false, class Prob, class Epi>
; __device__ __forceinline__ void gemm_phase(LAS unsigned char* lds, const Prob& S, const Epi& E) {
;     ...
;             PG8_WAIT_V(8); PG8_WAIT_L(0); PG8_BAR; if (!CP || fullu) PG8_MMA(0, 0, At, B0); PG8_MMA(0, 1, At, B1); PG8_BAR; PG8_SCHED;
;             if (!HM) PG8_LDA(At, 1, 1); PG8_STAGE(PG8_SB(1, 0), b3, voffB); PG8_STAGE(PG8_SB(1, 1), b3 + h2, voffB); PG8_STAGE(PG8_SA(1, 0), a3, voffA);
;             PG8_WAIT_V(8); PG8_WAIT_L(0); PG8_BAR; if (!HM) { if (!CP || fullu) PG8_MMA(1, 0, At, B0); PG8_MMA(1, 1, At, B1); } PG8_BAR; PG8_SCHED;
.LBB0_838:
	s_waitcnt lgkmcnt(0)
	v_mfma_f32_16x16x32_bf16 v[126:129], v[130:133], v[186:189], v[126:129]
	v_mfma_f32_16x16x32_bf16 v[122:125], v[138:141], v[186:189], v[122:125]
	v_mfma_f32_16x16x32_bf16 v[118:121], v[130:133], v[178:181], v[118:121]
	v_mfma_f32_16x16x32_bf16 v[114:117], v[138:141], v[178:181], v[114:117]
	v_mfma_f32_16x16x32_bf16 v[110:113], v[130:133], v[170:173], v[110:113]
	v_mfma_f32_16x16x32_bf16 v[106:109], v[138:141], v[170:173], v[106:109]
	v_mfma_f32_16x16x32_bf16 v[102:105], v[130:133], v[162:165], v[102:105]
	v_mfma_f32_16x16x32_bf16 v[98:101], v[138:141], v[162:165], v[98:101]
	v_mfma_f32_16x16x32_bf16 v[126:129], v[134:137], v[190:193], v[126:129]
	v_mfma_f32_16x16x32_bf16 v[122:125], v[142:145], v[190:193], v[122:125]
	v_mfma_f32_16x16x32_bf16 v[118:121], v[134:137], v[182:185], v[118:121]
	v_mfma_f32_16x16x32_bf16 v[114:117], v[142:145], v[182:185], v[114:117]
	v_mfma_f32_16x16x32_bf16 v[110:113], v[134:137], v[174:177], v[110:113]
	v_mfma_f32_16x16x32_bf16 v[106:109], v[142:145], v[174:177], v[106:109]
	v_mfma_f32_16x16x32_bf16 v[102:105], v[134:137], v[166:169], v[102:105]
	v_mfma_f32_16x16x32_bf16 v[98:101], v[142:145], v[166:169], v[98:101]
	s_barrier
	s_mov_b32 m0, s84
	v_lshl_add_u64 v[204:205], v[204:205], 0, s[20:21]
	ds_read_b128 v[186:189], v232 offset:49152
	ds_read_b128 v[190:193], v232 offset:50176
	ds_read_b128 v[178:181], v232 offset:51200
	ds_read_b128 v[182:185], v232 offset:52224
	ds_read_b128 v[170:173], v232 offset:53248
	ds_read_b128 v[174:177], v232 offset:54272
	ds_read_b128 v[162:165], v232 offset:55296
	ds_read_b128 v[166:169], v232 offset:56320
	global_load_lds_dwordx4 v[204:205], off
	v_lshl_add_u64 v[204:205], v[206:207], 0, s[20:21]
	s_mov_b32 m0, s56
	s_and_b64 vcc, exec, s[42:43]
	global_load_lds_dwordx4 v[204:205], off
	v_lshl_add_u64 v[204:205], v[208:209], 0, s[20:21]
	s_mov_b32 m0, s18
	s_mov_b64 s[42:43], -1
	global_load_lds_dwordx4 v[204:205], off
	v_lshl_add_u64 v[204:205], v[210:211], 0, s[20:21]
	s_mov_b32 m0, s19
	s_nop 0
	global_load_lds_dwordx4 v[204:205], off
	v_lshl_add_u64 v[204:205], v[212:213], 0, s[20:21]
	s_mov_b32 m0, s33
	s_nop 0
	global_load_lds_dwordx4 v[204:205], off
	v_lshl_add_u64 v[204:205], v[214:215], 0, s[20:21]
	s_mov_b32 m0, s2
	s_nop 0
	global_load_lds_dwordx4 v[204:205], off
	s_waitcnt vmcnt(8)
	s_waitcnt lgkmcnt(0)
	s_barrier
	s_cbranch_vccnz .LBB0_840
	s_mov_b64 s[42:43], 0
.LBB0_840:
	s_andn2_b64 vcc, exec, s[42:43]
	s_cbranch_vccnz .LBB0_825
	s_waitcnt lgkmcnt(0)
	v_mfma_f32_16x16x32_bf16 v[34:37], v[146:149], v[186:189], v[34:37]
	v_mfma_f32_16x16x32_bf16 v[30:33], v[154:157], v[186:189], v[30:33]
	v_mfma_f32_16x16x32_bf16 v[22:25], v[146:149], v[178:181], v[22:25]
	v_mfma_f32_16x16x32_bf16 v[18:21], v[154:157], v[178:181], v[18:21]
	v_mfma_f32_16x16x32_bf16 v[14:17], v[146:149], v[170:173], v[14:17]
	v_mfma_f32_16x16x32_bf16 v[10:13], v[154:157], v[170:173], v[10:13]
	v_mfma_f32_16x16x32_bf16 v[6:9], v[146:149], v[162:165], v[6:9]
	v_mfma_f32_16x16x32_bf16 v[2:5], v[154:157], v[162:165], v[2:5]
	v_mfma_f32_16x16x32_bf16 v[34:37], v[150:153], v[190:193], v[34:37]
	v_mfma_f32_16x16x32_bf16 v[30:33], v[158:161], v[190:193], v[30:33]
	v_mfma_f32_16x16x32_bf16 v[22:25], v[150:153], v[182:185], v[22:25]
	v_mfma_f32_16x16x32_bf16 v[18:21], v[158:161], v[182:185], v[18:21]
	v_mfma_f32_16x16x32_bf16 v[14:17], v[150:153], v[174:177], v[14:17]
	v_mfma_f32_16x16x32_bf16 v[10:13], v[158:161], v[174:177], v[10:13]
	v_mfma_f32_16x16x32_bf16 v[6:9], v[150:153], v[166:169], v[6:9]
	v_mfma_f32_16x16x32_bf16 v[2:5], v[158:161], v[166:169], v[2:5]
	s_branch .LBB0_825

; #define PG8_STAGE(bufoff, gbase, voff) do { _Pragma("unroll") for (int _i = 0; _i < 2; ++_i) \
;         __builtin_amdgcn_global_load_lds((const unsigned*)((const char*)(gbase) + (voff)[_i]), (LAS unsigned*)(lds + (bufoff) + ldsw + _i * 8192), 16, 0, 0); } while (0)
; #define PG8_LDA(dst, b, h) do { _Pragma("unroll") for (int m = 0; m < 4; ++m) _Pragma("unroll") for (int k = 0; k < 2; ++k) dst[m][k] = *(const LAS bf16x8*)(lds + PG8_SA(b, h) + aoff + m * 2048 + k * 1024); } while (0)
; #define PG8_LDB(dst, b, h) do { _Pragma("unroll") for (int n = 0; n < 2; ++n) _Pragma("unroll") for (int k = 0; k < 2; ++k) dst[n][k] = *(const LAS bf16x8*)(lds + PG8_SB(b, h) + boff + n * 2048 + k * 1024); } while (0)
; #define PG8_MMA(ai, bj, At, Bt) do { __builtin_amdgcn_s_setprio(1); _Pragma("unroll") for (int m = 0; m < 4; ++m) _Pragma("unroll") for (int n = 0; n < 2; ++n) _Pragma("unroll") for (int k = 0; k < 2; ++k) \
;         acc[ai][bj][m][n] = __builtin_amdgcn_mfma_f32_16x16x32_bf16(Bt[n][k], At[m][k], acc[ai][bj][m][n], 0, 0, 0); __builtin_amdgcn_s_setprio(0); } while (0)
; #define PG8_WAIT_V(n) asm volatile("s_waitcnt vmcnt(" #n ")" ::: "memory")
; #define PG8_WAIT_L(n) asm volatile("s_waitcnt lgkmcnt(" #n ")" ::: "memory")
; #define PG8_BAR __builtin_amdgcn_s_barrier()
; #define PG8_SCHED __builtin_amdgcn_sched_barrier(0)
; template <bool HM = false, bool PERM = false, bool CP = false, class Prob, class Epi>
; __device__ __forceinline__ void gemm_phase(LAS unsigned char* lds, const Prob& S, const Epi& E) {
;     ...
;             const bool last = (t == nt - 2);
;             const char* a1 = cA + (size_t)(t + 1) * kstepA;
;             const char* a2 = last ? nA : cA + (size_t)(t + 2) * kstepA; const char* b2 = last ? nB : cB + (size_t)(t + 2) * kstepB;
;             const char* a3 = a2 + kstepA; const char* b3 = b2 + kstepB; const long h2 = last ? nhB : chB;
;     ...
;             PG8_LDB(B0, 0, 0); PG8_LDB(B1, 0, 1); PG8_SCHED; PG8_LDA(At, 0, 0); PG8_STAGE(PG8_SA(1, 1), a1 + hstepA, voffA);
;             PG8_WAIT_V(8); PG8_WAIT_L(0); PG8_BAR; if (!CP || fullu) PG8_MMA(0, 0, At, B0); PG8_MMA(0, 1, At, B1); PG8_BAR; PG8_SCHED;
;             if (!HM) PG8_LDA(At, 0, 1); PG8_STAGE(PG8_SB(0, 0), b2, voffB); PG8_STAGE(PG8_SB(0, 1), b2 + h2, voffB); PG8_STAGE(PG8_SA(0, 0), a2, voffA);
.LBB0_1001:
	s_add_i32 s77, s34, 2
	s_add_u32 s24, s8, 0xfffc0080
	s_addc_u32 s25, s9, -1
	s_cmp_eq_u32 s39, s34
	s_cselect_b32 s35, s17, s25
	s_cselect_b32 s34, s16, s24
	s_cselect_b32 s25, s37, s76
	s_cselect_b32 s24, s36, s45
	s_add_i32 s78, 0, 0x10000
	v_add_u32_e32 v140, s78, v144
	s_add_i32 s80, 0, 0x14000
	ds_read_b128 v[136:139], v140
	ds_read_b128 v[146:149], v140 offset:1024
	ds_read_b128 v[150:153], v140 offset:2048
	ds_read_b128 v[154:157], v140 offset:3072
	v_add_u32_e32 v140, s80, v144
	ds_read_b128 v[158:161], v140
	ds_read_b128 v[162:165], v140 offset:1024
	ds_read_b128 v[166:169], v140 offset:2048
	ds_read_b128 v[170:173], v140 offset:3072
	v_lshl_add_u64 v[140:141], s[8:9], 0, v[132:133]
	s_add_i32 m0, s65, 0xc000
	ds_read_b128 v[174:177], v145
	ds_read_b128 v[178:181], v145 offset:1024
	ds_read_b128 v[182:185], v145 offset:2048
	ds_read_b128 v[186:189], v145 offset:3072
	ds_read_b128 v[190:193], v145 offset:4096
	ds_read_b128 v[194:197], v145 offset:5120
	ds_read_b128 v[198:201], v145 offset:6144
	ds_read_b128 v[202:205], v145 offset:7168
	global_load_lds_dwordx4 v[140:141], off
	v_lshl_add_u64 v[140:141], s[8:9], 0, v[134:135]
	s_add_i32 m0, s65, 0xe000
	s_nop 0
	global_load_lds_dwordx4 v[140:141], off
	s_waitcnt vmcnt(8)
	s_waitcnt lgkmcnt(0)
	s_barrier
	s_waitcnt lgkmcnt(0)
	v_mfma_f32_16x16x32_bf16 v[126:129], v[136:139], v[174:177], v[126:129]
	v_mfma_f32_16x16x32_bf16 v[122:125], v[150:153], v[174:177], v[122:125]
	v_mfma_f32_16x16x32_bf16 v[110:113], v[136:139], v[182:185], v[110:113]
	v_mfma_f32_16x16x32_bf16 v[106:109], v[150:153], v[182:185], v[106:109]
	v_mfma_f32_16x16x32_bf16 v[94:97], v[136:139], v[190:193], v[94:97]
	v_mfma_f32_16x16x32_bf16 v[90:93], v[150:153], v[190:193], v[90:93]
	v_mfma_f32_16x16x32_bf16 v[78:81], v[136:139], v[198:201], v[78:81]
	v_mfma_f32_16x16x32_bf16 v[74:77], v[150:153], v[198:201], v[74:77]
	v_mfma_f32_16x16x32_bf16 v[126:129], v[146:149], v[178:181], v[126:129]
	v_mfma_f32_16x16x32_bf16 v[122:125], v[154:157], v[178:181], v[122:125]
	v_mfma_f32_16x16x32_bf16 v[110:113], v[146:149], v[186:189], v[110:113]
	v_mfma_f32_16x16x32_bf16 v[106:109], v[154:157], v[186:189], v[106:109]
	v_mfma_f32_16x16x32_bf16 v[94:97], v[146:149], v[194:197], v[94:97]
	v_mfma_f32_16x16x32_bf16 v[90:93], v[154:157], v[194:197], v[90:93]
	v_mfma_f32_16x16x32_bf16 v[78:81], v[146:149], v[202:205], v[78:81]
	v_mfma_f32_16x16x32_bf16 v[74:77], v[154:157], v[202:205], v[74:77]
	v_mfma_f32_16x16x32_bf16 v[118:121], v[158:161], v[174:177], v[118:121]
	v_mfma_f32_16x16x32_bf16 v[114:117], v[166:169], v[174:177], v[114:117]
	v_mfma_f32_16x16x32_bf16 v[102:105], v[158:161], v[182:185], v[102:105]
	v_mfma_f32_16x16x32_bf16 v[98:101], v[166:169], v[182:185], v[98:101]
	v_mfma_f32_16x16x32_bf16 v[86:89], v[158:161], v[190:193], v[86:89]
	v_mfma_f32_16x16x32_bf16 v[82:85], v[166:169], v[190:193], v[82:85]
	v_mfma_f32_16x16x32_bf16 v[70:73], v[158:161], v[198:201], v[70:73]
	v_mfma_f32_16x16x32_bf16 v[66:69], v[166:169], v[198:201], v[66:69]
	v_mfma_f32_16x16x32_bf16 v[118:121], v[162:165], v[178:181], v[118:121]
	v_mfma_f32_16x16x32_bf16 v[114:117], v[170:173], v[178:181], v[114:117]
	v_mfma_f32_16x16x32_bf16 v[102:105], v[162:165], v[186:189], v[102:105]
	v_mfma_f32_16x16x32_bf16 v[98:101], v[170:173], v[186:189], v[98:101]
	v_mfma_f32_16x16x32_bf16 v[86:89], v[162:165], v[194:197], v[86:89]
	v_mfma_f32_16x16x32_bf16 v[82:85], v[170:173], v[194:197], v[82:85]
	v_mfma_f32_16x16x32_bf16 v[70:73], v[162:165], v[202:205], v[70:73]
	v_mfma_f32_16x16x32_bf16 v[66:69], v[170:173], v[202:205], v[66:69]
	s_barrier
	s_add_i32 s78, s78, s63
	v_lshl_add_u64 v[140:141], s[24:25], 0, v[0:1]
	s_mov_b32 m0, s78
	ds_read_b128 v[174:177], v145 offset:16384
	ds_read_b128 v[178:181], v145 offset:17408
	ds_read_b128 v[182:185], v145 offset:18432
	ds_read_b128 v[186:189], v145 offset:19456
	ds_read_b128 v[190:193], v145 offset:20480
	ds_read_b128 v[194:197], v145 offset:21504
	ds_read_b128 v[198:201], v145 offset:22528
	ds_read_b128 v[202:205], v145 offset:23552
	global_load_lds_dwordx4 v[140:141], off
	s_add_i32 m0, s78, 0x2000
	s_add_u32 s78, s24, 0x40000
	v_lshl_add_u64 v[206:207], s[24:25], 0, v[130:131]
	s_addc_u32 s79, s25, 0
	s_add_i32 s80, s80, s63
	global_load_lds_dwordx4 v[206:207], off
	v_lshl_add_u64 v[208:209], s[78:79], 0, v[0:1]
	s_mov_b32 m0, s80
	v_lshl_add_u64 v[210:211], s[34:35], 0, v[130:131]
	global_load_lds_dwordx4 v[208:209], off
	v_lshl_add_u64 v[208:209], s[78:79], 0, v[130:131]
	s_add_i32 m0, s80, 0x2000
	s_nop 0
	global_load_lds_dwordx4 v[208:209], off
	v_lshl_add_u64 v[208:209], s[34:35], 0, v[0:1]
	s_mov_b32 m0, s65
	s_nop 0
	global_load_lds_dwordx4 v[208:209], off
	s_mov_b32 m0, s66
	s_nop 0
	global_load_lds_dwordx4 v[210:211], off
	s_waitcnt vmcnt(8)
	s_waitcnt lgkmcnt(0)
	s_barrier
; #define PG8_STAGE(bufoff, gbase, voff) do { _Pragma("unroll") for (int _i = 0; _i < 2; ++_i) \
;         __builtin_amdgcn_global_load_lds((const unsigned*)((const char*)(gbase) + (voff)[_i]), (LAS unsigned*)(lds + (bufoff) + ldsw + _i * 8192), 16, 0, 0); } while (0)
; #define PG8_LDA(dst, b, h) do { _Pragma("unroll") for (int m = 0; m < 4; ++m) _Pragma("unroll") for (int k = 0; k < 2; ++k) dst[m][k] = *(const LAS bf16x8*)(lds + PG8_SA(b, h) + aoff + m * 2048 + k * 1024); } while (0)
; #define PG8_LDB(dst, b, h) do { _Pragma("unroll") for (int n = 0; n < 2; ++n) _Pragma("unroll") for (int k = 0; k < 2; ++k) dst[n][k] = *(const LAS bf16x8*)(lds + PG8_SB(b, h) + boff + n * 2048 + k * 1024); } while (0)
; #define PG8_MMA(ai, bj, At, Bt) do { __builtin_amdgcn_s_setprio(1); _Pragma("unroll") for (int m = 0; m < 4; ++m) _Pragma("unroll") for (int n = 0; n < 2; ++n) _Pragma("unroll") for (int k = 0; k < 2; ++k) \
;         acc[ai][bj][m][n] = __builtin_amdgcn_mfma_f32_16x16x32_bf16(Bt[n][k], At[m][k], acc[ai][bj][m][n], 0, 0, 0); __builtin_amdgcn_s_setprio(0); } while (0)
; #define PG8_WAIT_V(n) asm volatile("s_waitcnt vmcnt(" #n ")" ::: "memory")
; #define PG8_WAIT_L(n) asm volatile("s_waitcnt lgkmcnt(" #n ")" ::: "memory")
; #define PG8_BAR __builtin_amdgcn_s_barrier()
; #define PG8_SCHED __builtin_amdgcn_sched_barrier(0)
; template <bool HM = false, bool PERM = false, bool CP = false, class Prob, class Epi>
; __device__ __forceinline__ void gemm_phase(LAS unsigned char* lds, const Prob& S, const Epi& E) {
;     ...
;             PG8_WAIT_V(8); PG8_WAIT_L(0); PG8_BAR; if (!HM) { if (!CP || fullu) PG8_MMA(1, 0, At, B0); PG8_MMA(1, 1, At, B1); } PG8_BAR; PG8_SCHED;
;             PG8_LDB(B0, 1, 0); PG8_LDB(B1, 1, 1); PG8_SCHED; PG8_LDA(At, 1, 0); PG8_STAGE(PG8_SA(0, 1), a2 + hstepA, voffA);
;             PG8_WAIT_V(8); PG8_WAIT_L(0); PG8_BAR; if (!CP || fullu) PG8_MMA(0, 0, At, B0); PG8_MMA(0, 1, At, B1); PG8_BAR; PG8_SCHED;
	s_waitcnt lgkmcnt(0)
	v_mfma_f32_16x16x32_bf16 v[62:65], v[136:139], v[174:177], v[62:65]
	v_mfma_f32_16x16x32_bf16 v[58:61], v[150:153], v[174:177], v[58:61]
	v_mfma_f32_16x16x32_bf16 v[46:49], v[136:139], v[182:185], v[46:49]
	v_mfma_f32_16x16x32_bf16 v[42:45], v[150:153], v[182:185], v[42:45]
	v_mfma_f32_16x16x32_bf16 v[30:33], v[136:139], v[190:193], v[30:33]
	v_mfma_f32_16x16x32_bf16 v[26:29], v[150:153], v[190:193], v[26:29]
	v_mfma_f32_16x16x32_bf16 v[14:17], v[136:139], v[198:201], v[14:17]
	v_mfma_f32_16x16x32_bf16 v[10:13], v[150:153], v[198:201], v[10:13]
	v_mfma_f32_16x16x32_bf16 v[62:65], v[146:149], v[178:181], v[62:65]
	v_mfma_f32_16x16x32_bf16 v[58:61], v[154:157], v[178:181], v[58:61]
	v_mfma_f32_16x16x32_bf16 v[46:49], v[146:149], v[186:189], v[46:49]
	v_mfma_f32_16x16x32_bf16 v[42:45], v[154:157], v[186:189], v[42:45]
	v_mfma_f32_16x16x32_bf16 v[30:33], v[146:149], v[194:197], v[30:33]
	v_mfma_f32_16x16x32_bf16 v[26:29], v[154:157], v[194:197], v[26:29]
	v_mfma_f32_16x16x32_bf16 v[14:17], v[146:149], v[202:205], v[14:17]
	v_mfma_f32_16x16x32_bf16 v[10:13], v[154:157], v[202:205], v[10:13]
	v_mfma_f32_16x16x32_bf16 v[54:57], v[158:161], v[174:177], v[54:57]
	v_mfma_f32_16x16x32_bf16 v[50:53], v[166:169], v[174:177], v[50:53]
	v_mfma_f32_16x16x32_bf16 v[38:41], v[158:161], v[182:185], v[38:41]
	v_mfma_f32_16x16x32_bf16 v[34:37], v[166:169], v[182:185], v[34:37]
	v_mfma_f32_16x16x32_bf16 v[22:25], v[158:161], v[190:193], v[22:25]
	v_mfma_f32_16x16x32_bf16 v[18:21], v[166:169], v[190:193], v[18:21]
	v_mfma_f32_16x16x32_bf16 v[6:9], v[158:161], v[198:201], v[6:9]
	v_mfma_f32_16x16x32_bf16 v[2:5], v[166:169], v[198:201], v[2:5]
	v_mfma_f32_16x16x32_bf16 v[54:57], v[162:165], v[178:181], v[54:57]
	v_mfma_f32_16x16x32_bf16 v[50:53], v[170:173], v[178:181], v[50:53]
	v_mfma_f32_16x16x32_bf16 v[38:41], v[162:165], v[186:189], v[38:41]
	v_mfma_f32_16x16x32_bf16 v[34:37], v[170:173], v[186:189], v[34:37]
	v_mfma_f32_16x16x32_bf16 v[22:25], v[162:165], v[194:197], v[22:25]
	v_mfma_f32_16x16x32_bf16 v[18:21], v[170:173], v[194:197], v[18:21]
	v_mfma_f32_16x16x32_bf16 v[6:9], v[162:165], v[202:205], v[6:9]
	v_mfma_f32_16x16x32_bf16 v[2:5], v[170:173], v[202:205], v[2:5]
	s_barrier
	s_add_i32 s78, 0, 0x18000
	s_add_i32 s79, 0, 0x1c000
	v_add_u32_e32 v154, s78, v144
	v_add_u32_e32 v170, s79, v144
	ds_read_b128 v[136:139], v154
	ds_read_b128 v[146:149], v154 offset:1024
	ds_read_b128 v[150:153], v154 offset:2048
	ds_read_b128 v[154:157], v154 offset:3072
	ds_read_b128 v[158:161], v170
	ds_read_b128 v[162:165], v170 offset:1024
	ds_read_b128 v[166:169], v170 offset:2048
	ds_read_b128 v[170:173], v170 offset:3072
	s_add_u32 s34, s34, 0x40000
	s_addc_u32 s35, s35, 0
	s_mov_b32 m0, s67
	v_lshl_add_u64 v[212:213], s[34:35], 0, v[0:1]
	ds_read_b128 v[174:177], v145 offset:32768
	ds_read_b128 v[178:181], v145 offset:33792
	ds_read_b128 v[182:185], v145 offset:34816
	ds_read_b128 v[186:189], v145 offset:35840
	ds_read_b128 v[190:193], v145 offset:36864
	ds_read_b128 v[194:197], v145 offset:37888
	ds_read_b128 v[198:201], v145 offset:38912
	ds_read_b128 v[202:205], v145 offset:39936
	global_load_lds_dwordx4 v[212:213], off
	v_lshl_add_u64 v[212:213], s[34:35], 0, v[130:131]
	s_mov_b32 m0, s68
	s_nop 0
	global_load_lds_dwordx4 v[212:213], off
	s_waitcnt vmcnt(8)
	s_waitcnt lgkmcnt(0)
	s_barrier
	s_waitcnt lgkmcnt(0)
	v_mfma_f32_16x16x32_bf16 v[126:129], v[136:139], v[174:177], v[126:129]
	v_mfma_f32_16x16x32_bf16 v[122:125], v[150:153], v[174:177], v[122:125]
	v_mfma_f32_16x16x32_bf16 v[110:113], v[136:139], v[182:185], v[110:113]
	v_mfma_f32_16x16x32_bf16 v[106:109], v[150:153], v[182:185], v[106:109]
	v_mfma_f32_16x16x32_bf16 v[94:97], v[136:139], v[190:193], v[94:97]
	v_mfma_f32_16x16x32_bf16 v[90:93], v[150:153], v[190:193], v[90:93]
	v_mfma_f32_16x16x32_bf16 v[78:81], v[136:139], v[198:201], v[78:81]
	v_mfma_f32_16x16x32_bf16 v[74:77], v[150:153], v[198:201], v[74:77]
	v_mfma_f32_16x16x32_bf16 v[126:129], v[146:149], v[178:181], v[126:129]
	v_mfma_f32_16x16x32_bf16 v[122:125], v[154:157], v[178:181], v[122:125]
	v_mfma_f32_16x16x32_bf16 v[110:113], v[146:149], v[186:189], v[110:113]
	v_mfma_f32_16x16x32_bf16 v[106:109], v[154:157], v[186:189], v[106:109]
	v_mfma_f32_16x16x32_bf16 v[94:97], v[146:149], v[194:197], v[94:97]
	v_mfma_f32_16x16x32_bf16 v[90:93], v[154:157], v[194:197], v[90:93]
	v_mfma_f32_16x16x32_bf16 v[78:81], v[146:149], v[202:205], v[78:81]
	v_mfma_f32_16x16x32_bf16 v[74:77], v[154:157], v[202:205], v[74:77]
	v_mfma_f32_16x16x32_bf16 v[118:121], v[158:161], v[174:177], v[118:121]
	v_mfma_f32_16x16x32_bf16 v[114:117], v[166:169], v[174:177], v[114:117]
	v_mfma_f32_16x16x32_bf16 v[102:105], v[158:161], v[182:185], v[102:105]
	v_mfma_f32_16x16x32_bf16 v[98:101], v[166:169], v[182:185], v[98:101]
	v_mfma_f32_16x16x32_bf16 v[86:89], v[158:161], v[190:193], v[86:89]
	v_mfma_f32_16x16x32_bf16 v[82:85], v[166:169], v[190:193], v[82:85]
	v_mfma_f32_16x16x32_bf16 v[70:73], v[158:161], v[198:201], v[70:73]
	v_mfma_f32_16x16x32_bf16 v[66:69], v[166:169], v[198:201], v[66:69]
	v_mfma_f32_16x16x32_bf16 v[118:121], v[162:165], v[178:181], v[118:121]
	v_mfma_f32_16x16x32_bf16 v[114:117], v[170:173], v[178:181], v[114:117]
	v_mfma_f32_16x16x32_bf16 v[102:105], v[162:165], v[186:189], v[102:105]
	v_mfma_f32_16x16x32_bf16 v[98:101], v[170:173], v[186:189], v[98:101]
	v_mfma_f32_16x16x32_bf16 v[86:89], v[162:165], v[194:197], v[86:89]
	v_mfma_f32_16x16x32_bf16 v[82:85], v[170:173], v[194:197], v[82:85]
	v_mfma_f32_16x16x32_bf16 v[70:73], v[162:165], v[202:205], v[70:73]
	v_mfma_f32_16x16x32_bf16 v[66:69], v[170:173], v[202:205], v[66:69]
	s_barrier
; #define PG8_STAGE(bufoff, gbase, voff) do { _Pragma("unroll") for (int _i = 0; _i < 2; ++_i) \
;         __builtin_amdgcn_global_load_lds((const unsigned*)((const char*)(gbase) + (voff)[_i]), (LAS unsigned*)(lds + (bufoff) + ldsw + _i * 8192), 16, 0, 0); } while (0)
; #define PG8_LDA(dst, b, h) do { _Pragma("unroll") for (int m = 0; m < 4; ++m) _Pragma("unroll") for (int k = 0; k < 2; ++k) dst[m][k] = *(const LAS bf16x8*)(lds + PG8_SA(b, h) + aoff + m * 2048 + k * 1024); } while (0)
; #define PG8_MMA(ai, bj, At, Bt) do { __builtin_amdgcn_s_setprio(1); _Pragma("unroll") for (int m = 0; m < 4; ++m) _Pragma("unroll") for (int n = 0; n < 2; ++n) _Pragma("unroll") for (int k = 0; k < 2; ++k) \
;         acc[ai][bj][m][n] = __builtin_amdgcn_mfma_f32_16x16x32_bf16(Bt[n][k], At[m][k], acc[ai][bj][m][n], 0, 0, 0); __builtin_amdgcn_s_setprio(0); } while (0)
; #define PG8_WAIT_V(n) asm volatile("s_waitcnt vmcnt(" #n ")" ::: "memory")
; #define PG8_WAIT_L(n) asm volatile("s_waitcnt lgkmcnt(" #n ")" ::: "memory")
; #define PG8_BAR __builtin_amdgcn_s_barrier()
; #define PG8_SCHED __builtin_amdgcn_sched_barrier(0)
; template <bool HM = false, bool PERM = false, bool CP = false, class Prob, class Epi>
; __device__ __forceinline__ void gemm_phase(LAS unsigned char* lds, const Prob& S, const Epi& E) {
;     ...
;         for (int t = 0; t < nt; t += 2) {
;     ...
;             if (!HM) PG8_LDA(At, 1, 1); PG8_STAGE(PG8_SB(1, 0), b3, voffB); PG8_STAGE(PG8_SB(1, 1), b3 + h2, voffB); PG8_STAGE(PG8_SA(1, 0), a3, voffA);
;             PG8_WAIT_V(8); PG8_WAIT_L(0); PG8_BAR; if (!HM) { if (!CP || fullu) PG8_MMA(1, 0, At, B0); PG8_MMA(1, 1, At, B1); } PG8_BAR; PG8_SCHED;
	s_add_i32 s34, s78, s63
	v_lshl_add_u64 v[140:141], v[140:141], 0, s[20:21]
	s_mov_b32 m0, s34
	ds_read_b128 v[174:177], v145 offset:49152
	ds_read_b128 v[178:181], v145 offset:50176
	ds_read_b128 v[182:185], v145 offset:51200
	ds_read_b128 v[186:189], v145 offset:52224
	ds_read_b128 v[190:193], v145 offset:53248
	ds_read_b128 v[194:197], v145 offset:54272
	ds_read_b128 v[198:201], v145 offset:55296
	ds_read_b128 v[202:205], v145 offset:56320
	global_load_lds_dwordx4 v[140:141], off
	s_add_i32 m0, s34, 0x2000
	s_add_u32 s24, s24, 0x40080
	v_lshl_add_u64 v[140:141], v[206:207], 0, s[20:21]
	s_addc_u32 s25, s25, 0
	s_add_i32 s34, s79, s63
	global_load_lds_dwordx4 v[140:141], off
	v_lshl_add_u64 v[140:141], s[24:25], 0, v[0:1]
	s_mov_b32 m0, s34
	s_nop 0
	global_load_lds_dwordx4 v[140:141], off
	v_lshl_add_u64 v[140:141], s[24:25], 0, v[130:131]
	s_add_i32 m0, s34, 0x2000
	s_nop 0
	global_load_lds_dwordx4 v[140:141], off
	v_lshl_add_u64 v[140:141], v[208:209], 0, s[20:21]
	s_mov_b32 m0, s70
	s_nop 0
	global_load_lds_dwordx4 v[140:141], off
	v_lshl_add_u64 v[140:141], v[210:211], 0, s[20:21]
	s_mov_b32 m0, s71
	s_nop 0
	global_load_lds_dwordx4 v[140:141], off
	s_waitcnt vmcnt(8)
	s_waitcnt lgkmcnt(0)
	s_barrier
	s_waitcnt lgkmcnt(0)
	v_mfma_f32_16x16x32_bf16 v[62:65], v[136:139], v[174:177], v[62:65]
	v_mfma_f32_16x16x32_bf16 v[58:61], v[150:153], v[174:177], v[58:61]
	v_mfma_f32_16x16x32_bf16 v[46:49], v[136:139], v[182:185], v[46:49]
	v_mfma_f32_16x16x32_bf16 v[42:45], v[150:153], v[182:185], v[42:45]
	v_mfma_f32_16x16x32_bf16 v[30:33], v[136:139], v[190:193], v[30:33]
	v_mfma_f32_16x16x32_bf16 v[26:29], v[150:153], v[190:193], v[26:29]
	v_mfma_f32_16x16x32_bf16 v[14:17], v[136:139], v[198:201], v[14:17]
	v_mfma_f32_16x16x32_bf16 v[10:13], v[150:153], v[198:201], v[10:13]
	v_mfma_f32_16x16x32_bf16 v[62:65], v[146:149], v[178:181], v[62:65]
	v_mfma_f32_16x16x32_bf16 v[58:61], v[154:157], v[178:181], v[58:61]
	v_mfma_f32_16x16x32_bf16 v[46:49], v[146:149], v[186:189], v[46:49]
	v_mfma_f32_16x16x32_bf16 v[42:45], v[154:157], v[186:189], v[42:45]
	v_mfma_f32_16x16x32_bf16 v[30:33], v[146:149], v[194:197], v[30:33]
	v_mfma_f32_16x16x32_bf16 v[26:29], v[154:157], v[194:197], v[26:29]
	v_mfma_f32_16x16x32_bf16 v[14:17], v[146:149], v[202:205], v[14:17]
	v_mfma_f32_16x16x32_bf16 v[10:13], v[154:157], v[202:205], v[10:13]
	v_mfma_f32_16x16x32_bf16 v[54:57], v[158:161], v[174:177], v[54:57]
	v_mfma_f32_16x16x32_bf16 v[50:53], v[166:169], v[174:177], v[50:53]
	v_mfma_f32_16x16x32_bf16 v[38:41], v[158:161], v[182:185], v[38:41]
	v_mfma_f32_16x16x32_bf16 v[34:37], v[166:169], v[182:185], v[34:37]
	v_mfma_f32_16x16x32_bf16 v[22:25], v[158:161], v[190:193], v[22:25]
	v_mfma_f32_16x16x32_bf16 v[18:21], v[166:169], v[190:193], v[18:21]
	v_mfma_f32_16x16x32_bf16 v[6:9], v[158:161], v[198:201], v[6:9]
	v_mfma_f32_16x16x32_bf16 v[2:5], v[166:169], v[198:201], v[2:5]
	v_mfma_f32_16x16x32_bf16 v[54:57], v[162:165], v[178:181], v[54:57]
	v_mfma_f32_16x16x32_bf16 v[50:53], v[170:173], v[178:181], v[50:53]
	v_mfma_f32_16x16x32_bf16 v[38:41], v[162:165], v[186:189], v[38:41]
	v_mfma_f32_16x16x32_bf16 v[34:37], v[170:173], v[186:189], v[34:37]
	v_mfma_f32_16x16x32_bf16 v[22:25], v[162:165], v[194:197], v[22:25]
	v_mfma_f32_16x16x32_bf16 v[18:21], v[170:173], v[194:197], v[18:21]
	v_mfma_f32_16x16x32_bf16 v[6:9], v[162:165], v[202:205], v[6:9]
	v_mfma_f32_16x16x32_bf16 v[2:5], v[170:173], v[202:205], v[2:5]
	s_barrier
	s_add_u32 s8, s8, 0x100
	s_addc_u32 s9, s9, 0
	s_add_u32 s45, s45, 0x100
	s_addc_u32 s76, s76, 0
	s_cmp_ge_u32 s77, s5
	s_mov_b32 s34, s77
	s_cbranch_scc0 .LBB0_1001
	s_and_b64 vcc, exec, s[22:23]
	s_cbranch_vccz .LBB0_1004
	s_barrier

; #define PG8_STAGE(bufoff, gbase, voff) do { _Pragma("unroll") for (int _i = 0; _i < 2; ++_i) \
;         __builtin_amdgcn_global_load_lds((const unsigned*)((const char*)(gbase) + (voff)[_i]), (LAS unsigned*)(lds + (bufoff) + ldsw + _i * 8192), 16, 0, 0); } while (0)
; #define PG8_LDA(dst, b, h) do { _Pragma("unroll") for (int m = 0; m < 4; ++m) _Pragma("unroll") for (int k = 0; k < 2; ++k) dst[m][k] = *(const LAS bf16x8*)(lds + PG8_SA(b, h) + aoff + m * 2048 + k * 1024); } while (0)
; #define PG8_LDB(dst, b, h) do { _Pragma("unroll") for (int n = 0; n < 2; ++n) _Pragma("unroll") for (int k = 0; k < 2; ++k) dst[n][k] = *(const LAS bf16x8*)(lds + PG8_SB(b, h) + boff + n * 2048 + k * 1024); } while (0)
; #define PG8_MMA(ai, bj, At, Bt) do { __builtin_amdgcn_s_setprio(1); _Pragma("unroll") for (int m = 0; m < 4; ++m) _Pragma("unroll") for (int n = 0; n < 2; ++n) _Pragma("unroll") for (int k = 0; k < 2; ++k) \
;         acc[ai][bj][m][n] = __builtin_amdgcn_mfma_f32_16x16x32_bf16(Bt[n][k], At[m][k], acc[ai][bj][m][n], 0, 0, 0); __builtin_amdgcn_s_setprio(0); } while (0)
; #define PG8_WAIT_V(n) asm volatile("s_waitcnt vmcnt(" #n ")" ::: "memory")
; #define PG8_WAIT_L(n) asm volatile("s_waitcnt lgkmcnt(" #n ")" ::: "memory")
; #define PG8_BAR __builtin_amdgcn_s_barrier()
; #define PG8_SCHED __builtin_amdgcn_sched_barrier(0)
; template <bool HM = false, bool PERM = false, bool CP = false, class Prob, class Epi>
; __device__ __forceinline__ void gemm_phase(LAS unsigned char* lds, const Prob& S, const Epi& E) {
;     ...
;             const bool last = (t == nt - 2);
;             const char* a1 = cA + (size_t)(t + 1) * kstepA;
;             const char* a2 = last ? nA : cA + (size_t)(t + 2) * kstepA; const char* b2 = last ? nB : cB + (size_t)(t + 2) * kstepB;
;             const char* a3 = a2 + kstepA; const char* b3 = b2 + kstepB; const long h2 = last ? nhB : chB;
;     ...
;             PG8_LDB(B0, 0, 0); PG8_LDB(B1, 0, 1); PG8_SCHED; PG8_LDA(At, 0, 0); PG8_STAGE(PG8_SA(1, 1), a1 + hstepA, voffA);
;             PG8_WAIT_V(8); PG8_WAIT_L(0); PG8_BAR; if (!CP || fullu) PG8_MMA(0, 0, At, B0); PG8_MMA(0, 1, At, B1); PG8_BAR; PG8_SCHED;
;             if (!HM) PG8_LDA(At, 0, 1); PG8_STAGE(PG8_SB(0, 0), b2, voffB); PG8_STAGE(PG8_SB(0, 1), b2 + h2, voffB); PG8_STAGE(PG8_SA(0, 0), a2, voffA);
.LBB0_1035:
	s_add_u32 s24, s0, 0xfffc0080
	s_addc_u32 s25, s1, -1
	s_cmp_eq_u32 s69, 12
	s_cselect_b32 s35, s37, s25
	s_cselect_b32 s34, s45, s24
	s_cselect_b32 s25, s23, s68
	s_cselect_b32 s24, s66, s67
	s_add_i32 s70, 0, 0x10000
	s_add_i32 s72, 0, 0x14000
	v_add_u32_e32 v152, s70, v146
	v_add_u32_e32 v168, s72, v146
	ds_read_b128 v[136:139], v152
	ds_read_b128 v[140:143], v152 offset:1024
	ds_read_b128 v[148:151], v152 offset:2048
	ds_read_b128 v[152:155], v152 offset:3072
	ds_read_b128 v[156:159], v168
	ds_read_b128 v[160:163], v168 offset:1024
	ds_read_b128 v[164:167], v168 offset:2048
	ds_read_b128 v[168:171], v168 offset:3072
	v_lshl_add_u64 v[204:205], s[0:1], 0, v[132:133]
	s_add_i32 m0, s2, 0xc000
	ds_read_b128 v[172:175], v147
	ds_read_b128 v[176:179], v147 offset:1024
	ds_read_b128 v[180:183], v147 offset:2048
	ds_read_b128 v[184:187], v147 offset:3072
	ds_read_b128 v[188:191], v147 offset:4096
	ds_read_b128 v[192:195], v147 offset:5120
	ds_read_b128 v[196:199], v147 offset:6144
	ds_read_b128 v[200:203], v147 offset:7168
	global_load_lds_dwordx4 v[204:205], off
	v_lshl_add_u64 v[204:205], s[0:1], 0, v[134:135]
	s_add_i32 m0, s2, 0xe000
	s_nop 0
	global_load_lds_dwordx4 v[204:205], off
	s_waitcnt vmcnt(8)
	s_waitcnt lgkmcnt(0)
	s_barrier
	s_waitcnt lgkmcnt(0)
	v_mfma_f32_16x16x32_bf16 v[126:129], v[136:139], v[172:175], v[126:129]
	v_mfma_f32_16x16x32_bf16 v[122:125], v[148:151], v[172:175], v[122:125]
	v_mfma_f32_16x16x32_bf16 v[110:113], v[136:139], v[180:183], v[110:113]
	v_mfma_f32_16x16x32_bf16 v[106:109], v[148:151], v[180:183], v[106:109]
	v_mfma_f32_16x16x32_bf16 v[94:97], v[136:139], v[188:191], v[94:97]
	v_mfma_f32_16x16x32_bf16 v[90:93], v[148:151], v[188:191], v[90:93]
	v_mfma_f32_16x16x32_bf16 v[78:81], v[136:139], v[196:199], v[78:81]
	v_mfma_f32_16x16x32_bf16 v[74:77], v[148:151], v[196:199], v[74:77]
	v_mfma_f32_16x16x32_bf16 v[126:129], v[140:143], v[176:179], v[126:129]
	v_mfma_f32_16x16x32_bf16 v[122:125], v[152:155], v[176:179], v[122:125]
	v_mfma_f32_16x16x32_bf16 v[110:113], v[140:143], v[184:187], v[110:113]
	v_mfma_f32_16x16x32_bf16 v[106:109], v[152:155], v[184:187], v[106:109]
	v_mfma_f32_16x16x32_bf16 v[94:97], v[140:143], v[192:195], v[94:97]
	v_mfma_f32_16x16x32_bf16 v[90:93], v[152:155], v[192:195], v[90:93]
	v_mfma_f32_16x16x32_bf16 v[78:81], v[140:143], v[200:203], v[78:81]
	v_mfma_f32_16x16x32_bf16 v[74:77], v[152:155], v[200:203], v[74:77]
	v_mfma_f32_16x16x32_bf16 v[118:121], v[156:159], v[172:175], v[118:121]
	v_mfma_f32_16x16x32_bf16 v[114:117], v[164:167], v[172:175], v[114:117]
	v_mfma_f32_16x16x32_bf16 v[102:105], v[156:159], v[180:183], v[102:105]
	v_mfma_f32_16x16x32_bf16 v[98:101], v[164:167], v[180:183], v[98:101]
	v_mfma_f32_16x16x32_bf16 v[86:89], v[156:159], v[188:191], v[86:89]
	v_mfma_f32_16x16x32_bf16 v[82:85], v[164:167], v[188:191], v[82:85]
	v_mfma_f32_16x16x32_bf16 v[70:73], v[156:159], v[196:199], v[70:73]
	v_mfma_f32_16x16x32_bf16 v[66:69], v[164:167], v[196:199], v[66:69]
	v_mfma_f32_16x16x32_bf16 v[118:121], v[160:163], v[176:179], v[118:121]
	v_mfma_f32_16x16x32_bf16 v[114:117], v[168:171], v[176:179], v[114:117]
	v_mfma_f32_16x16x32_bf16 v[102:105], v[160:163], v[184:187], v[102:105]
	v_mfma_f32_16x16x32_bf16 v[98:101], v[168:171], v[184:187], v[98:101]
	v_mfma_f32_16x16x32_bf16 v[86:89], v[160:163], v[192:195], v[86:89]
	v_mfma_f32_16x16x32_bf16 v[82:85], v[168:171], v[192:195], v[82:85]
	v_mfma_f32_16x16x32_bf16 v[70:73], v[160:163], v[200:203], v[70:73]
	v_mfma_f32_16x16x32_bf16 v[66:69], v[168:171], v[200:203], v[66:69]
	s_barrier
	s_add_i32 s70, s70, s31
	v_lshl_add_u64 v[204:205], s[24:25], 0, v[0:1]
	s_mov_b32 m0, s70
	ds_read_b128 v[172:175], v147 offset:16384
	ds_read_b128 v[176:179], v147 offset:17408
	ds_read_b128 v[180:183], v147 offset:18432
	ds_read_b128 v[184:187], v147 offset:19456
	ds_read_b128 v[188:191], v147 offset:20480
	ds_read_b128 v[192:195], v147 offset:21504
	ds_read_b128 v[196:199], v147 offset:22528
	ds_read_b128 v[200:203], v147 offset:23552
	global_load_lds_dwordx4 v[204:205], off
	s_add_i32 m0, s70, 0x2000
	s_add_u32 s70, s24, 0x40000
	v_lshl_add_u64 v[206:207], s[24:25], 0, v[130:131]
	s_addc_u32 s71, s25, 0
	s_add_i32 s72, s72, s31
	global_load_lds_dwordx4 v[206:207], off
	v_lshl_add_u64 v[208:209], s[70:71], 0, v[0:1]
	s_mov_b32 m0, s72
	v_lshl_add_u64 v[210:211], s[34:35], 0, v[130:131]
	global_load_lds_dwordx4 v[208:209], off
	v_lshl_add_u64 v[208:209], s[70:71], 0, v[130:131]
	s_add_i32 m0, s72, 0x2000
	s_nop 0
	global_load_lds_dwordx4 v[208:209], off
	v_lshl_add_u64 v[208:209], s[34:35], 0, v[0:1]
	s_mov_b32 m0, s2
	s_nop 0
	global_load_lds_dwordx4 v[208:209], off
	s_mov_b32 m0, s3
	s_nop 0
	global_load_lds_dwordx4 v[210:211], off
	s_waitcnt vmcnt(8)
	s_waitcnt lgkmcnt(0)
	s_barrier
; #define PG8_STAGE(bufoff, gbase, voff) do { _Pragma("unroll") for (int _i = 0; _i < 2; ++_i) \
;         __builtin_amdgcn_global_load_lds((const unsigned*)((const char*)(gbase) + (voff)[_i]), (LAS unsigned*)(lds + (bufoff) + ldsw + _i * 8192), 16, 0, 0); } while (0)
; #define PG8_LDA(dst, b, h) do { _Pragma("unroll") for (int m = 0; m < 4; ++m) _Pragma("unroll") for (int k = 0; k < 2; ++k) dst[m][k] = *(const LAS bf16x8*)(lds + PG8_SA(b, h) + aoff + m * 2048 + k * 1024); } while (0)
; #define PG8_LDB(dst, b, h) do { _Pragma("unroll") for (int n = 0; n < 2; ++n) _Pragma("unroll") for (int k = 0; k < 2; ++k) dst[n][k] = *(const LAS bf16x8*)(lds + PG8_SB(b, h) + boff + n * 2048 + k * 1024); } while (0)
; #define PG8_MMA(ai, bj, At, Bt) do { __builtin_amdgcn_s_setprio(1); _Pragma("unroll") for (int m = 0; m < 4; ++m) _Pragma("unroll") for (int n = 0; n < 2; ++n) _Pragma("unroll") for (int k = 0; k < 2; ++k) \
;         acc[ai][bj][m][n] = __builtin_amdgcn_mfma_f32_16x16x32_bf16(Bt[n][k], At[m][k], acc[ai][bj][m][n], 0, 0, 0); __builtin_amdgcn_s_setprio(0); } while (0)
; #define PG8_WAIT_V(n) asm volatile("s_waitcnt vmcnt(" #n ")" ::: "memory")
; #define PG8_WAIT_L(n) asm volatile("s_waitcnt lgkmcnt(" #n ")" ::: "memory")
; #define PG8_BAR __builtin_amdgcn_s_barrier()
; #define PG8_SCHED __builtin_amdgcn_sched_barrier(0)
; template <bool HM = false, bool PERM = false, bool CP = false, class Prob, class Epi>
; __device__ __forceinline__ void gemm_phase(LAS unsigned char* lds, const Prob& S, const Epi& E) {
;     ...
;             PG8_WAIT_V(8); PG8_WAIT_L(0); PG8_BAR; if (!HM) { if (!CP || fullu) PG8_MMA(1, 0, At, B0); PG8_MMA(1, 1, At, B1); } PG8_BAR; PG8_SCHED;
;             PG8_LDB(B0, 1, 0); PG8_LDB(B1, 1, 1); PG8_SCHED; PG8_LDA(At, 1, 0); PG8_STAGE(PG8_SA(0, 1), a2 + hstepA, voffA);
;             PG8_WAIT_V(8); PG8_WAIT_L(0); PG8_BAR; if (!CP || fullu) PG8_MMA(0, 0, At, B0); PG8_MMA(0, 1, At, B1); PG8_BAR; PG8_SCHED;
	s_waitcnt lgkmcnt(0)
	v_mfma_f32_16x16x32_bf16 v[62:65], v[136:139], v[172:175], v[62:65]
	v_mfma_f32_16x16x32_bf16 v[58:61], v[148:151], v[172:175], v[58:61]
	v_mfma_f32_16x16x32_bf16 v[46:49], v[136:139], v[180:183], v[46:49]
	v_mfma_f32_16x16x32_bf16 v[42:45], v[148:151], v[180:183], v[42:45]
	v_mfma_f32_16x16x32_bf16 v[30:33], v[136:139], v[188:191], v[30:33]
	v_mfma_f32_16x16x32_bf16 v[26:29], v[148:151], v[188:191], v[26:29]
	v_mfma_f32_16x16x32_bf16 v[14:17], v[136:139], v[196:199], v[14:17]
	v_mfma_f32_16x16x32_bf16 v[10:13], v[148:151], v[196:199], v[10:13]
	v_mfma_f32_16x16x32_bf16 v[62:65], v[140:143], v[176:179], v[62:65]
	v_mfma_f32_16x16x32_bf16 v[58:61], v[152:155], v[176:179], v[58:61]
	v_mfma_f32_16x16x32_bf16 v[46:49], v[140:143], v[184:187], v[46:49]
	v_mfma_f32_16x16x32_bf16 v[42:45], v[152:155], v[184:187], v[42:45]
	v_mfma_f32_16x16x32_bf16 v[30:33], v[140:143], v[192:195], v[30:33]
	v_mfma_f32_16x16x32_bf16 v[26:29], v[152:155], v[192:195], v[26:29]
	v_mfma_f32_16x16x32_bf16 v[14:17], v[140:143], v[200:203], v[14:17]
	v_mfma_f32_16x16x32_bf16 v[10:13], v[152:155], v[200:203], v[10:13]
	v_mfma_f32_16x16x32_bf16 v[54:57], v[156:159], v[172:175], v[54:57]
	v_mfma_f32_16x16x32_bf16 v[50:53], v[164:167], v[172:175], v[50:53]
	v_mfma_f32_16x16x32_bf16 v[38:41], v[156:159], v[180:183], v[38:41]
	v_mfma_f32_16x16x32_bf16 v[34:37], v[164:167], v[180:183], v[34:37]
	v_mfma_f32_16x16x32_bf16 v[22:25], v[156:159], v[188:191], v[22:25]
	v_mfma_f32_16x16x32_bf16 v[18:21], v[164:167], v[188:191], v[18:21]
	v_mfma_f32_16x16x32_bf16 v[6:9], v[156:159], v[196:199], v[6:9]
	v_mfma_f32_16x16x32_bf16 v[2:5], v[164:167], v[196:199], v[2:5]
	v_mfma_f32_16x16x32_bf16 v[54:57], v[160:163], v[176:179], v[54:57]
	v_mfma_f32_16x16x32_bf16 v[50:53], v[168:171], v[176:179], v[50:53]
	v_mfma_f32_16x16x32_bf16 v[38:41], v[160:163], v[184:187], v[38:41]
	v_mfma_f32_16x16x32_bf16 v[34:37], v[168:171], v[184:187], v[34:37]
	v_mfma_f32_16x16x32_bf16 v[22:25], v[160:163], v[192:195], v[22:25]
	v_mfma_f32_16x16x32_bf16 v[18:21], v[168:171], v[192:195], v[18:21]
	v_mfma_f32_16x16x32_bf16 v[6:9], v[160:163], v[200:203], v[6:9]
	v_mfma_f32_16x16x32_bf16 v[2:5], v[168:171], v[200:203], v[2:5]
	s_barrier
	s_add_i32 s70, 0, 0x18000
	s_add_i32 s71, 0, 0x1c000
	v_add_u32_e32 v152, s70, v146
	v_add_u32_e32 v168, s71, v146
	ds_read_b128 v[136:139], v152
	ds_read_b128 v[140:143], v152 offset:1024
	ds_read_b128 v[148:151], v152 offset:2048
	ds_read_b128 v[152:155], v152 offset:3072
	ds_read_b128 v[156:159], v168
	ds_read_b128 v[160:163], v168 offset:1024
	ds_read_b128 v[164:167], v168 offset:2048
	ds_read_b128 v[168:171], v168 offset:3072
	s_add_u32 s34, s34, 0x40000
	s_addc_u32 s35, s35, 0
	s_mov_b32 m0, s18
	v_lshl_add_u64 v[212:213], s[34:35], 0, v[0:1]
	ds_read_b128 v[172:175], v147 offset:32768
	ds_read_b128 v[176:179], v147 offset:33792
	ds_read_b128 v[180:183], v147 offset:34816
	ds_read_b128 v[184:187], v147 offset:35840
	ds_read_b128 v[188:191], v147 offset:36864
	ds_read_b128 v[192:195], v147 offset:37888
	ds_read_b128 v[196:199], v147 offset:38912
	ds_read_b128 v[200:203], v147 offset:39936
	global_load_lds_dwordx4 v[212:213], off
	v_lshl_add_u64 v[212:213], s[34:35], 0, v[130:131]
	s_mov_b32 m0, s19
	s_nop 0
	global_load_lds_dwordx4 v[212:213], off
	s_waitcnt vmcnt(8)
	s_waitcnt lgkmcnt(0)
	s_barrier
	s_waitcnt lgkmcnt(0)
	v_mfma_f32_16x16x32_bf16 v[126:129], v[136:139], v[172:175], v[126:129]
	v_mfma_f32_16x16x32_bf16 v[122:125], v[148:151], v[172:175], v[122:125]
	v_mfma_f32_16x16x32_bf16 v[110:113], v[136:139], v[180:183], v[110:113]
	v_mfma_f32_16x16x32_bf16 v[106:109], v[148:151], v[180:183], v[106:109]
	v_mfma_f32_16x16x32_bf16 v[94:97], v[136:139], v[188:191], v[94:97]
	v_mfma_f32_16x16x32_bf16 v[90:93], v[148:151], v[188:191], v[90:93]
	v_mfma_f32_16x16x32_bf16 v[78:81], v[136:139], v[196:199], v[78:81]
	v_mfma_f32_16x16x32_bf16 v[74:77], v[148:151], v[196:199], v[74:77]
	v_mfma_f32_16x16x32_bf16 v[126:129], v[140:143], v[176:179], v[126:129]
	v_mfma_f32_16x16x32_bf16 v[122:125], v[152:155], v[176:179], v[122:125]
	v_mfma_f32_16x16x32_bf16 v[110:113], v[140:143], v[184:187], v[110:113]
	v_mfma_f32_16x16x32_bf16 v[106:109], v[152:155], v[184:187], v[106:109]
	v_mfma_f32_16x16x32_bf16 v[94:97], v[140:143], v[192:195], v[94:97]
	v_mfma_f32_16x16x32_bf16 v[90:93], v[152:155], v[192:195], v[90:93]
	v_mfma_f32_16x16x32_bf16 v[78:81], v[140:143], v[200:203], v[78:81]
	v_mfma_f32_16x16x32_bf16 v[74:77], v[152:155], v[200:203], v[74:77]
	v_mfma_f32_16x16x32_bf16 v[118:121], v[156:159], v[172:175], v[118:121]
	v_mfma_f32_16x16x32_bf16 v[114:117], v[164:167], v[172:175], v[114:117]
	v_mfma_f32_16x16x32_bf16 v[102:105], v[156:159], v[180:183], v[102:105]
	v_mfma_f32_16x16x32_bf16 v[98:101], v[164:167], v[180:183], v[98:101]
	v_mfma_f32_16x16x32_bf16 v[86:89], v[156:159], v[188:191], v[86:89]
	v_mfma_f32_16x16x32_bf16 v[82:85], v[164:167], v[188:191], v[82:85]
	v_mfma_f32_16x16x32_bf16 v[70:73], v[156:159], v[196:199], v[70:73]
	v_mfma_f32_16x16x32_bf16 v[66:69], v[164:167], v[196:199], v[66:69]
	v_mfma_f32_16x16x32_bf16 v[118:121], v[160:163], v[176:179], v[118:121]
	v_mfma_f32_16x16x32_bf16 v[114:117], v[168:171], v[176:179], v[114:117]
	v_mfma_f32_16x16x32_bf16 v[102:105], v[160:163], v[184:187], v[102:105]
	v_mfma_f32_16x16x32_bf16 v[98:101], v[168:171], v[184:187], v[98:101]
	v_mfma_f32_16x16x32_bf16 v[86:89], v[160:163], v[192:195], v[86:89]
	v_mfma_f32_16x16x32_bf16 v[82:85], v[168:171], v[192:195], v[82:85]
	v_mfma_f32_16x16x32_bf16 v[70:73], v[160:163], v[200:203], v[70:73]
	v_mfma_f32_16x16x32_bf16 v[66:69], v[168:171], v[200:203], v[66:69]
	s_barrier
; #define PG8_STAGE(bufoff, gbase, voff) do { _Pragma("unroll") for (int _i = 0; _i < 2; ++_i) \
;         __builtin_amdgcn_global_load_lds((const unsigned*)((const char*)(gbase) + (voff)[_i]), (LAS unsigned*)(lds + (bufoff) + ldsw + _i * 8192), 16, 0, 0); } while (0)
; #define PG8_LDA(dst, b, h) do { _Pragma("unroll") for (int m = 0; m < 4; ++m) _Pragma("unroll") for (int k = 0; k < 2; ++k) dst[m][k] = *(const LAS bf16x8*)(lds + PG8_SA(b, h) + aoff + m * 2048 + k * 1024); } while (0)
; #define PG8_MMA(ai, bj, At, Bt) do { __builtin_amdgcn_s_setprio(1); _Pragma("unroll") for (int m = 0; m < 4; ++m) _Pragma("unroll") for (int n = 0; n < 2; ++n) _Pragma("unroll") for (int k = 0; k < 2; ++k) \
;         acc[ai][bj][m][n] = __builtin_amdgcn_mfma_f32_16x16x32_bf16(Bt[n][k], At[m][k], acc[ai][bj][m][n], 0, 0, 0); __builtin_amdgcn_s_setprio(0); } while (0)
; #define PG8_WAIT_V(n) asm volatile("s_waitcnt vmcnt(" #n ")" ::: "memory")
; #define PG8_WAIT_L(n) asm volatile("s_waitcnt lgkmcnt(" #n ")" ::: "memory")
; #define PG8_BAR __builtin_amdgcn_s_barrier()
; #define PG8_SCHED __builtin_amdgcn_sched_barrier(0)
; template <bool HM = false, bool PERM = false, bool CP = false, class Prob, class Epi>
; __device__ __forceinline__ void gemm_phase(LAS unsigned char* lds, const Prob& S, const Epi& E) {
;     ...
;         for (int t = 0; t < nt; t += 2) {
;     ...
;             if (!HM) PG8_LDA(At, 1, 1); PG8_STAGE(PG8_SB(1, 0), b3, voffB); PG8_STAGE(PG8_SB(1, 1), b3 + h2, voffB); PG8_STAGE(PG8_SA(1, 0), a3, voffA);
;             PG8_WAIT_V(8); PG8_WAIT_L(0); PG8_BAR; if (!HM) { if (!CP || fullu) PG8_MMA(1, 0, At, B0); PG8_MMA(1, 1, At, B1); } PG8_BAR; PG8_SCHED;
	s_add_i32 s34, s70, s31
	v_lshl_add_u64 v[204:205], v[204:205], 0, s[20:21]
	s_mov_b32 m0, s34
	ds_read_b128 v[172:175], v147 offset:49152
	ds_read_b128 v[176:179], v147 offset:50176
	ds_read_b128 v[180:183], v147 offset:51200
	ds_read_b128 v[184:187], v147 offset:52224
	ds_read_b128 v[188:191], v147 offset:53248
	ds_read_b128 v[192:195], v147 offset:54272
	ds_read_b128 v[196:199], v147 offset:55296
	ds_read_b128 v[200:203], v147 offset:56320
	global_load_lds_dwordx4 v[204:205], off
	s_add_i32 m0, s34, 0x2000
	s_add_u32 s24, s24, 0x40080
	v_lshl_add_u64 v[204:205], v[206:207], 0, s[20:21]
	s_addc_u32 s25, s25, 0
	s_add_i32 s34, s71, s31
	global_load_lds_dwordx4 v[204:205], off
	v_lshl_add_u64 v[204:205], s[24:25], 0, v[0:1]
	s_mov_b32 m0, s34
	s_nop 0
	global_load_lds_dwordx4 v[204:205], off
	v_lshl_add_u64 v[204:205], s[24:25], 0, v[130:131]
	s_add_i32 m0, s34, 0x2000
	s_nop 0
	global_load_lds_dwordx4 v[204:205], off
	v_lshl_add_u64 v[204:205], v[208:209], 0, s[20:21]
	s_mov_b32 m0, s61
	s_nop 0
	global_load_lds_dwordx4 v[204:205], off
	v_lshl_add_u64 v[204:205], v[210:211], 0, s[20:21]
	s_mov_b32 m0, s62
	s_nop 0
	global_load_lds_dwordx4 v[204:205], off
	s_waitcnt vmcnt(8)
	s_waitcnt lgkmcnt(0)
	s_barrier
	s_waitcnt lgkmcnt(0)
	v_mfma_f32_16x16x32_bf16 v[62:65], v[136:139], v[172:175], v[62:65]
	v_mfma_f32_16x16x32_bf16 v[58:61], v[148:151], v[172:175], v[58:61]
	v_mfma_f32_16x16x32_bf16 v[46:49], v[136:139], v[180:183], v[46:49]
	v_mfma_f32_16x16x32_bf16 v[42:45], v[148:151], v[180:183], v[42:45]
	v_mfma_f32_16x16x32_bf16 v[30:33], v[136:139], v[188:191], v[30:33]
	v_mfma_f32_16x16x32_bf16 v[26:29], v[148:151], v[188:191], v[26:29]
	v_mfma_f32_16x16x32_bf16 v[14:17], v[136:139], v[196:199], v[14:17]
	v_mfma_f32_16x16x32_bf16 v[10:13], v[148:151], v[196:199], v[10:13]
	v_mfma_f32_16x16x32_bf16 v[62:65], v[140:143], v[176:179], v[62:65]
	v_mfma_f32_16x16x32_bf16 v[58:61], v[152:155], v[176:179], v[58:61]
	v_mfma_f32_16x16x32_bf16 v[46:49], v[140:143], v[184:187], v[46:49]
	v_mfma_f32_16x16x32_bf16 v[42:45], v[152:155], v[184:187], v[42:45]
	v_mfma_f32_16x16x32_bf16 v[30:33], v[140:143], v[192:195], v[30:33]
	v_mfma_f32_16x16x32_bf16 v[26:29], v[152:155], v[192:195], v[26:29]
	v_mfma_f32_16x16x32_bf16 v[14:17], v[140:143], v[200:203], v[14:17]
	v_mfma_f32_16x16x32_bf16 v[10:13], v[152:155], v[200:203], v[10:13]
	v_mfma_f32_16x16x32_bf16 v[54:57], v[156:159], v[172:175], v[54:57]
	v_mfma_f32_16x16x32_bf16 v[50:53], v[164:167], v[172:175], v[50:53]
	v_mfma_f32_16x16x32_bf16 v[38:41], v[156:159], v[180:183], v[38:41]
	v_mfma_f32_16x16x32_bf16 v[34:37], v[164:167], v[180:183], v[34:37]
	v_mfma_f32_16x16x32_bf16 v[22:25], v[156:159], v[188:191], v[22:25]
	v_mfma_f32_16x16x32_bf16 v[18:21], v[164:167], v[188:191], v[18:21]
	v_mfma_f32_16x16x32_bf16 v[6:9], v[156:159], v[196:199], v[6:9]
	v_mfma_f32_16x16x32_bf16 v[2:5], v[164:167], v[196:199], v[2:5]
	v_mfma_f32_16x16x32_bf16 v[54:57], v[160:163], v[176:179], v[54:57]
	v_mfma_f32_16x16x32_bf16 v[50:53], v[168:171], v[176:179], v[50:53]
	v_mfma_f32_16x16x32_bf16 v[38:41], v[160:163], v[184:187], v[38:41]
	v_mfma_f32_16x16x32_bf16 v[34:37], v[168:171], v[184:187], v[34:37]
	v_mfma_f32_16x16x32_bf16 v[22:25], v[160:163], v[192:195], v[22:25]
	v_mfma_f32_16x16x32_bf16 v[18:21], v[168:171], v[192:195], v[18:21]
	v_mfma_f32_16x16x32_bf16 v[6:9], v[160:163], v[200:203], v[6:9]
	v_mfma_f32_16x16x32_bf16 v[2:5], v[168:171], v[200:203], v[2:5]
	s_barrier
	s_add_i32 s69, s69, 2
	s_add_u32 s0, s0, 0x100
	s_addc_u32 s1, s1, 0
	s_add_u32 s67, s67, 0x100
	s_addc_u32 s68, s68, 0
	s_cmp_gt_u32 s69, 13
	s_cbranch_scc0 .LBB0_1035
	s_and_b64 vcc, exec, s[4:5]
	s_cbranch_vccz .LBB0_1038
	s_barrier

; #define PG8_STAGE(bufoff, gbase, voff) do { _Pragma("unroll") for (int _i = 0; _i < 2; ++_i) \
;         __builtin_amdgcn_global_load_lds((const unsigned*)((const char*)(gbase) + (voff)[_i]), (LAS unsigned*)(lds + (bufoff) + ldsw + _i * 8192), 16, 0, 0); } while (0)
; #define PG8_LDA(dst, b, h) do { _Pragma("unroll") for (int m = 0; m < 4; ++m) _Pragma("unroll") for (int k = 0; k < 2; ++k) dst[m][k] = *(const LAS bf16x8*)(lds + PG8_SA(b, h) + aoff + m * 2048 + k * 1024); } while (0)
; #define PG8_LDB(dst, b, h) do { _Pragma("unroll") for (int n = 0; n < 2; ++n) _Pragma("unroll") for (int k = 0; k < 2; ++k) dst[n][k] = *(const LAS bf16x8*)(lds + PG8_SB(b, h) + boff + n * 2048 + k * 1024); } while (0)
; #define PG8_MMA(ai, bj, At, Bt) do { __builtin_amdgcn_s_setprio(1); _Pragma("unroll") for (int m = 0; m < 4; ++m) _Pragma("unroll") for (int n = 0; n < 2; ++n) _Pragma("unroll") for (int k = 0; k < 2; ++k) \
;         acc[ai][bj][m][n] = __builtin_amdgcn_mfma_f32_16x16x32_bf16(Bt[n][k], At[m][k], acc[ai][bj][m][n], 0, 0, 0); __builtin_amdgcn_s_setprio(0); } while (0)
; #define PG8_WAIT_V(n) asm volatile("s_waitcnt vmcnt(" #n ")" ::: "memory")
; #define PG8_WAIT_L(n) asm volatile("s_waitcnt lgkmcnt(" #n ")" ::: "memory")
; #define PG8_BAR __builtin_amdgcn_s_barrier()
; #define PG8_SCHED __builtin_amdgcn_sched_barrier(0)
; template <bool HM = false, bool PERM = false, bool CP = false, class Prob, class Epi>
; __device__ __forceinline__ void gemm_phase(LAS unsigned char* lds, const Prob& S, const Epi& E) {
;     ...
;             const bool last = (t == nt - 2);
;             const char* a1 = cA + (size_t)(t + 1) * kstepA;
;             const char* a2 = last ? nA : cA + (size_t)(t + 2) * kstepA; const char* b2 = last ? nB : cB + (size_t)(t + 2) * kstepB;
;             const char* a3 = a2 + kstepA; const char* b3 = b2 + kstepB; const long h2 = last ? nhB : chB;
;     ...
;             PG8_LDB(B0, 0, 0); PG8_LDB(B1, 0, 1); PG8_SCHED; PG8_LDA(At, 0, 0); PG8_STAGE(PG8_SA(1, 1), a1 + hstepA, voffA);
;             PG8_WAIT_V(8); PG8_WAIT_L(0); PG8_BAR; if (!CP || fullu) PG8_MMA(0, 0, At, B0); PG8_MMA(0, 1, At, B1); PG8_BAR; PG8_SCHED;
;             if (!HM) PG8_LDA(At, 0, 1); PG8_STAGE(PG8_SB(0, 0), b2, voffB); PG8_STAGE(PG8_SB(0, 1), b2 + h2, voffB); PG8_STAGE(PG8_SA(0, 0), a2, voffA);
.LBB0_1224:
	s_add_u32 s24, s0, 0xfffc0080
	s_addc_u32 s25, s1, -1
	s_cmp_eq_u32 s71, 12
	s_cselect_b32 s35, s45, s25
	s_cselect_b32 s34, s67, s24
	s_cselect_b32 s25, s43, s70
	s_cselect_b32 s24, s68, s69
	s_add_i32 s72, 0, 0x10000
	v_add_u32_e32 v0, s72, v144
	s_add_i32 s74, 0, 0x14000
	ds_read_b128 v[146:149], v0
	ds_read_b128 v[150:153], v0 offset:1024
	ds_read_b128 v[154:157], v0 offset:2048
	ds_read_b128 v[158:161], v0 offset:3072
	v_add_u32_e32 v0, s74, v144
	ds_read_b128 v[162:165], v0
	ds_read_b128 v[166:169], v0 offset:1024
	ds_read_b128 v[170:173], v0 offset:2048
	ds_read_b128 v[174:177], v0 offset:3072
	v_lshl_add_u64 v[210:211], s[0:1], 0, v[138:139]
	s_add_i32 m0, s59, 0xc000
	ds_read_b128 v[178:181], v145
	ds_read_b128 v[182:185], v145 offset:1024
	ds_read_b128 v[186:189], v145 offset:2048
	ds_read_b128 v[190:193], v145 offset:3072
	ds_read_b128 v[194:197], v145 offset:4096
	ds_read_b128 v[198:201], v145 offset:5120
	ds_read_b128 v[202:205], v145 offset:6144
	ds_read_b128 v[206:209], v145 offset:7168
	global_load_lds_dwordx4 v[210:211], off
	v_lshl_add_u64 v[210:211], s[0:1], 0, v[140:141]
	s_add_i32 m0, s59, 0xe000
	s_nop 0
	global_load_lds_dwordx4 v[210:211], off
	s_waitcnt vmcnt(8)
	s_waitcnt lgkmcnt(0)
	s_barrier
	s_waitcnt lgkmcnt(0)
	v_mfma_f32_16x16x32_bf16 v[126:129], v[146:149], v[178:181], v[126:129]
	v_mfma_f32_16x16x32_bf16 v[122:125], v[154:157], v[178:181], v[122:125]
	v_mfma_f32_16x16x32_bf16 v[110:113], v[146:149], v[186:189], v[110:113]
	v_mfma_f32_16x16x32_bf16 v[106:109], v[154:157], v[186:189], v[106:109]
	v_mfma_f32_16x16x32_bf16 v[94:97], v[146:149], v[194:197], v[94:97]
	v_mfma_f32_16x16x32_bf16 v[90:93], v[154:157], v[194:197], v[90:93]
	v_mfma_f32_16x16x32_bf16 v[78:81], v[146:149], v[202:205], v[78:81]
	v_mfma_f32_16x16x32_bf16 v[74:77], v[154:157], v[202:205], v[74:77]
	v_mfma_f32_16x16x32_bf16 v[126:129], v[150:153], v[182:185], v[126:129]
	v_mfma_f32_16x16x32_bf16 v[122:125], v[158:161], v[182:185], v[122:125]
	v_mfma_f32_16x16x32_bf16 v[110:113], v[150:153], v[190:193], v[110:113]
	v_mfma_f32_16x16x32_bf16 v[106:109], v[158:161], v[190:193], v[106:109]
	v_mfma_f32_16x16x32_bf16 v[94:97], v[150:153], v[198:201], v[94:97]
	v_mfma_f32_16x16x32_bf16 v[90:93], v[158:161], v[198:201], v[90:93]
	v_mfma_f32_16x16x32_bf16 v[78:81], v[150:153], v[206:209], v[78:81]
	v_mfma_f32_16x16x32_bf16 v[74:77], v[158:161], v[206:209], v[74:77]
	v_mfma_f32_16x16x32_bf16 v[118:121], v[162:165], v[178:181], v[118:121]
	v_mfma_f32_16x16x32_bf16 v[114:117], v[170:173], v[178:181], v[114:117]
	v_mfma_f32_16x16x32_bf16 v[102:105], v[162:165], v[186:189], v[102:105]
	v_mfma_f32_16x16x32_bf16 v[98:101], v[170:173], v[186:189], v[98:101]
	v_mfma_f32_16x16x32_bf16 v[86:89], v[162:165], v[194:197], v[86:89]
	v_mfma_f32_16x16x32_bf16 v[82:85], v[170:173], v[194:197], v[82:85]
	v_mfma_f32_16x16x32_bf16 v[70:73], v[162:165], v[202:205], v[70:73]
	v_mfma_f32_16x16x32_bf16 v[66:69], v[170:173], v[202:205], v[66:69]
	v_mfma_f32_16x16x32_bf16 v[118:121], v[166:169], v[182:185], v[118:121]
	v_mfma_f32_16x16x32_bf16 v[114:117], v[174:177], v[182:185], v[114:117]
	v_mfma_f32_16x16x32_bf16 v[102:105], v[166:169], v[190:193], v[102:105]
	v_mfma_f32_16x16x32_bf16 v[98:101], v[174:177], v[190:193], v[98:101]
	v_mfma_f32_16x16x32_bf16 v[86:89], v[166:169], v[198:201], v[86:89]
	v_mfma_f32_16x16x32_bf16 v[82:85], v[174:177], v[198:201], v[82:85]
	v_mfma_f32_16x16x32_bf16 v[70:73], v[166:169], v[206:209], v[70:73]
	v_mfma_f32_16x16x32_bf16 v[66:69], v[174:177], v[206:209], v[66:69]
	s_barrier
	s_add_i32 s72, s72, s55
	v_lshl_add_u64 v[210:211], s[24:25], 0, v[134:135]
	s_mov_b32 m0, s72
	ds_read_b128 v[178:181], v145 offset:16384
	ds_read_b128 v[182:185], v145 offset:17408
	ds_read_b128 v[186:189], v145 offset:18432
	ds_read_b128 v[190:193], v145 offset:19456
	ds_read_b128 v[194:197], v145 offset:20480
	ds_read_b128 v[198:201], v145 offset:21504
	ds_read_b128 v[202:205], v145 offset:22528
	ds_read_b128 v[206:209], v145 offset:23552
	global_load_lds_dwordx4 v[210:211], off
	s_add_i32 m0, s72, 0x2000
	s_add_u32 s72, s24, 0x40000
	v_lshl_add_u64 v[212:213], s[24:25], 0, v[130:131]
	s_addc_u32 s73, s25, 0
	s_add_i32 s74, s74, s55
	global_load_lds_dwordx4 v[212:213], off
	v_lshl_add_u64 v[214:215], s[72:73], 0, v[134:135]
	s_mov_b32 m0, s74
	v_lshl_add_u64 v[230:231], s[34:35], 0, v[132:133]
	global_load_lds_dwordx4 v[214:215], off
	v_lshl_add_u64 v[214:215], s[72:73], 0, v[130:131]
	s_add_i32 m0, s74, 0x2000
	s_nop 0
	global_load_lds_dwordx4 v[214:215], off
	v_lshl_add_u64 v[214:215], s[34:35], 0, v[136:137]
	s_mov_b32 m0, s59
	s_nop 0
	global_load_lds_dwordx4 v[214:215], off
	s_mov_b32 m0, s9
	s_nop 0
	global_load_lds_dwordx4 v[230:231], off
	s_waitcnt vmcnt(8)
	s_waitcnt lgkmcnt(0)
	s_barrier
; #define PG8_STAGE(bufoff, gbase, voff) do { _Pragma("unroll") for (int _i = 0; _i < 2; ++_i) \
;         __builtin_amdgcn_global_load_lds((const unsigned*)((const char*)(gbase) + (voff)[_i]), (LAS unsigned*)(lds + (bufoff) + ldsw + _i * 8192), 16, 0, 0); } while (0)
; #define PG8_LDA(dst, b, h) do { _Pragma("unroll") for (int m = 0; m < 4; ++m) _Pragma("unroll") for (int k = 0; k < 2; ++k) dst[m][k] = *(const LAS bf16x8*)(lds + PG8_SA(b, h) + aoff + m * 2048 + k * 1024); } while (0)
; #define PG8_LDB(dst, b, h) do { _Pragma("unroll") for (int n = 0; n < 2; ++n) _Pragma("unroll") for (int k = 0; k < 2; ++k) dst[n][k] = *(const LAS bf16x8*)(lds + PG8_SB(b, h) + boff + n * 2048 + k * 1024); } while (0)
; #define PG8_MMA(ai, bj, At, Bt) do { __builtin_amdgcn_s_setprio(1); _Pragma("unroll") for (int m = 0; m < 4; ++m) _Pragma("unroll") for (int n = 0; n < 2; ++n) _Pragma("unroll") for (int k = 0; k < 2; ++k) \
;         acc[ai][bj][m][n] = __builtin_amdgcn_mfma_f32_16x16x32_bf16(Bt[n][k], At[m][k], acc[ai][bj][m][n], 0, 0, 0); __builtin_amdgcn_s_setprio(0); } while (0)
; #define PG8_WAIT_V(n) asm volatile("s_waitcnt vmcnt(" #n ")" ::: "memory")
; #define PG8_WAIT_L(n) asm volatile("s_waitcnt lgkmcnt(" #n ")" ::: "memory")
; #define PG8_BAR __builtin_amdgcn_s_barrier()
; #define PG8_SCHED __builtin_amdgcn_sched_barrier(0)
; template <bool HM = false, bool PERM = false, bool CP = false, class Prob, class Epi>
; __device__ __forceinline__ void gemm_phase(LAS unsigned char* lds, const Prob& S, const Epi& E) {
;     ...
;             PG8_WAIT_V(8); PG8_WAIT_L(0); PG8_BAR; if (!HM) { if (!CP || fullu) PG8_MMA(1, 0, At, B0); PG8_MMA(1, 1, At, B1); } PG8_BAR; PG8_SCHED;
;             PG8_LDB(B0, 1, 0); PG8_LDB(B1, 1, 1); PG8_SCHED; PG8_LDA(At, 1, 0); PG8_STAGE(PG8_SA(0, 1), a2 + hstepA, voffA);
;             PG8_WAIT_V(8); PG8_WAIT_L(0); PG8_BAR; if (!CP || fullu) PG8_MMA(0, 0, At, B0); PG8_MMA(0, 1, At, B1); PG8_BAR; PG8_SCHED;
	s_waitcnt lgkmcnt(0)
	v_mfma_f32_16x16x32_bf16 v[62:65], v[146:149], v[178:181], v[62:65]
	v_mfma_f32_16x16x32_bf16 v[58:61], v[154:157], v[178:181], v[58:61]
	v_mfma_f32_16x16x32_bf16 v[46:49], v[146:149], v[186:189], v[46:49]
	v_mfma_f32_16x16x32_bf16 v[42:45], v[154:157], v[186:189], v[42:45]
	v_mfma_f32_16x16x32_bf16 v[30:33], v[146:149], v[194:197], v[30:33]
	v_mfma_f32_16x16x32_bf16 v[26:29], v[154:157], v[194:197], v[26:29]
	v_mfma_f32_16x16x32_bf16 v[14:17], v[146:149], v[202:205], v[14:17]
	v_mfma_f32_16x16x32_bf16 v[10:13], v[154:157], v[202:205], v[10:13]
	v_mfma_f32_16x16x32_bf16 v[62:65], v[150:153], v[182:185], v[62:65]
	v_mfma_f32_16x16x32_bf16 v[58:61], v[158:161], v[182:185], v[58:61]
	v_mfma_f32_16x16x32_bf16 v[46:49], v[150:153], v[190:193], v[46:49]
	v_mfma_f32_16x16x32_bf16 v[42:45], v[158:161], v[190:193], v[42:45]
	v_mfma_f32_16x16x32_bf16 v[30:33], v[150:153], v[198:201], v[30:33]
	v_mfma_f32_16x16x32_bf16 v[26:29], v[158:161], v[198:201], v[26:29]
	v_mfma_f32_16x16x32_bf16 v[14:17], v[150:153], v[206:209], v[14:17]
	v_mfma_f32_16x16x32_bf16 v[10:13], v[158:161], v[206:209], v[10:13]
	v_mfma_f32_16x16x32_bf16 v[54:57], v[162:165], v[178:181], v[54:57]
	v_mfma_f32_16x16x32_bf16 v[50:53], v[170:173], v[178:181], v[50:53]
	v_mfma_f32_16x16x32_bf16 v[38:41], v[162:165], v[186:189], v[38:41]
	v_mfma_f32_16x16x32_bf16 v[34:37], v[170:173], v[186:189], v[34:37]
	v_mfma_f32_16x16x32_bf16 v[22:25], v[162:165], v[194:197], v[22:25]
	v_mfma_f32_16x16x32_bf16 v[18:21], v[170:173], v[194:197], v[18:21]
	v_mfma_f32_16x16x32_bf16 v[6:9], v[162:165], v[202:205], v[6:9]
	v_mfma_f32_16x16x32_bf16 v[2:5], v[170:173], v[202:205], v[2:5]
	v_mfma_f32_16x16x32_bf16 v[54:57], v[166:169], v[182:185], v[54:57]
	v_mfma_f32_16x16x32_bf16 v[50:53], v[174:177], v[182:185], v[50:53]
	v_mfma_f32_16x16x32_bf16 v[38:41], v[166:169], v[190:193], v[38:41]
	v_mfma_f32_16x16x32_bf16 v[34:37], v[174:177], v[190:193], v[34:37]
	v_mfma_f32_16x16x32_bf16 v[22:25], v[166:169], v[198:201], v[22:25]
	v_mfma_f32_16x16x32_bf16 v[18:21], v[174:177], v[198:201], v[18:21]
	v_mfma_f32_16x16x32_bf16 v[6:9], v[166:169], v[206:209], v[6:9]
	v_mfma_f32_16x16x32_bf16 v[2:5], v[174:177], v[206:209], v[2:5]
	s_barrier
	s_add_i32 s72, 0, 0x18000
	v_add_u32_e32 v0, s72, v144
	s_add_i32 s73, 0, 0x1c000
	ds_read_b128 v[146:149], v0
	ds_read_b128 v[150:153], v0 offset:1024
	ds_read_b128 v[154:157], v0 offset:2048
	ds_read_b128 v[158:161], v0 offset:3072
	v_add_u32_e32 v0, s73, v144
	ds_read_b128 v[162:165], v0
	ds_read_b128 v[166:169], v0 offset:1024
	ds_read_b128 v[170:173], v0 offset:2048
	ds_read_b128 v[174:177], v0 offset:3072
	s_add_u32 s34, s34, 0x40000
	s_addc_u32 s35, s35, 0
	s_mov_b32 m0, s60
	v_lshl_add_u64 v[232:233], s[34:35], 0, v[136:137]
	ds_read_b128 v[178:181], v145 offset:32768
	ds_read_b128 v[182:185], v145 offset:33792
	ds_read_b128 v[186:189], v145 offset:34816
	ds_read_b128 v[190:193], v145 offset:35840
	ds_read_b128 v[194:197], v145 offset:36864
	ds_read_b128 v[198:201], v145 offset:37888
	ds_read_b128 v[202:205], v145 offset:38912
	ds_read_b128 v[206:209], v145 offset:39936
	global_load_lds_dwordx4 v[232:233], off
	v_lshl_add_u64 v[232:233], s[34:35], 0, v[132:133]
	s_mov_b32 m0, s61
	s_nop 0
	global_load_lds_dwordx4 v[232:233], off
	s_waitcnt vmcnt(8)
	s_waitcnt lgkmcnt(0)
	s_barrier
	s_waitcnt lgkmcnt(0)
	v_mfma_f32_16x16x32_bf16 v[126:129], v[146:149], v[178:181], v[126:129]
	v_mfma_f32_16x16x32_bf16 v[122:125], v[154:157], v[178:181], v[122:125]
	v_mfma_f32_16x16x32_bf16 v[110:113], v[146:149], v[186:189], v[110:113]
	v_mfma_f32_16x16x32_bf16 v[106:109], v[154:157], v[186:189], v[106:109]
	v_mfma_f32_16x16x32_bf16 v[94:97], v[146:149], v[194:197], v[94:97]
	v_mfma_f32_16x16x32_bf16 v[90:93], v[154:157], v[194:197], v[90:93]
	v_mfma_f32_16x16x32_bf16 v[78:81], v[146:149], v[202:205], v[78:81]
	v_mfma_f32_16x16x32_bf16 v[74:77], v[154:157], v[202:205], v[74:77]
	v_mfma_f32_16x16x32_bf16 v[126:129], v[150:153], v[182:185], v[126:129]
	v_mfma_f32_16x16x32_bf16 v[122:125], v[158:161], v[182:185], v[122:125]
	v_mfma_f32_16x16x32_bf16 v[110:113], v[150:153], v[190:193], v[110:113]
	v_mfma_f32_16x16x32_bf16 v[106:109], v[158:161], v[190:193], v[106:109]
	v_mfma_f32_16x16x32_bf16 v[94:97], v[150:153], v[198:201], v[94:97]
	v_mfma_f32_16x16x32_bf16 v[90:93], v[158:161], v[198:201], v[90:93]
	v_mfma_f32_16x16x32_bf16 v[78:81], v[150:153], v[206:209], v[78:81]
	v_mfma_f32_16x16x32_bf16 v[74:77], v[158:161], v[206:209], v[74:77]
	v_mfma_f32_16x16x32_bf16 v[118:121], v[162:165], v[178:181], v[118:121]
	v_mfma_f32_16x16x32_bf16 v[114:117], v[170:173], v[178:181], v[114:117]
	v_mfma_f32_16x16x32_bf16 v[102:105], v[162:165], v[186:189], v[102:105]
	v_mfma_f32_16x16x32_bf16 v[98:101], v[170:173], v[186:189], v[98:101]
	v_mfma_f32_16x16x32_bf16 v[86:89], v[162:165], v[194:197], v[86:89]
	v_mfma_f32_16x16x32_bf16 v[82:85], v[170:173], v[194:197], v[82:85]
	v_mfma_f32_16x16x32_bf16 v[70:73], v[162:165], v[202:205], v[70:73]
	v_mfma_f32_16x16x32_bf16 v[66:69], v[170:173], v[202:205], v[66:69]
	v_mfma_f32_16x16x32_bf16 v[118:121], v[166:169], v[182:185], v[118:121]
	v_mfma_f32_16x16x32_bf16 v[114:117], v[174:177], v[182:185], v[114:117]
	v_mfma_f32_16x16x32_bf16 v[102:105], v[166:169], v[190:193], v[102:105]
	v_mfma_f32_16x16x32_bf16 v[98:101], v[174:177], v[190:193], v[98:101]
	v_mfma_f32_16x16x32_bf16 v[86:89], v[166:169], v[198:201], v[86:89]
	v_mfma_f32_16x16x32_bf16 v[82:85], v[174:177], v[198:201], v[82:85]
	v_mfma_f32_16x16x32_bf16 v[70:73], v[166:169], v[206:209], v[70:73]
	v_mfma_f32_16x16x32_bf16 v[66:69], v[174:177], v[206:209], v[66:69]
	s_barrier
; #define PG8_STAGE(bufoff, gbase, voff) do { _Pragma("unroll") for (int _i = 0; _i < 2; ++_i) \
;         __builtin_amdgcn_global_load_lds((const unsigned*)((const char*)(gbase) + (voff)[_i]), (LAS unsigned*)(lds + (bufoff) + ldsw + _i * 8192), 16, 0, 0); } while (0)
; #define PG8_LDA(dst, b, h) do { _Pragma("unroll") for (int m = 0; m < 4; ++m) _Pragma("unroll") for (int k = 0; k < 2; ++k) dst[m][k] = *(const LAS bf16x8*)(lds + PG8_SA(b, h) + aoff + m * 2048 + k * 1024); } while (0)
; #define PG8_MMA(ai, bj, At, Bt) do { __builtin_amdgcn_s_setprio(1); _Pragma("unroll") for (int m = 0; m < 4; ++m) _Pragma("unroll") for (int n = 0; n < 2; ++n) _Pragma("unroll") for (int k = 0; k < 2; ++k) \
;         acc[ai][bj][m][n] = __builtin_amdgcn_mfma_f32_16x16x32_bf16(Bt[n][k], At[m][k], acc[ai][bj][m][n], 0, 0, 0); __builtin_amdgcn_s_setprio(0); } while (0)
; #define PG8_WAIT_V(n) asm volatile("s_waitcnt vmcnt(" #n ")" ::: "memory")
; #define PG8_WAIT_L(n) asm volatile("s_waitcnt lgkmcnt(" #n ")" ::: "memory")
; #define PG8_BAR __builtin_amdgcn_s_barrier()
; #define PG8_SCHED __builtin_amdgcn_sched_barrier(0)
; template <bool HM = false, bool PERM = false, bool CP = false, class Prob, class Epi>
; __device__ __forceinline__ void gemm_phase(LAS unsigned char* lds, const Prob& S, const Epi& E) {
;     ...
;         for (int t = 0; t < nt; t += 2) {
;     ...
;             if (!HM) PG8_LDA(At, 1, 1); PG8_STAGE(PG8_SB(1, 0), b3, voffB); PG8_STAGE(PG8_SB(1, 1), b3 + h2, voffB); PG8_STAGE(PG8_SA(1, 0), a3, voffA);
;             PG8_WAIT_V(8); PG8_WAIT_L(0); PG8_BAR; if (!HM) { if (!CP || fullu) PG8_MMA(1, 0, At, B0); PG8_MMA(1, 1, At, B1); } PG8_BAR; PG8_SCHED;
	s_add_i32 s34, s72, s55
	v_lshl_add_u64 v[210:211], v[210:211], 0, s[20:21]
	s_mov_b32 m0, s34
	ds_read_b128 v[178:181], v145 offset:49152
	ds_read_b128 v[182:185], v145 offset:50176
	ds_read_b128 v[186:189], v145 offset:51200
	ds_read_b128 v[190:193], v145 offset:52224
	ds_read_b128 v[194:197], v145 offset:53248
	ds_read_b128 v[198:201], v145 offset:54272
	ds_read_b128 v[202:205], v145 offset:55296
	ds_read_b128 v[206:209], v145 offset:56320
	global_load_lds_dwordx4 v[210:211], off
	s_add_i32 m0, s34, 0x2000
	s_add_u32 s24, s24, 0x40080
	v_lshl_add_u64 v[210:211], v[212:213], 0, s[20:21]
	s_addc_u32 s25, s25, 0
	s_add_i32 s34, s73, s55
	global_load_lds_dwordx4 v[210:211], off
	v_lshl_add_u64 v[210:211], s[24:25], 0, v[134:135]
	s_mov_b32 m0, s34
	s_nop 0
	global_load_lds_dwordx4 v[210:211], off
	v_lshl_add_u64 v[210:211], s[24:25], 0, v[130:131]
	s_add_i32 m0, s34, 0x2000
	s_nop 0
	global_load_lds_dwordx4 v[210:211], off
	v_lshl_add_u64 v[210:211], v[214:215], 0, s[20:21]
	s_mov_b32 m0, s63
	s_nop 0
	global_load_lds_dwordx4 v[210:211], off
	v_lshl_add_u64 v[210:211], v[230:231], 0, s[20:21]
	s_mov_b32 m0, s64
	s_nop 0
	global_load_lds_dwordx4 v[210:211], off
	s_waitcnt vmcnt(8)
	s_waitcnt lgkmcnt(0)
	s_barrier
	s_waitcnt lgkmcnt(0)
	v_mfma_f32_16x16x32_bf16 v[62:65], v[146:149], v[178:181], v[62:65]
	v_mfma_f32_16x16x32_bf16 v[58:61], v[154:157], v[178:181], v[58:61]
	v_mfma_f32_16x16x32_bf16 v[46:49], v[146:149], v[186:189], v[46:49]
	v_mfma_f32_16x16x32_bf16 v[42:45], v[154:157], v[186:189], v[42:45]
	v_mfma_f32_16x16x32_bf16 v[30:33], v[146:149], v[194:197], v[30:33]
	v_mfma_f32_16x16x32_bf16 v[26:29], v[154:157], v[194:197], v[26:29]
	v_mfma_f32_16x16x32_bf16 v[14:17], v[146:149], v[202:205], v[14:17]
	v_mfma_f32_16x16x32_bf16 v[10:13], v[154:157], v[202:205], v[10:13]
	v_mfma_f32_16x16x32_bf16 v[62:65], v[150:153], v[182:185], v[62:65]
	v_mfma_f32_16x16x32_bf16 v[58:61], v[158:161], v[182:185], v[58:61]
	v_mfma_f32_16x16x32_bf16 v[46:49], v[150:153], v[190:193], v[46:49]
	v_mfma_f32_16x16x32_bf16 v[42:45], v[158:161], v[190:193], v[42:45]
	v_mfma_f32_16x16x32_bf16 v[30:33], v[150:153], v[198:201], v[30:33]
	v_mfma_f32_16x16x32_bf16 v[26:29], v[158:161], v[198:201], v[26:29]
	v_mfma_f32_16x16x32_bf16 v[14:17], v[150:153], v[206:209], v[14:17]
	v_mfma_f32_16x16x32_bf16 v[10:13], v[158:161], v[206:209], v[10:13]
	v_mfma_f32_16x16x32_bf16 v[54:57], v[162:165], v[178:181], v[54:57]
	v_mfma_f32_16x16x32_bf16 v[50:53], v[170:173], v[178:181], v[50:53]
	v_mfma_f32_16x16x32_bf16 v[38:41], v[162:165], v[186:189], v[38:41]
	v_mfma_f32_16x16x32_bf16 v[34:37], v[170:173], v[186:189], v[34:37]
	v_mfma_f32_16x16x32_bf16 v[22:25], v[162:165], v[194:197], v[22:25]
	v_mfma_f32_16x16x32_bf16 v[18:21], v[170:173], v[194:197], v[18:21]
	v_mfma_f32_16x16x32_bf16 v[6:9], v[162:165], v[202:205], v[6:9]
	v_mfma_f32_16x16x32_bf16 v[2:5], v[170:173], v[202:205], v[2:5]
	v_mfma_f32_16x16x32_bf16 v[54:57], v[166:169], v[182:185], v[54:57]
	v_mfma_f32_16x16x32_bf16 v[50:53], v[174:177], v[182:185], v[50:53]
	v_mfma_f32_16x16x32_bf16 v[38:41], v[166:169], v[190:193], v[38:41]
	v_mfma_f32_16x16x32_bf16 v[34:37], v[174:177], v[190:193], v[34:37]
	v_mfma_f32_16x16x32_bf16 v[22:25], v[166:169], v[198:201], v[22:25]
	v_mfma_f32_16x16x32_bf16 v[18:21], v[174:177], v[198:201], v[18:21]
	v_mfma_f32_16x16x32_bf16 v[6:9], v[166:169], v[206:209], v[6:9]
	v_mfma_f32_16x16x32_bf16 v[2:5], v[174:177], v[206:209], v[2:5]
	s_barrier
	s_add_i32 s71, s71, 2
	s_add_u32 s0, s0, 0x100
	s_addc_u32 s1, s1, 0
	s_add_u32 s69, s69, 0x100
	s_addc_u32 s70, s70, 0
	s_cmp_gt_u32 s71, 13
	s_cbranch_scc0 .LBB0_1224
	s_and_b64 vcc, exec, s[38:39]
	s_cbranch_vccz .LBB0_1227
	s_barrier

; #define PG8_STAGE(bufoff, gbase, voff) do { _Pragma("unroll") for (int _i = 0; _i < 2; ++_i) \
;         __builtin_amdgcn_global_load_lds((const unsigned*)((const char*)(gbase) + (voff)[_i]), (LAS unsigned*)(lds + (bufoff) + ldsw + _i * 8192), 16, 0, 0); } while (0)
; #define PG8_LDA(dst, b, h) do { _Pragma("unroll") for (int m = 0; m < 4; ++m) _Pragma("unroll") for (int k = 0; k < 2; ++k) dst[m][k] = *(const LAS bf16x8*)(lds + PG8_SA(b, h) + aoff + m * 2048 + k * 1024); } while (0)
; #define PG8_LDB(dst, b, h) do { _Pragma("unroll") for (int n = 0; n < 2; ++n) _Pragma("unroll") for (int k = 0; k < 2; ++k) dst[n][k] = *(const LAS bf16x8*)(lds + PG8_SB(b, h) + boff + n * 2048 + k * 1024); } while (0)
; #define PG8_BAR __builtin_amdgcn_s_barrier()
; template <bool HM = false, bool PERM = false, bool CP = false, class Prob, class Epi>
; __device__ __forceinline__ void gemm_phase(LAS unsigned char* lds, const Prob& S, const Epi& E) {
;     ...
;             const char* a1 = cA + (size_t)(t + 1) * kstepA;
;             const char* a2 = last ? nA : cA + (size_t)(t + 2) * kstepA; const char* b2 = last ? nB : cB + (size_t)(t + 2) * kstepB;
;             const char* a3 = a2 + kstepA; const char* b3 = b2 + kstepB; const long h2 = last ? nhB : chB;
;     ...
;             PG8_LDB(B0, 0, 0); PG8_LDB(B1, 0, 1); PG8_SCHED; PG8_LDA(At, 0, 0); PG8_STAGE(PG8_SA(1, 1), a1 + hstepA, voffA);
;             PG8_WAIT_V(8); PG8_WAIT_L(0); PG8_BAR; if (!CP || fullu) PG8_MMA(0, 0, At, B0); PG8_MMA(0, 1, At, B1); PG8_BAR; PG8_SCHED;
;             if (!HM) PG8_LDA(At, 0, 1); PG8_STAGE(PG8_SB(0, 0), b2, voffB); PG8_STAGE(PG8_SB(0, 1), b2 + h2, voffB); PG8_STAGE(PG8_SA(0, 0), a2, voffA);
;             PG8_WAIT_V(8); PG8_WAIT_L(0); PG8_BAR; if (!HM) { if (!CP || fullu) PG8_MMA(1, 0, At, B0); PG8_MMA(1, 1, At, B1); } PG8_BAR; PG8_SCHED;
;             PG8_LDB(B0, 1, 0); PG8_LDB(B1, 1, 1); PG8_SCHED; PG8_LDA(At, 1, 0); PG8_STAGE(PG8_SA(0, 1), a2 + hstepA, voffA);
;             PG8_WAIT_V(8); PG8_WAIT_L(0); PG8_BAR; if (!CP || fullu) PG8_MMA(0, 0, At, B0); PG8_MMA(0, 1, At, B1); PG8_BAR; PG8_SCHED;
;             if (!HM) PG8_LDA(At, 1, 1); PG8_STAGE(PG8_SB(1, 0), b3, voffB); PG8_STAGE(PG8_SB(1, 1), b3 + h2, voffB); PG8_STAGE(PG8_SA(1, 0), a3, voffA);
;             PG8_WAIT_V(8); PG8_WAIT_L(0); PG8_BAR; if (!HM) { if (!CP || fullu) PG8_MMA(1, 0, At, B0); PG8_MMA(1, 1, At, B1); } PG8_BAR; PG8_SCHED;
.LBB0_1356:
	s_add_i32 s5, s5, 2
	s_and_b64 s[34:35], exec, s[34:35]
	s_cselect_b32 s59, s37, s79
	s_cselect_b32 s58, s36, s49
	s_add_u32 s34, s24, 0x440000
	s_addc_u32 s35, s25, 0
	s_add_i32 s80, 0, 0x10000
	v_add_u32_e32 v140, s80, v144
	s_add_i32 s82, 0, 0x14000
	ds_read_b128 v[136:139], v140
	ds_read_b128 v[146:149], v140 offset:1024
	ds_read_b128 v[150:153], v140 offset:2048
	ds_read_b128 v[154:157], v140 offset:3072
	v_add_u32_e32 v140, s82, v144
	ds_read_b128 v[158:161], v140
	ds_read_b128 v[162:165], v140 offset:1024
	ds_read_b128 v[166:169], v140 offset:2048
	ds_read_b128 v[170:173], v140 offset:3072
	v_lshl_add_u64 v[140:141], s[8:9], 0, v[132:133]
	s_add_i32 m0, s47, 0xc000
	ds_read_b128 v[174:177], v145
	ds_read_b128 v[178:181], v145 offset:1024
	ds_read_b128 v[182:185], v145 offset:2048
	ds_read_b128 v[186:189], v145 offset:3072
	ds_read_b128 v[190:193], v145 offset:4096
	ds_read_b128 v[194:197], v145 offset:5120
	ds_read_b128 v[198:201], v145 offset:6144
	ds_read_b128 v[202:205], v145 offset:7168
	global_load_lds_dwordx4 v[140:141], off
	v_lshl_add_u64 v[140:141], s[8:9], 0, v[134:135]
	s_add_i32 m0, s47, 0xe000
	s_nop 0
	global_load_lds_dwordx4 v[140:141], off
	s_waitcnt vmcnt(8)
	s_waitcnt lgkmcnt(0)
	s_barrier
	s_waitcnt lgkmcnt(0)
	v_mfma_f32_16x16x32_bf16 v[126:129], v[136:139], v[174:177], v[126:129]
	v_mfma_f32_16x16x32_bf16 v[122:125], v[150:153], v[174:177], v[122:125]
	v_mfma_f32_16x16x32_bf16 v[110:113], v[136:139], v[182:185], v[110:113]
	v_mfma_f32_16x16x32_bf16 v[106:109], v[150:153], v[182:185], v[106:109]
	v_mfma_f32_16x16x32_bf16 v[94:97], v[136:139], v[190:193], v[94:97]
	v_mfma_f32_16x16x32_bf16 v[90:93], v[150:153], v[190:193], v[90:93]
	v_mfma_f32_16x16x32_bf16 v[78:81], v[136:139], v[198:201], v[78:81]
	v_mfma_f32_16x16x32_bf16 v[74:77], v[150:153], v[198:201], v[74:77]
	v_mfma_f32_16x16x32_bf16 v[126:129], v[146:149], v[178:181], v[126:129]
	v_mfma_f32_16x16x32_bf16 v[122:125], v[154:157], v[178:181], v[122:125]
	v_mfma_f32_16x16x32_bf16 v[110:113], v[146:149], v[186:189], v[110:113]
	v_mfma_f32_16x16x32_bf16 v[106:109], v[154:157], v[186:189], v[106:109]
	v_mfma_f32_16x16x32_bf16 v[94:97], v[146:149], v[194:197], v[94:97]
	v_mfma_f32_16x16x32_bf16 v[90:93], v[154:157], v[194:197], v[90:93]
	v_mfma_f32_16x16x32_bf16 v[78:81], v[146:149], v[202:205], v[78:81]
	v_mfma_f32_16x16x32_bf16 v[74:77], v[154:157], v[202:205], v[74:77]
	v_mfma_f32_16x16x32_bf16 v[118:121], v[158:161], v[174:177], v[118:121]
	v_mfma_f32_16x16x32_bf16 v[114:117], v[166:169], v[174:177], v[114:117]
	v_mfma_f32_16x16x32_bf16 v[102:105], v[158:161], v[182:185], v[102:105]
	v_mfma_f32_16x16x32_bf16 v[98:101], v[166:169], v[182:185], v[98:101]
	v_mfma_f32_16x16x32_bf16 v[86:89], v[158:161], v[190:193], v[86:89]
	v_mfma_f32_16x16x32_bf16 v[82:85], v[166:169], v[190:193], v[82:85]
	v_mfma_f32_16x16x32_bf16 v[70:73], v[158:161], v[198:201], v[70:73]
	v_mfma_f32_16x16x32_bf16 v[66:69], v[166:169], v[198:201], v[66:69]
	v_mfma_f32_16x16x32_bf16 v[118:121], v[162:165], v[178:181], v[118:121]
	v_mfma_f32_16x16x32_bf16 v[114:117], v[170:173], v[178:181], v[114:117]
	v_mfma_f32_16x16x32_bf16 v[102:105], v[162:165], v[186:189], v[102:105]
	v_mfma_f32_16x16x32_bf16 v[98:101], v[170:173], v[186:189], v[98:101]
	v_mfma_f32_16x16x32_bf16 v[86:89], v[162:165], v[194:197], v[86:89]
	v_mfma_f32_16x16x32_bf16 v[82:85], v[170:173], v[194:197], v[82:85]
	v_mfma_f32_16x16x32_bf16 v[70:73], v[162:165], v[202:205], v[70:73]
	v_mfma_f32_16x16x32_bf16 v[66:69], v[170:173], v[202:205], v[66:69]
	s_barrier
	s_add_i32 s80, s80, s70
	v_lshl_add_u64 v[140:141], s[58:59], 0, v[0:1]
	s_mov_b32 m0, s80
	ds_read_b128 v[174:177], v145 offset:16384
	ds_read_b128 v[178:181], v145 offset:17408
	ds_read_b128 v[182:185], v145 offset:18432
	ds_read_b128 v[186:189], v145 offset:19456
	ds_read_b128 v[190:193], v145 offset:20480
	ds_read_b128 v[194:197], v145 offset:21504
	ds_read_b128 v[198:201], v145 offset:22528
	ds_read_b128 v[202:205], v145 offset:23552
	global_load_lds_dwordx4 v[140:141], off
	s_add_i32 m0, s80, 0x2000
	s_add_u32 s80, s58, 0x4000
	v_lshl_add_u64 v[140:141], s[58:59], 0, v[130:131]
	s_addc_u32 s81, s59, 0
	s_add_i32 s82, s82, s70
	global_load_lds_dwordx4 v[140:141], off
	v_lshl_add_u64 v[140:141], s[80:81], 0, v[0:1]
	s_mov_b32 m0, s82
	s_nop 0
	global_load_lds_dwordx4 v[140:141], off
	v_lshl_add_u64 v[140:141], s[80:81], 0, v[130:131]
	s_add_i32 m0, s82, 0x2000
	s_nop 0
	global_load_lds_dwordx4 v[140:141], off
	v_lshl_add_u64 v[140:141], s[24:25], 0, v[0:1]
	s_mov_b32 m0, s47
	s_nop 0
	global_load_lds_dwordx4 v[140:141], off
	v_lshl_add_u64 v[140:141], s[24:25], 0, v[130:131]
	s_mov_b32 m0, s71
	s_nop 0
	global_load_lds_dwordx4 v[140:141], off
	s_waitcnt vmcnt(8)
	s_waitcnt lgkmcnt(0)
	s_barrier
; #define PG8_STAGE(bufoff, gbase, voff) do { _Pragma("unroll") for (int _i = 0; _i < 2; ++_i) \
;         __builtin_amdgcn_global_load_lds((const unsigned*)((const char*)(gbase) + (voff)[_i]), (LAS unsigned*)(lds + (bufoff) + ldsw + _i * 8192), 16, 0, 0); } while (0)
; #define PG8_LDA(dst, b, h) do { _Pragma("unroll") for (int m = 0; m < 4; ++m) _Pragma("unroll") for (int k = 0; k < 2; ++k) dst[m][k] = *(const LAS bf16x8*)(lds + PG8_SA(b, h) + aoff + m * 2048 + k * 1024); } while (0)
; #define PG8_LDB(dst, b, h) do { _Pragma("unroll") for (int n = 0; n < 2; ++n) _Pragma("unroll") for (int k = 0; k < 2; ++k) dst[n][k] = *(const LAS bf16x8*)(lds + PG8_SB(b, h) + boff + n * 2048 + k * 1024); } while (0)
; #define PG8_BAR __builtin_amdgcn_s_barrier()
; template <bool HM = false, bool PERM = false, bool CP = false, class Prob, class Epi>
; __device__ __forceinline__ void gemm_phase(LAS unsigned char* lds, const Prob& S, const Epi& E) {
;     ...
;             const char* a1 = cA + (size_t)(t + 1) * kstepA;
;             const char* a2 = last ? nA : cA + (size_t)(t + 2) * kstepA; const char* b2 = last ? nB : cB + (size_t)(t + 2) * kstepB;
;             const char* a3 = a2 + kstepA; const char* b3 = b2 + kstepB; const long h2 = last ? nhB : chB;
;     ...
;             PG8_LDB(B0, 0, 0); PG8_LDB(B1, 0, 1); PG8_SCHED; PG8_LDA(At, 0, 0); PG8_STAGE(PG8_SA(1, 1), a1 + hstepA, voffA);
;             PG8_WAIT_V(8); PG8_WAIT_L(0); PG8_BAR; if (!CP || fullu) PG8_MMA(0, 0, At, B0); PG8_MMA(0, 1, At, B1); PG8_BAR; PG8_SCHED;
;             if (!HM) PG8_LDA(At, 0, 1); PG8_STAGE(PG8_SB(0, 0), b2, voffB); PG8_STAGE(PG8_SB(0, 1), b2 + h2, voffB); PG8_STAGE(PG8_SA(0, 0), a2, voffA);
;             PG8_WAIT_V(8); PG8_WAIT_L(0); PG8_BAR; if (!HM) { if (!CP || fullu) PG8_MMA(1, 0, At, B0); PG8_MMA(1, 1, At, B1); } PG8_BAR; PG8_SCHED;
;             PG8_LDB(B0, 1, 0); PG8_LDB(B1, 1, 1); PG8_SCHED; PG8_LDA(At, 1, 0); PG8_STAGE(PG8_SA(0, 1), a2 + hstepA, voffA);
;             PG8_WAIT_V(8); PG8_WAIT_L(0); PG8_BAR; if (!CP || fullu) PG8_MMA(0, 0, At, B0); PG8_MMA(0, 1, At, B1); PG8_BAR; PG8_SCHED;
;             if (!HM) PG8_LDA(At, 1, 1); PG8_STAGE(PG8_SB(1, 0), b3, voffB); PG8_STAGE(PG8_SB(1, 1), b3 + h2, voffB); PG8_STAGE(PG8_SA(1, 0), a3, voffA);
;             PG8_WAIT_V(8); PG8_WAIT_L(0); PG8_BAR; if (!HM) { if (!CP || fullu) PG8_MMA(1, 0, At, B0); PG8_MMA(1, 1, At, B1); } PG8_BAR; PG8_SCHED;
	s_waitcnt lgkmcnt(0)
	v_mfma_f32_16x16x32_bf16 v[62:65], v[136:139], v[174:177], v[62:65]
	v_mfma_f32_16x16x32_bf16 v[58:61], v[150:153], v[174:177], v[58:61]
	v_mfma_f32_16x16x32_bf16 v[46:49], v[136:139], v[182:185], v[46:49]
	v_mfma_f32_16x16x32_bf16 v[42:45], v[150:153], v[182:185], v[42:45]
	v_mfma_f32_16x16x32_bf16 v[30:33], v[136:139], v[190:193], v[30:33]
	v_mfma_f32_16x16x32_bf16 v[26:29], v[150:153], v[190:193], v[26:29]
	v_mfma_f32_16x16x32_bf16 v[14:17], v[136:139], v[198:201], v[14:17]
	v_mfma_f32_16x16x32_bf16 v[10:13], v[150:153], v[198:201], v[10:13]
	v_mfma_f32_16x16x32_bf16 v[62:65], v[146:149], v[178:181], v[62:65]
	v_mfma_f32_16x16x32_bf16 v[58:61], v[154:157], v[178:181], v[58:61]
	v_mfma_f32_16x16x32_bf16 v[46:49], v[146:149], v[186:189], v[46:49]
	v_mfma_f32_16x16x32_bf16 v[42:45], v[154:157], v[186:189], v[42:45]
	v_mfma_f32_16x16x32_bf16 v[30:33], v[146:149], v[194:197], v[30:33]
	v_mfma_f32_16x16x32_bf16 v[26:29], v[154:157], v[194:197], v[26:29]
	v_mfma_f32_16x16x32_bf16 v[14:17], v[146:149], v[202:205], v[14:17]
	v_mfma_f32_16x16x32_bf16 v[10:13], v[154:157], v[202:205], v[10:13]
	v_mfma_f32_16x16x32_bf16 v[54:57], v[158:161], v[174:177], v[54:57]
	v_mfma_f32_16x16x32_bf16 v[50:53], v[166:169], v[174:177], v[50:53]
	v_mfma_f32_16x16x32_bf16 v[38:41], v[158:161], v[182:185], v[38:41]
	v_mfma_f32_16x16x32_bf16 v[34:37], v[166:169], v[182:185], v[34:37]
	v_mfma_f32_16x16x32_bf16 v[22:25], v[158:161], v[190:193], v[22:25]
	v_mfma_f32_16x16x32_bf16 v[18:21], v[166:169], v[190:193], v[18:21]
	v_mfma_f32_16x16x32_bf16 v[6:9], v[158:161], v[198:201], v[6:9]
	v_mfma_f32_16x16x32_bf16 v[2:5], v[166:169], v[198:201], v[2:5]
	v_mfma_f32_16x16x32_bf16 v[54:57], v[162:165], v[178:181], v[54:57]
	v_mfma_f32_16x16x32_bf16 v[50:53], v[170:173], v[178:181], v[50:53]
	v_mfma_f32_16x16x32_bf16 v[38:41], v[162:165], v[186:189], v[38:41]
	v_mfma_f32_16x16x32_bf16 v[34:37], v[170:173], v[186:189], v[34:37]
	v_mfma_f32_16x16x32_bf16 v[22:25], v[162:165], v[194:197], v[22:25]
	v_mfma_f32_16x16x32_bf16 v[18:21], v[170:173], v[194:197], v[18:21]
	v_mfma_f32_16x16x32_bf16 v[6:9], v[162:165], v[202:205], v[6:9]
	v_mfma_f32_16x16x32_bf16 v[2:5], v[170:173], v[202:205], v[2:5]
	s_barrier
	s_add_i32 s80, 0, 0x18000
	v_add_u32_e32 v140, s80, v144
	s_add_i32 s81, 0, 0x1c000
	ds_read_b128 v[136:139], v140
	ds_read_b128 v[146:149], v140 offset:1024
	ds_read_b128 v[150:153], v140 offset:2048
	ds_read_b128 v[154:157], v140 offset:3072
	v_add_u32_e32 v140, s81, v144
	ds_read_b128 v[158:161], v140
	ds_read_b128 v[162:165], v140 offset:1024
	ds_read_b128 v[166:169], v140 offset:2048
	ds_read_b128 v[170:173], v140 offset:3072
	s_add_u32 s24, s24, 0x4000
	s_addc_u32 s25, s25, 0
	s_mov_b32 m0, s72
	v_lshl_add_u64 v[140:141], s[24:25], 0, v[0:1]
	ds_read_b128 v[174:177], v145 offset:32768
	ds_read_b128 v[178:181], v145 offset:33792
	ds_read_b128 v[182:185], v145 offset:34816
	ds_read_b128 v[186:189], v145 offset:35840
	ds_read_b128 v[190:193], v145 offset:36864
	ds_read_b128 v[194:197], v145 offset:37888
	ds_read_b128 v[198:201], v145 offset:38912
	ds_read_b128 v[202:205], v145 offset:39936
	global_load_lds_dwordx4 v[140:141], off
	v_lshl_add_u64 v[140:141], s[24:25], 0, v[130:131]
	s_mov_b32 m0, s73
	s_nop 0
	global_load_lds_dwordx4 v[140:141], off
	s_waitcnt vmcnt(8)
	s_waitcnt lgkmcnt(0)
	s_barrier
	s_waitcnt lgkmcnt(0)
	v_mfma_f32_16x16x32_bf16 v[126:129], v[136:139], v[174:177], v[126:129]
	v_mfma_f32_16x16x32_bf16 v[122:125], v[150:153], v[174:177], v[122:125]
	v_mfma_f32_16x16x32_bf16 v[110:113], v[136:139], v[182:185], v[110:113]
	v_mfma_f32_16x16x32_bf16 v[106:109], v[150:153], v[182:185], v[106:109]
	v_mfma_f32_16x16x32_bf16 v[94:97], v[136:139], v[190:193], v[94:97]
	v_mfma_f32_16x16x32_bf16 v[90:93], v[150:153], v[190:193], v[90:93]
	v_mfma_f32_16x16x32_bf16 v[78:81], v[136:139], v[198:201], v[78:81]
	v_mfma_f32_16x16x32_bf16 v[74:77], v[150:153], v[198:201], v[74:77]
	v_mfma_f32_16x16x32_bf16 v[126:129], v[146:149], v[178:181], v[126:129]
	v_mfma_f32_16x16x32_bf16 v[122:125], v[154:157], v[178:181], v[122:125]
	v_mfma_f32_16x16x32_bf16 v[110:113], v[146:149], v[186:189], v[110:113]
	v_mfma_f32_16x16x32_bf16 v[106:109], v[154:157], v[186:189], v[106:109]
	v_mfma_f32_16x16x32_bf16 v[94:97], v[146:149], v[194:197], v[94:97]
	v_mfma_f32_16x16x32_bf16 v[90:93], v[154:157], v[194:197], v[90:93]
	v_mfma_f32_16x16x32_bf16 v[78:81], v[146:149], v[202:205], v[78:81]
	v_mfma_f32_16x16x32_bf16 v[74:77], v[154:157], v[202:205], v[74:77]
	v_mfma_f32_16x16x32_bf16 v[118:121], v[158:161], v[174:177], v[118:121]
	v_mfma_f32_16x16x32_bf16 v[114:117], v[166:169], v[174:177], v[114:117]
	v_mfma_f32_16x16x32_bf16 v[102:105], v[158:161], v[182:185], v[102:105]
	v_mfma_f32_16x16x32_bf16 v[98:101], v[166:169], v[182:185], v[98:101]
	v_mfma_f32_16x16x32_bf16 v[86:89], v[158:161], v[190:193], v[86:89]
	v_mfma_f32_16x16x32_bf16 v[82:85], v[166:169], v[190:193], v[82:85]
	v_mfma_f32_16x16x32_bf16 v[70:73], v[158:161], v[198:201], v[70:73]
	v_mfma_f32_16x16x32_bf16 v[66:69], v[166:169], v[198:201], v[66:69]
	v_mfma_f32_16x16x32_bf16 v[118:121], v[162:165], v[178:181], v[118:121]
	v_mfma_f32_16x16x32_bf16 v[114:117], v[170:173], v[178:181], v[114:117]
	v_mfma_f32_16x16x32_bf16 v[102:105], v[162:165], v[186:189], v[102:105]
	v_mfma_f32_16x16x32_bf16 v[98:101], v[170:173], v[186:189], v[98:101]
	v_mfma_f32_16x16x32_bf16 v[86:89], v[162:165], v[194:197], v[86:89]
	v_mfma_f32_16x16x32_bf16 v[82:85], v[170:173], v[194:197], v[82:85]
	v_mfma_f32_16x16x32_bf16 v[70:73], v[162:165], v[202:205], v[70:73]
	v_mfma_f32_16x16x32_bf16 v[66:69], v[170:173], v[202:205], v[66:69]
	s_barrier
; #define PG8_STAGE(bufoff, gbase, voff) do { _Pragma("unroll") for (int _i = 0; _i < 2; ++_i) \
;         __builtin_amdgcn_global_load_lds((const unsigned*)((const char*)(gbase) + (voff)[_i]), (LAS unsigned*)(lds + (bufoff) + ldsw + _i * 8192), 16, 0, 0); } while (0)
; #define PG8_LDA(dst, b, h) do { _Pragma("unroll") for (int m = 0; m < 4; ++m) _Pragma("unroll") for (int k = 0; k < 2; ++k) dst[m][k] = *(const LAS bf16x8*)(lds + PG8_SA(b, h) + aoff + m * 2048 + k * 1024); } while (0)
; #define PG8_LDB(dst, b, h) do { _Pragma("unroll") for (int n = 0; n < 2; ++n) _Pragma("unroll") for (int k = 0; k < 2; ++k) dst[n][k] = *(const LAS bf16x8*)(lds + PG8_SB(b, h) + boff + n * 2048 + k * 1024); } while (0)
; #define PG8_MMA(ai, bj, At, Bt) do { __builtin_amdgcn_s_setprio(1); _Pragma("unroll") for (int m = 0; m < 4; ++m) _Pragma("unroll") for (int n = 0; n < 2; ++n) _Pragma("unroll") for (int k = 0; k < 2; ++k) \
;         acc[ai][bj][m][n] = __builtin_amdgcn_mfma_f32_16x16x32_bf16(Bt[n][k], At[m][k], acc[ai][bj][m][n], 0, 0, 0); __builtin_amdgcn_s_setprio(0); } while (0)
; #define PG8_WAIT_V(n) asm volatile("s_waitcnt vmcnt(" #n ")" ::: "memory")
; #define PG8_WAIT_L(n) asm volatile("s_waitcnt lgkmcnt(" #n ")" ::: "memory")
; #define PG8_BAR __builtin_amdgcn_s_barrier()
; template <bool HM = false, bool PERM = false, bool CP = false, class Prob, class Epi>
; __device__ __forceinline__ void gemm_phase(LAS unsigned char* lds, const Prob& S, const Epi& E) {
;     ...
;             if (!HM) PG8_LDA(At, 0, 1); PG8_STAGE(PG8_SB(0, 0), b2, voffB); PG8_STAGE(PG8_SB(0, 1), b2 + h2, voffB); PG8_STAGE(PG8_SA(0, 0), a2, voffA);
;             PG8_WAIT_V(8); PG8_WAIT_L(0); PG8_BAR; if (!HM) { if (!CP || fullu) PG8_MMA(1, 0, At, B0); PG8_MMA(1, 1, At, B1); } PG8_BAR; PG8_SCHED;
;             PG8_LDB(B0, 1, 0); PG8_LDB(B1, 1, 1); PG8_SCHED; PG8_LDA(At, 1, 0); PG8_STAGE(PG8_SA(0, 1), a2 + hstepA, voffA);
;             PG8_WAIT_V(8); PG8_WAIT_L(0); PG8_BAR; if (!CP || fullu) PG8_MMA(0, 0, At, B0); PG8_MMA(0, 1, At, B1); PG8_BAR; PG8_SCHED;
;             if (!HM) PG8_LDA(At, 1, 1); PG8_STAGE(PG8_SB(1, 0), b3, voffB); PG8_STAGE(PG8_SB(1, 1), b3 + h2, voffB); PG8_STAGE(PG8_SA(1, 0), a3, voffA);
;             PG8_WAIT_V(8); PG8_WAIT_L(0); PG8_BAR; if (!HM) { if (!CP || fullu) PG8_MMA(1, 0, At, B0); PG8_MMA(1, 1, At, B1); } PG8_BAR; PG8_SCHED;
	s_add_u32 s24, s58, 0x20000
	s_addc_u32 s25, s59, 0
	s_add_i32 s80, s80, s70
	v_lshl_add_u64 v[140:141], s[24:25], 0, v[0:1]
	s_mov_b32 m0, s80
	ds_read_b128 v[174:177], v145 offset:49152
	ds_read_b128 v[178:181], v145 offset:50176
	ds_read_b128 v[182:185], v145 offset:51200
	ds_read_b128 v[186:189], v145 offset:52224
	ds_read_b128 v[190:193], v145 offset:53248
	ds_read_b128 v[194:197], v145 offset:54272
	ds_read_b128 v[198:201], v145 offset:55296
	ds_read_b128 v[202:205], v145 offset:56320
	global_load_lds_dwordx4 v[140:141], off
	s_add_i32 m0, s80, 0x2000
	v_lshl_add_u64 v[140:141], s[24:25], 0, v[130:131]
	s_add_u32 s24, s58, 0x24000
	s_addc_u32 s25, s59, 0
	s_add_i32 s58, s81, s70
	global_load_lds_dwordx4 v[140:141], off
	v_lshl_add_u64 v[140:141], s[24:25], 0, v[0:1]
	s_mov_b32 m0, s58
	s_nop 0
	global_load_lds_dwordx4 v[140:141], off
	v_lshl_add_u64 v[140:141], s[24:25], 0, v[130:131]
	s_add_i32 m0, s58, 0x2000
	s_nop 0
	global_load_lds_dwordx4 v[140:141], off
	v_lshl_add_u64 v[140:141], s[34:35], 0, v[0:1]
	s_mov_b32 m0, s76
	s_nop 0
	global_load_lds_dwordx4 v[140:141], off
	v_lshl_add_u64 v[140:141], s[34:35], 0, v[130:131]
	s_mov_b32 m0, s77
	s_nop 0
	global_load_lds_dwordx4 v[140:141], off
	s_waitcnt vmcnt(8)
	s_waitcnt lgkmcnt(0)
	s_barrier
	s_waitcnt lgkmcnt(0)
	v_mfma_f32_16x16x32_bf16 v[62:65], v[136:139], v[174:177], v[62:65]
	v_mfma_f32_16x16x32_bf16 v[58:61], v[150:153], v[174:177], v[58:61]
	v_mfma_f32_16x16x32_bf16 v[46:49], v[136:139], v[182:185], v[46:49]
	v_mfma_f32_16x16x32_bf16 v[42:45], v[150:153], v[182:185], v[42:45]
	v_mfma_f32_16x16x32_bf16 v[30:33], v[136:139], v[190:193], v[30:33]
	v_mfma_f32_16x16x32_bf16 v[26:29], v[150:153], v[190:193], v[26:29]
	v_mfma_f32_16x16x32_bf16 v[14:17], v[136:139], v[198:201], v[14:17]
	v_mfma_f32_16x16x32_bf16 v[10:13], v[150:153], v[198:201], v[10:13]
	v_mfma_f32_16x16x32_bf16 v[62:65], v[146:149], v[178:181], v[62:65]
	v_mfma_f32_16x16x32_bf16 v[58:61], v[154:157], v[178:181], v[58:61]
	v_mfma_f32_16x16x32_bf16 v[46:49], v[146:149], v[186:189], v[46:49]
	v_mfma_f32_16x16x32_bf16 v[42:45], v[154:157], v[186:189], v[42:45]
	v_mfma_f32_16x16x32_bf16 v[30:33], v[146:149], v[194:197], v[30:33]
	v_mfma_f32_16x16x32_bf16 v[26:29], v[154:157], v[194:197], v[26:29]
	v_mfma_f32_16x16x32_bf16 v[14:17], v[146:149], v[202:205], v[14:17]
	v_mfma_f32_16x16x32_bf16 v[10:13], v[154:157], v[202:205], v[10:13]
	v_mfma_f32_16x16x32_bf16 v[54:57], v[158:161], v[174:177], v[54:57]
	v_mfma_f32_16x16x32_bf16 v[50:53], v[166:169], v[174:177], v[50:53]
	v_mfma_f32_16x16x32_bf16 v[38:41], v[158:161], v[182:185], v[38:41]
	v_mfma_f32_16x16x32_bf16 v[34:37], v[166:169], v[182:185], v[34:37]
	v_mfma_f32_16x16x32_bf16 v[22:25], v[158:161], v[190:193], v[22:25]
	v_mfma_f32_16x16x32_bf16 v[18:21], v[166:169], v[190:193], v[18:21]
	v_mfma_f32_16x16x32_bf16 v[6:9], v[158:161], v[198:201], v[6:9]
	v_mfma_f32_16x16x32_bf16 v[2:5], v[166:169], v[198:201], v[2:5]
	v_mfma_f32_16x16x32_bf16 v[54:57], v[162:165], v[178:181], v[54:57]
	v_mfma_f32_16x16x32_bf16 v[50:53], v[170:173], v[178:181], v[50:53]
	v_mfma_f32_16x16x32_bf16 v[38:41], v[162:165], v[186:189], v[38:41]
	v_mfma_f32_16x16x32_bf16 v[34:37], v[170:173], v[186:189], v[34:37]
	v_mfma_f32_16x16x32_bf16 v[22:25], v[162:165], v[194:197], v[22:25]
	v_mfma_f32_16x16x32_bf16 v[18:21], v[170:173], v[194:197], v[18:21]
	v_mfma_f32_16x16x32_bf16 v[6:9], v[162:165], v[202:205], v[6:9]
	v_mfma_f32_16x16x32_bf16 v[2:5], v[170:173], v[202:205], v[2:5]
	s_barrier
	s_add_u32 s49, s49, 0x40000
	s_addc_u32 s79, s79, 0
	s_add_u32 s8, s8, 0x880000
	s_addc_u32 s9, s9, 0
	s_cmp_ge_u32 s5, s39
	s_cbranch_scc1 .LBB0_1359

; #define PG8_STAGE(bufoff, gbase, voff) do { _Pragma("unroll") for (int _i = 0; _i < 2; ++_i) \
;         __builtin_amdgcn_global_load_lds((const unsigned*)((const char*)(gbase) + (voff)[_i]), (LAS unsigned*)(lds + (bufoff) + ldsw + _i * 8192), 16, 0, 0); } while (0)
; #define PG8_LDA(dst, b, h) do { _Pragma("unroll") for (int m = 0; m < 4; ++m) _Pragma("unroll") for (int k = 0; k < 2; ++k) dst[m][k] = *(const LAS bf16x8*)(lds + PG8_SA(b, h) + aoff + m * 2048 + k * 1024); } while (0)
; #define PG8_LDB(dst, b, h) do { _Pragma("unroll") for (int n = 0; n < 2; ++n) _Pragma("unroll") for (int k = 0; k < 2; ++k) dst[n][k] = *(const LAS bf16x8*)(lds + PG8_SB(b, h) + boff + n * 2048 + k * 1024); } while (0)
; #define PG8_BAR __builtin_amdgcn_s_barrier()
; template <bool HM = false, bool PERM = false, bool CP = false, class Prob, class Epi>
; __device__ __forceinline__ void gemm_phase(LAS unsigned char* lds, const Prob& S, const Epi& E) {
;     ...
;             const char* a1 = cA + (size_t)(t + 1) * kstepA;
;             const char* a2 = last ? nA : cA + (size_t)(t + 2) * kstepA; const char* b2 = last ? nB : cB + (size_t)(t + 2) * kstepB;
;             const char* a3 = a2 + kstepA; const char* b3 = b2 + kstepB; const long h2 = last ? nhB : chB;
;     ...
;             PG8_LDB(B0, 0, 0); PG8_LDB(B1, 0, 1); PG8_SCHED; PG8_LDA(At, 0, 0); PG8_STAGE(PG8_SA(1, 1), a1 + hstepA, voffA);
;             PG8_WAIT_V(8); PG8_WAIT_L(0); PG8_BAR; if (!CP || fullu) PG8_MMA(0, 0, At, B0); PG8_MMA(0, 1, At, B1); PG8_BAR; PG8_SCHED;
;             if (!HM) PG8_LDA(At, 0, 1); PG8_STAGE(PG8_SB(0, 0), b2, voffB); PG8_STAGE(PG8_SB(0, 1), b2 + h2, voffB); PG8_STAGE(PG8_SA(0, 0), a2, voffA);
;             PG8_WAIT_V(8); PG8_WAIT_L(0); PG8_BAR; if (!HM) { if (!CP || fullu) PG8_MMA(1, 0, At, B0); PG8_MMA(1, 1, At, B1); } PG8_BAR; PG8_SCHED;
;             PG8_LDB(B0, 1, 0); PG8_LDB(B1, 1, 1); PG8_SCHED; PG8_LDA(At, 1, 0); PG8_STAGE(PG8_SA(0, 1), a2 + hstepA, voffA);
;             PG8_WAIT_V(8); PG8_WAIT_L(0); PG8_BAR; if (!CP || fullu) PG8_MMA(0, 0, At, B0); PG8_MMA(0, 1, At, B1); PG8_BAR; PG8_SCHED;
;             if (!HM) PG8_LDA(At, 1, 1); PG8_STAGE(PG8_SB(1, 0), b3, voffB); PG8_STAGE(PG8_SB(1, 1), b3 + h2, voffB); PG8_STAGE(PG8_SA(1, 0), a3, voffA);
;             PG8_WAIT_V(8); PG8_WAIT_L(0); PG8_BAR; if (!HM) { if (!CP || fullu) PG8_MMA(1, 0, At, B0); PG8_MMA(1, 1, At, B1); } PG8_BAR; PG8_SCHED;
.LBB0_1393:
	s_or_b32 s75, s74, 1
	s_add_u32 s58, s46, s58
	s_addc_u32 s59, s47, s59
	s_and_b64 s[34:35], exec, s[34:35]
	s_cselect_b32 s59, s17, s59
	s_cselect_b32 s58, s39, s58
	s_add_u32 s34, s24, 0x440000
	s_addc_u32 s35, s25, 0
	s_add_i32 s78, 0, 0x10000
	s_add_i32 s79, 0, 0x14000
	v_add_u32_e32 v148, s78, v142
	v_add_u32_e32 v164, s79, v142
	ds_read_b128 v[132:135], v148
	ds_read_b128 v[136:139], v148 offset:1024
	ds_read_b128 v[144:147], v148 offset:2048
	ds_read_b128 v[148:151], v148 offset:3072
	ds_read_b128 v[152:155], v164
	ds_read_b128 v[156:159], v164 offset:1024
	ds_read_b128 v[160:163], v164 offset:2048
	ds_read_b128 v[164:167], v164 offset:3072
	s_mul_hi_u32 s77, s75, 0x440000
	s_mul_i32 s75, s75, 0x440000
	s_add_u32 s76, s45, s75
	s_addc_u32 s77, s73, s77
	v_lshl_add_u64 v[200:201], s[76:77], 0, v[0:1]
	s_add_i32 m0, s2, 0xc000
	ds_read_b128 v[168:171], v143
	ds_read_b128 v[172:175], v143 offset:1024
	ds_read_b128 v[176:179], v143 offset:2048
	ds_read_b128 v[180:183], v143 offset:3072
	ds_read_b128 v[184:187], v143 offset:4096
	ds_read_b128 v[188:191], v143 offset:5120
	ds_read_b128 v[192:195], v143 offset:6144
	ds_read_b128 v[196:199], v143 offset:7168
	global_load_lds_dwordx4 v[200:201], off
	v_lshl_add_u64 v[200:201], s[76:77], 0, v[130:131]
	s_add_i32 m0, s2, 0xe000
	s_nop 0
	global_load_lds_dwordx4 v[200:201], off
	s_waitcnt vmcnt(8)
	s_waitcnt lgkmcnt(0)
	s_barrier
	s_waitcnt lgkmcnt(0)
	v_mfma_f32_16x16x32_bf16 v[126:129], v[132:135], v[168:171], v[126:129]
	v_mfma_f32_16x16x32_bf16 v[122:125], v[144:147], v[168:171], v[122:125]
	v_mfma_f32_16x16x32_bf16 v[110:113], v[132:135], v[176:179], v[110:113]
	v_mfma_f32_16x16x32_bf16 v[106:109], v[144:147], v[176:179], v[106:109]
	v_mfma_f32_16x16x32_bf16 v[94:97], v[132:135], v[184:187], v[94:97]
	v_mfma_f32_16x16x32_bf16 v[90:93], v[144:147], v[184:187], v[90:93]
	v_mfma_f32_16x16x32_bf16 v[78:81], v[132:135], v[192:195], v[78:81]
	v_mfma_f32_16x16x32_bf16 v[74:77], v[144:147], v[192:195], v[74:77]
	v_mfma_f32_16x16x32_bf16 v[126:129], v[136:139], v[172:175], v[126:129]
	v_mfma_f32_16x16x32_bf16 v[122:125], v[148:151], v[172:175], v[122:125]
	v_mfma_f32_16x16x32_bf16 v[110:113], v[136:139], v[180:183], v[110:113]
	v_mfma_f32_16x16x32_bf16 v[106:109], v[148:151], v[180:183], v[106:109]
	v_mfma_f32_16x16x32_bf16 v[94:97], v[136:139], v[188:191], v[94:97]
	v_mfma_f32_16x16x32_bf16 v[90:93], v[148:151], v[188:191], v[90:93]
	v_mfma_f32_16x16x32_bf16 v[78:81], v[136:139], v[196:199], v[78:81]
	v_mfma_f32_16x16x32_bf16 v[74:77], v[148:151], v[196:199], v[74:77]
	v_mfma_f32_16x16x32_bf16 v[118:121], v[152:155], v[168:171], v[118:121]
	v_mfma_f32_16x16x32_bf16 v[114:117], v[160:163], v[168:171], v[114:117]
	v_mfma_f32_16x16x32_bf16 v[102:105], v[152:155], v[176:179], v[102:105]
	v_mfma_f32_16x16x32_bf16 v[98:101], v[160:163], v[176:179], v[98:101]
	v_mfma_f32_16x16x32_bf16 v[86:89], v[152:155], v[184:187], v[86:89]
	v_mfma_f32_16x16x32_bf16 v[82:85], v[160:163], v[184:187], v[82:85]
	v_mfma_f32_16x16x32_bf16 v[70:73], v[152:155], v[192:195], v[70:73]
	v_mfma_f32_16x16x32_bf16 v[66:69], v[160:163], v[192:195], v[66:69]
	v_mfma_f32_16x16x32_bf16 v[118:121], v[156:159], v[172:175], v[118:121]
	v_mfma_f32_16x16x32_bf16 v[114:117], v[164:167], v[172:175], v[114:117]
	v_mfma_f32_16x16x32_bf16 v[102:105], v[156:159], v[180:183], v[102:105]
	v_mfma_f32_16x16x32_bf16 v[98:101], v[164:167], v[180:183], v[98:101]
	v_mfma_f32_16x16x32_bf16 v[86:89], v[156:159], v[188:191], v[86:89]
	v_mfma_f32_16x16x32_bf16 v[82:85], v[164:167], v[188:191], v[82:85]
	v_mfma_f32_16x16x32_bf16 v[70:73], v[156:159], v[196:199], v[70:73]
	v_mfma_f32_16x16x32_bf16 v[66:69], v[164:167], v[196:199], v[66:69]
	s_barrier
	s_add_i32 s75, s78, s31
	v_lshl_add_u64 v[200:201], s[58:59], 0, v[0:1]
	s_mov_b32 m0, s75
	ds_read_b128 v[168:171], v143 offset:16384
	ds_read_b128 v[172:175], v143 offset:17408
	ds_read_b128 v[176:179], v143 offset:18432
	ds_read_b128 v[180:183], v143 offset:19456
	ds_read_b128 v[184:187], v143 offset:20480
	ds_read_b128 v[188:191], v143 offset:21504
	ds_read_b128 v[192:195], v143 offset:22528
	ds_read_b128 v[196:199], v143 offset:23552
	global_load_lds_dwordx4 v[200:201], off
	s_add_i32 m0, s75, 0x2000
	s_add_u32 s76, s58, 0x4000
	v_lshl_add_u64 v[200:201], s[58:59], 0, v[130:131]
	s_addc_u32 s77, s59, 0
	s_add_i32 s75, s79, s31
	global_load_lds_dwordx4 v[200:201], off
	v_lshl_add_u64 v[200:201], s[76:77], 0, v[0:1]
	s_mov_b32 m0, s75
	s_nop 0
	global_load_lds_dwordx4 v[200:201], off
	v_lshl_add_u64 v[200:201], s[76:77], 0, v[130:131]
	s_add_i32 m0, s75, 0x2000
	s_nop 0
	global_load_lds_dwordx4 v[200:201], off
	v_lshl_add_u64 v[200:201], s[24:25], 0, v[0:1]
	s_mov_b32 m0, s2
	s_nop 0
	global_load_lds_dwordx4 v[200:201], off
	v_lshl_add_u64 v[200:201], s[24:25], 0, v[130:131]
	s_mov_b32 m0, s3
	s_nop 0
	global_load_lds_dwordx4 v[200:201], off
	s_waitcnt vmcnt(8)
	s_waitcnt lgkmcnt(0)
	s_barrier
; #define PG8_STAGE(bufoff, gbase, voff) do { _Pragma("unroll") for (int _i = 0; _i < 2; ++_i) \
;         __builtin_amdgcn_global_load_lds((const unsigned*)((const char*)(gbase) + (voff)[_i]), (LAS unsigned*)(lds + (bufoff) + ldsw + _i * 8192), 16, 0, 0); } while (0)
; #define PG8_LDA(dst, b, h) do { _Pragma("unroll") for (int m = 0; m < 4; ++m) _Pragma("unroll") for (int k = 0; k < 2; ++k) dst[m][k] = *(const LAS bf16x8*)(lds + PG8_SA(b, h) + aoff + m * 2048 + k * 1024); } while (0)
; #define PG8_LDB(dst, b, h) do { _Pragma("unroll") for (int n = 0; n < 2; ++n) _Pragma("unroll") for (int k = 0; k < 2; ++k) dst[n][k] = *(const LAS bf16x8*)(lds + PG8_SB(b, h) + boff + n * 2048 + k * 1024); } while (0)
; #define PG8_BAR __builtin_amdgcn_s_barrier()
; template <bool HM = false, bool PERM = false, bool CP = false, class Prob, class Epi>
; __device__ __forceinline__ void gemm_phase(LAS unsigned char* lds, const Prob& S, const Epi& E) {
;     ...
;             const char* a1 = cA + (size_t)(t + 1) * kstepA;
;             const char* a2 = last ? nA : cA + (size_t)(t + 2) * kstepA; const char* b2 = last ? nB : cB + (size_t)(t + 2) * kstepB;
;             const char* a3 = a2 + kstepA; const char* b3 = b2 + kstepB; const long h2 = last ? nhB : chB;
;     ...
;             PG8_LDB(B0, 0, 0); PG8_LDB(B1, 0, 1); PG8_SCHED; PG8_LDA(At, 0, 0); PG8_STAGE(PG8_SA(1, 1), a1 + hstepA, voffA);
;             PG8_WAIT_V(8); PG8_WAIT_L(0); PG8_BAR; if (!CP || fullu) PG8_MMA(0, 0, At, B0); PG8_MMA(0, 1, At, B1); PG8_BAR; PG8_SCHED;
;             if (!HM) PG8_LDA(At, 0, 1); PG8_STAGE(PG8_SB(0, 0), b2, voffB); PG8_STAGE(PG8_SB(0, 1), b2 + h2, voffB); PG8_STAGE(PG8_SA(0, 0), a2, voffA);
;             PG8_WAIT_V(8); PG8_WAIT_L(0); PG8_BAR; if (!HM) { if (!CP || fullu) PG8_MMA(1, 0, At, B0); PG8_MMA(1, 1, At, B1); } PG8_BAR; PG8_SCHED;
;             PG8_LDB(B0, 1, 0); PG8_LDB(B1, 1, 1); PG8_SCHED; PG8_LDA(At, 1, 0); PG8_STAGE(PG8_SA(0, 1), a2 + hstepA, voffA);
;             PG8_WAIT_V(8); PG8_WAIT_L(0); PG8_BAR; if (!CP || fullu) PG8_MMA(0, 0, At, B0); PG8_MMA(0, 1, At, B1); PG8_BAR; PG8_SCHED;
;             if (!HM) PG8_LDA(At, 1, 1); PG8_STAGE(PG8_SB(1, 0), b3, voffB); PG8_STAGE(PG8_SB(1, 1), b3 + h2, voffB); PG8_STAGE(PG8_SA(1, 0), a3, voffA);
;             PG8_WAIT_V(8); PG8_WAIT_L(0); PG8_BAR; if (!HM) { if (!CP || fullu) PG8_MMA(1, 0, At, B0); PG8_MMA(1, 1, At, B1); } PG8_BAR; PG8_SCHED;
	s_waitcnt lgkmcnt(0)
	v_mfma_f32_16x16x32_bf16 v[62:65], v[132:135], v[168:171], v[62:65]
	v_mfma_f32_16x16x32_bf16 v[58:61], v[144:147], v[168:171], v[58:61]
	v_mfma_f32_16x16x32_bf16 v[46:49], v[132:135], v[176:179], v[46:49]
	v_mfma_f32_16x16x32_bf16 v[42:45], v[144:147], v[176:179], v[42:45]
	v_mfma_f32_16x16x32_bf16 v[30:33], v[132:135], v[184:187], v[30:33]
	v_mfma_f32_16x16x32_bf16 v[26:29], v[144:147], v[184:187], v[26:29]
	v_mfma_f32_16x16x32_bf16 v[14:17], v[132:135], v[192:195], v[14:17]
	v_mfma_f32_16x16x32_bf16 v[10:13], v[144:147], v[192:195], v[10:13]
	v_mfma_f32_16x16x32_bf16 v[62:65], v[136:139], v[172:175], v[62:65]
	v_mfma_f32_16x16x32_bf16 v[58:61], v[148:151], v[172:175], v[58:61]
	v_mfma_f32_16x16x32_bf16 v[46:49], v[136:139], v[180:183], v[46:49]
	v_mfma_f32_16x16x32_bf16 v[42:45], v[148:151], v[180:183], v[42:45]
	v_mfma_f32_16x16x32_bf16 v[30:33], v[136:139], v[188:191], v[30:33]
	v_mfma_f32_16x16x32_bf16 v[26:29], v[148:151], v[188:191], v[26:29]
	v_mfma_f32_16x16x32_bf16 v[14:17], v[136:139], v[196:199], v[14:17]
	v_mfma_f32_16x16x32_bf16 v[10:13], v[148:151], v[196:199], v[10:13]
	v_mfma_f32_16x16x32_bf16 v[54:57], v[152:155], v[168:171], v[54:57]
	v_mfma_f32_16x16x32_bf16 v[50:53], v[160:163], v[168:171], v[50:53]
	v_mfma_f32_16x16x32_bf16 v[38:41], v[152:155], v[176:179], v[38:41]
	v_mfma_f32_16x16x32_bf16 v[34:37], v[160:163], v[176:179], v[34:37]
	v_mfma_f32_16x16x32_bf16 v[22:25], v[152:155], v[184:187], v[22:25]
	v_mfma_f32_16x16x32_bf16 v[18:21], v[160:163], v[184:187], v[18:21]
	v_mfma_f32_16x16x32_bf16 v[6:9], v[152:155], v[192:195], v[6:9]
	v_mfma_f32_16x16x32_bf16 v[2:5], v[160:163], v[192:195], v[2:5]
	v_mfma_f32_16x16x32_bf16 v[54:57], v[156:159], v[172:175], v[54:57]
	v_mfma_f32_16x16x32_bf16 v[50:53], v[164:167], v[172:175], v[50:53]
	v_mfma_f32_16x16x32_bf16 v[38:41], v[156:159], v[180:183], v[38:41]
	v_mfma_f32_16x16x32_bf16 v[34:37], v[164:167], v[180:183], v[34:37]
	v_mfma_f32_16x16x32_bf16 v[22:25], v[156:159], v[188:191], v[22:25]
	v_mfma_f32_16x16x32_bf16 v[18:21], v[164:167], v[188:191], v[18:21]
	v_mfma_f32_16x16x32_bf16 v[6:9], v[156:159], v[196:199], v[6:9]
	v_mfma_f32_16x16x32_bf16 v[2:5], v[164:167], v[196:199], v[2:5]
	s_barrier
	s_add_i32 s75, 0, 0x18000
	s_add_i32 s76, 0, 0x1c000
	v_add_u32_e32 v148, s75, v142
	v_add_u32_e32 v164, s76, v142
	ds_read_b128 v[132:135], v148
	ds_read_b128 v[136:139], v148 offset:1024
	ds_read_b128 v[144:147], v148 offset:2048
	ds_read_b128 v[148:151], v148 offset:3072
	ds_read_b128 v[152:155], v164
	ds_read_b128 v[156:159], v164 offset:1024
	ds_read_b128 v[160:163], v164 offset:2048
	ds_read_b128 v[164:167], v164 offset:3072
	s_add_u32 s24, s24, 0x4000
	s_addc_u32 s25, s25, 0
	s_mov_b32 m0, s18
	v_lshl_add_u64 v[200:201], s[24:25], 0, v[0:1]
	ds_read_b128 v[168:171], v143 offset:32768
	ds_read_b128 v[172:175], v143 offset:33792
	ds_read_b128 v[176:179], v143 offset:34816
	ds_read_b128 v[180:183], v143 offset:35840
	ds_read_b128 v[184:187], v143 offset:36864
	ds_read_b128 v[188:191], v143 offset:37888
	ds_read_b128 v[192:195], v143 offset:38912
	ds_read_b128 v[196:199], v143 offset:39936
	global_load_lds_dwordx4 v[200:201], off
	v_lshl_add_u64 v[200:201], s[24:25], 0, v[130:131]
	s_mov_b32 m0, s19
	s_nop 0
	global_load_lds_dwordx4 v[200:201], off
	s_waitcnt vmcnt(8)
	s_waitcnt lgkmcnt(0)
	s_barrier
	s_waitcnt lgkmcnt(0)
	v_mfma_f32_16x16x32_bf16 v[126:129], v[132:135], v[168:171], v[126:129]
	v_mfma_f32_16x16x32_bf16 v[122:125], v[144:147], v[168:171], v[122:125]
	v_mfma_f32_16x16x32_bf16 v[110:113], v[132:135], v[176:179], v[110:113]
	v_mfma_f32_16x16x32_bf16 v[106:109], v[144:147], v[176:179], v[106:109]
	v_mfma_f32_16x16x32_bf16 v[94:97], v[132:135], v[184:187], v[94:97]
	v_mfma_f32_16x16x32_bf16 v[90:93], v[144:147], v[184:187], v[90:93]
	v_mfma_f32_16x16x32_bf16 v[78:81], v[132:135], v[192:195], v[78:81]
	v_mfma_f32_16x16x32_bf16 v[74:77], v[144:147], v[192:195], v[74:77]
	v_mfma_f32_16x16x32_bf16 v[126:129], v[136:139], v[172:175], v[126:129]
	v_mfma_f32_16x16x32_bf16 v[122:125], v[148:151], v[172:175], v[122:125]
	v_mfma_f32_16x16x32_bf16 v[110:113], v[136:139], v[180:183], v[110:113]
	v_mfma_f32_16x16x32_bf16 v[106:109], v[148:151], v[180:183], v[106:109]
	v_mfma_f32_16x16x32_bf16 v[94:97], v[136:139], v[188:191], v[94:97]
	v_mfma_f32_16x16x32_bf16 v[90:93], v[148:151], v[188:191], v[90:93]
	v_mfma_f32_16x16x32_bf16 v[78:81], v[136:139], v[196:199], v[78:81]
	v_mfma_f32_16x16x32_bf16 v[74:77], v[148:151], v[196:199], v[74:77]
	v_mfma_f32_16x16x32_bf16 v[118:121], v[152:155], v[168:171], v[118:121]
	v_mfma_f32_16x16x32_bf16 v[114:117], v[160:163], v[168:171], v[114:117]
	v_mfma_f32_16x16x32_bf16 v[102:105], v[152:155], v[176:179], v[102:105]
	v_mfma_f32_16x16x32_bf16 v[98:101], v[160:163], v[176:179], v[98:101]
	v_mfma_f32_16x16x32_bf16 v[86:89], v[152:155], v[184:187], v[86:89]
	v_mfma_f32_16x16x32_bf16 v[82:85], v[160:163], v[184:187], v[82:85]
	v_mfma_f32_16x16x32_bf16 v[70:73], v[152:155], v[192:195], v[70:73]
	v_mfma_f32_16x16x32_bf16 v[66:69], v[160:163], v[192:195], v[66:69]
	v_mfma_f32_16x16x32_bf16 v[118:121], v[156:159], v[172:175], v[118:121]
	v_mfma_f32_16x16x32_bf16 v[114:117], v[164:167], v[172:175], v[114:117]
	v_mfma_f32_16x16x32_bf16 v[102:105], v[156:159], v[180:183], v[102:105]
	v_mfma_f32_16x16x32_bf16 v[98:101], v[164:167], v[180:183], v[98:101]
	v_mfma_f32_16x16x32_bf16 v[86:89], v[156:159], v[188:191], v[86:89]
	v_mfma_f32_16x16x32_bf16 v[82:85], v[164:167], v[188:191], v[82:85]
	v_mfma_f32_16x16x32_bf16 v[70:73], v[156:159], v[196:199], v[70:73]
	v_mfma_f32_16x16x32_bf16 v[66:69], v[164:167], v[196:199], v[66:69]
	s_barrier
; #define PG8_STAGE(bufoff, gbase, voff) do { _Pragma("unroll") for (int _i = 0; _i < 2; ++_i) \
;         __builtin_amdgcn_global_load_lds((const unsigned*)((const char*)(gbase) + (voff)[_i]), (LAS unsigned*)(lds + (bufoff) + ldsw + _i * 8192), 16, 0, 0); } while (0)
; #define PG8_LDA(dst, b, h) do { _Pragma("unroll") for (int m = 0; m < 4; ++m) _Pragma("unroll") for (int k = 0; k < 2; ++k) dst[m][k] = *(const LAS bf16x8*)(lds + PG8_SA(b, h) + aoff + m * 2048 + k * 1024); } while (0)
; #define PG8_LDB(dst, b, h) do { _Pragma("unroll") for (int n = 0; n < 2; ++n) _Pragma("unroll") for (int k = 0; k < 2; ++k) dst[n][k] = *(const LAS bf16x8*)(lds + PG8_SB(b, h) + boff + n * 2048 + k * 1024); } while (0)
; #define PG8_MMA(ai, bj, At, Bt) do { __builtin_amdgcn_s_setprio(1); _Pragma("unroll") for (int m = 0; m < 4; ++m) _Pragma("unroll") for (int n = 0; n < 2; ++n) _Pragma("unroll") for (int k = 0; k < 2; ++k) \
;         acc[ai][bj][m][n] = __builtin_amdgcn_mfma_f32_16x16x32_bf16(Bt[n][k], At[m][k], acc[ai][bj][m][n], 0, 0, 0); __builtin_amdgcn_s_setprio(0); } while (0)
; #define PG8_WAIT_V(n) asm volatile("s_waitcnt vmcnt(" #n ")" ::: "memory")
; #define PG8_WAIT_L(n) asm volatile("s_waitcnt lgkmcnt(" #n ")" ::: "memory")
; #define PG8_BAR __builtin_amdgcn_s_barrier()
; template <bool HM = false, bool PERM = false, bool CP = false, class Prob, class Epi>
; __device__ __forceinline__ void gemm_phase(LAS unsigned char* lds, const Prob& S, const Epi& E) {
;     ...
;             if (!HM) PG8_LDA(At, 0, 1); PG8_STAGE(PG8_SB(0, 0), b2, voffB); PG8_STAGE(PG8_SB(0, 1), b2 + h2, voffB); PG8_STAGE(PG8_SA(0, 0), a2, voffA);
;             PG8_WAIT_V(8); PG8_WAIT_L(0); PG8_BAR; if (!HM) { if (!CP || fullu) PG8_MMA(1, 0, At, B0); PG8_MMA(1, 1, At, B1); } PG8_BAR; PG8_SCHED;
;             PG8_LDB(B0, 1, 0); PG8_LDB(B1, 1, 1); PG8_SCHED; PG8_LDA(At, 1, 0); PG8_STAGE(PG8_SA(0, 1), a2 + hstepA, voffA);
;             PG8_WAIT_V(8); PG8_WAIT_L(0); PG8_BAR; if (!CP || fullu) PG8_MMA(0, 0, At, B0); PG8_MMA(0, 1, At, B1); PG8_BAR; PG8_SCHED;
;             if (!HM) PG8_LDA(At, 1, 1); PG8_STAGE(PG8_SB(1, 0), b3, voffB); PG8_STAGE(PG8_SB(1, 1), b3 + h2, voffB); PG8_STAGE(PG8_SA(1, 0), a3, voffA);
;             PG8_WAIT_V(8); PG8_WAIT_L(0); PG8_BAR; if (!HM) { if (!CP || fullu) PG8_MMA(1, 0, At, B0); PG8_MMA(1, 1, At, B1); } PG8_BAR; PG8_SCHED;
	s_add_u32 s24, s58, 0x20000
	s_addc_u32 s25, s59, 0
	s_add_i32 s75, s75, s31
	v_lshl_add_u64 v[200:201], s[24:25], 0, v[0:1]
	s_mov_b32 m0, s75
	ds_read_b128 v[168:171], v143 offset:49152
	ds_read_b128 v[172:175], v143 offset:50176
	ds_read_b128 v[176:179], v143 offset:51200
	ds_read_b128 v[180:183], v143 offset:52224
	ds_read_b128 v[184:187], v143 offset:53248
	ds_read_b128 v[188:191], v143 offset:54272
	ds_read_b128 v[192:195], v143 offset:55296
	ds_read_b128 v[196:199], v143 offset:56320
	global_load_lds_dwordx4 v[200:201], off
	s_add_i32 m0, s75, 0x2000
	v_lshl_add_u64 v[200:201], s[24:25], 0, v[130:131]
	s_add_u32 s24, s58, 0x24000
	s_addc_u32 s25, s59, 0
	s_add_i32 s58, s76, s31
	global_load_lds_dwordx4 v[200:201], off
	v_lshl_add_u64 v[200:201], s[24:25], 0, v[0:1]
	s_mov_b32 m0, s58
	s_nop 0
	global_load_lds_dwordx4 v[200:201], off
	v_lshl_add_u64 v[200:201], s[24:25], 0, v[130:131]
	s_add_i32 m0, s58, 0x2000
	s_nop 0
	global_load_lds_dwordx4 v[200:201], off
	v_lshl_add_u64 v[200:201], s[34:35], 0, v[0:1]
	s_mov_b32 m0, s64
	s_nop 0
	global_load_lds_dwordx4 v[200:201], off
	v_lshl_add_u64 v[200:201], s[34:35], 0, v[130:131]
	s_mov_b32 m0, s69
	s_nop 0
	global_load_lds_dwordx4 v[200:201], off
	s_waitcnt vmcnt(8)
	s_waitcnt lgkmcnt(0)
	s_barrier
	s_waitcnt lgkmcnt(0)
	v_mfma_f32_16x16x32_bf16 v[62:65], v[132:135], v[168:171], v[62:65]
	v_mfma_f32_16x16x32_bf16 v[58:61], v[144:147], v[168:171], v[58:61]
	v_mfma_f32_16x16x32_bf16 v[46:49], v[132:135], v[176:179], v[46:49]
	v_mfma_f32_16x16x32_bf16 v[42:45], v[144:147], v[176:179], v[42:45]
	v_mfma_f32_16x16x32_bf16 v[30:33], v[132:135], v[184:187], v[30:33]
	v_mfma_f32_16x16x32_bf16 v[26:29], v[144:147], v[184:187], v[26:29]
	v_mfma_f32_16x16x32_bf16 v[14:17], v[132:135], v[192:195], v[14:17]
	v_mfma_f32_16x16x32_bf16 v[10:13], v[144:147], v[192:195], v[10:13]
	v_mfma_f32_16x16x32_bf16 v[62:65], v[136:139], v[172:175], v[62:65]
	v_mfma_f32_16x16x32_bf16 v[58:61], v[148:151], v[172:175], v[58:61]
	v_mfma_f32_16x16x32_bf16 v[46:49], v[136:139], v[180:183], v[46:49]
	v_mfma_f32_16x16x32_bf16 v[42:45], v[148:151], v[180:183], v[42:45]
	v_mfma_f32_16x16x32_bf16 v[30:33], v[136:139], v[188:191], v[30:33]
	v_mfma_f32_16x16x32_bf16 v[26:29], v[148:151], v[188:191], v[26:29]
	v_mfma_f32_16x16x32_bf16 v[14:17], v[136:139], v[196:199], v[14:17]
	v_mfma_f32_16x16x32_bf16 v[10:13], v[148:151], v[196:199], v[10:13]
	v_mfma_f32_16x16x32_bf16 v[54:57], v[152:155], v[168:171], v[54:57]
	v_mfma_f32_16x16x32_bf16 v[50:53], v[160:163], v[168:171], v[50:53]
	v_mfma_f32_16x16x32_bf16 v[38:41], v[152:155], v[176:179], v[38:41]
	v_mfma_f32_16x16x32_bf16 v[34:37], v[160:163], v[176:179], v[34:37]
	v_mfma_f32_16x16x32_bf16 v[22:25], v[152:155], v[184:187], v[22:25]
	v_mfma_f32_16x16x32_bf16 v[18:21], v[160:163], v[184:187], v[18:21]
	v_mfma_f32_16x16x32_bf16 v[6:9], v[152:155], v[192:195], v[6:9]
	v_mfma_f32_16x16x32_bf16 v[2:5], v[160:163], v[192:195], v[2:5]
	v_mfma_f32_16x16x32_bf16 v[54:57], v[156:159], v[172:175], v[54:57]
	v_mfma_f32_16x16x32_bf16 v[50:53], v[164:167], v[172:175], v[50:53]
	v_mfma_f32_16x16x32_bf16 v[38:41], v[156:159], v[180:183], v[38:41]
	v_mfma_f32_16x16x32_bf16 v[34:37], v[164:167], v[180:183], v[34:37]
	v_mfma_f32_16x16x32_bf16 v[22:25], v[156:159], v[188:191], v[22:25]
	v_mfma_f32_16x16x32_bf16 v[18:21], v[164:167], v[188:191], v[18:21]
	v_mfma_f32_16x16x32_bf16 v[6:9], v[156:159], v[196:199], v[6:9]
	v_mfma_f32_16x16x32_bf16 v[2:5], v[164:167], v[196:199], v[2:5]
	s_barrier
	s_cmp_gt_u32 s74, 61
	s_mov_b32 s74, s6
	s_cbranch_scc1 .LBB0_1396
